# K-loops: s_setprio 0 moved behind the closing barrier (barrier arrival directly after the last MFMA)
# speedup vs baseline: 1.0057x; 1.0007x over previous
.LBB0_161:
	s_add_u32 s86, s69, s6
	s_addc_u32 s87, s70, s7
	s_add_u32 s88, s71, s8
	s_addc_u32 s89, s72, s9
	s_ashr_i32 s23, s22, 31
	s_lshl_b64 s[6:7], s[22:23], 19
	s_add_u32 s24, s34, s6
	s_addc_u32 s25, s35, s7
	s_and_b64 s[8:9], s[0:1], exec
	s_cselect_b32 s23, s25, s43
	s_cselect_b32 s90, s24, s42
	s_ashr_i32 s21, s20, 31
	s_lshl_b64 s[8:9], s[20:21], 19
	s_add_u32 s26, s17, s8
	s_addc_u32 s27, s19, s9
	s_and_b64 s[48:49], s[0:1], exec
	s_cselect_b32 s21, s27, s39
	s_cselect_b32 s91, s26, s38
	s_add_u32 s48, s90, 0x80
	s_addc_u32 s49, s23, 0
	s_add_u32 s54, s91, 0x80
	s_addc_u32 s55, s21, 0
	v_lshl_add_u64 v[128:129], s[42:43], 0, v[150:151]
	v_lshl_add_u64 v[130:131], s[42:43], 0, v[152:153]
	s_mov_b32 s92, 0
	s_mov_b64 s[56:57], 0
	s_cmpk_eq_i32 s56, 0x700
	s_cselect_b64 s[62:63], -1, 0
	s_add_u32 s64, s42, s56
	s_addc_u32 s65, s43, s57
	s_add_u32 s94, s38, s56
	s_addc_u32 s93, s39, s57
	s_add_u32 s58, s64, 0x180
	s_addc_u32 s59, s65, 0
	s_add_u32 s60, s94, 0x180
	s_addc_u32 s61, s93, 0
	s_cmpk_eq_i32 s56, 0x700
	s_cselect_b32 s58, s48, s58
	s_cselect_b32 s59, s49, s59
	s_cselect_b32 s60, s54, s60
	s_cselect_b32 s61, s55, s61
	v_add_u32_e32 v144, s82, v171
	ds_read_b128 v[132:135], v144
	ds_read_b128 v[158:161], v144 offset:1024
	ds_read_b128 v[162:165], v144 offset:2048
	ds_read_b128 v[166:169], v144 offset:3072
	v_add_u32_e32 v144, s83, v171
	ds_read_b128 v[184:187], v144
	ds_read_b128 v[188:191], v144 offset:1024
	ds_read_b128 v[192:195], v144 offset:2048
	ds_read_b128 v[196:199], v144 offset:3072
	s_add_u32 s10, s64, 0x100
	s_addc_u32 s95, s65, 0
	s_and_b64 s[64:65], exec, s[62:63]
	s_cselect_b32 s65, s23, s95
	s_cselect_b32 s64, s90, s10
	s_add_u32 s10, s94, 0x100
	s_addc_u32 s93, s93, 0
	s_and_b64 s[62:63], exec, s[62:63]
	s_cselect_b32 s63, s21, s93
	s_cselect_b32 s62, s91, s10
	v_lshl_add_u64 v[232:233], v[128:129], 0, s[56:57]
	s_add_i32 m0, s29, 0xc000
	ds_read_b128 v[200:203], v181
	ds_read_b128 v[204:207], v181 offset:1024
	ds_read_b128 v[208:211], v181 offset:2048
	ds_read_b128 v[212:215], v181 offset:3072
	ds_read_b128 v[216:219], v181 offset:4096
	ds_read_b128 v[220:223], v181 offset:5120
	ds_read_b128 v[224:227], v181 offset:6144
	global_load_lds_dwordx4 v[232:233], off
	v_lshl_add_u64 v[232:233], v[130:131], 0, s[56:57]
	s_add_i32 m0, s29, 0xe000
	ds_read_b128 v[228:231], v181 offset:7168
	global_load_lds_dwordx4 v[232:233], off
	s_waitcnt vmcnt(8)
	s_waitcnt lgkmcnt(0)
	s_setprio 1
	s_barrier
	v_mfma_f32_16x16x32_bf16 v[124:127], v[132:135], v[200:203], 0
	v_mfma_f32_16x16x32_bf16 v[120:123], v[162:165], v[200:203], 0
	v_mfma_f32_16x16x32_bf16 v[108:111], v[132:135], v[208:211], 0
	v_mfma_f32_16x16x32_bf16 v[104:107], v[162:165], v[208:211], 0
	v_mfma_f32_16x16x32_bf16 v[92:95], v[132:135], v[216:219], 0
	v_mfma_f32_16x16x32_bf16 v[88:91], v[162:165], v[216:219], 0
	v_mfma_f32_16x16x32_bf16 v[76:79], v[132:135], v[224:227], 0
	v_mfma_f32_16x16x32_bf16 v[72:75], v[162:165], v[224:227], 0
	v_mfma_f32_16x16x32_bf16 v[124:127], v[158:161], v[204:207], v[124:127]
	v_mfma_f32_16x16x32_bf16 v[120:123], v[166:169], v[204:207], v[120:123]
	v_mfma_f32_16x16x32_bf16 v[108:111], v[158:161], v[212:215], v[108:111]
	v_mfma_f32_16x16x32_bf16 v[104:107], v[166:169], v[212:215], v[104:107]
	v_mfma_f32_16x16x32_bf16 v[92:95], v[158:161], v[220:223], v[92:95]
	v_mfma_f32_16x16x32_bf16 v[88:91], v[166:169], v[220:223], v[88:91]
	v_mfma_f32_16x16x32_bf16 v[76:79], v[158:161], v[228:231], v[76:79]
	v_mfma_f32_16x16x32_bf16 v[72:75], v[166:169], v[228:231], v[72:75]
	s_setprio 0
	s_setprio 1
	v_mfma_f32_16x16x32_bf16 v[116:119], v[184:187], v[200:203], 0
	v_mfma_f32_16x16x32_bf16 v[112:115], v[192:195], v[200:203], 0
	v_mfma_f32_16x16x32_bf16 v[100:103], v[184:187], v[208:211], 0
	v_mfma_f32_16x16x32_bf16 v[96:99], v[192:195], v[208:211], 0
	v_mfma_f32_16x16x32_bf16 v[84:87], v[184:187], v[216:219], 0
	v_mfma_f32_16x16x32_bf16 v[80:83], v[192:195], v[216:219], 0
	v_mfma_f32_16x16x32_bf16 v[68:71], v[184:187], v[224:227], 0
	v_mfma_f32_16x16x32_bf16 v[64:67], v[192:195], v[224:227], 0
	v_mfma_f32_16x16x32_bf16 v[116:119], v[188:191], v[204:207], v[116:119]
	v_mfma_f32_16x16x32_bf16 v[112:115], v[196:199], v[204:207], v[112:115]
	v_mfma_f32_16x16x32_bf16 v[100:103], v[188:191], v[212:215], v[100:103]
	v_mfma_f32_16x16x32_bf16 v[96:99], v[196:199], v[212:215], v[96:99]
	v_mfma_f32_16x16x32_bf16 v[84:87], v[188:191], v[220:223], v[84:87]
	v_mfma_f32_16x16x32_bf16 v[80:83], v[196:199], v[220:223], v[80:83]
	v_mfma_f32_16x16x32_bf16 v[68:71], v[188:191], v[228:231], v[68:71]
	v_mfma_f32_16x16x32_bf16 v[64:67], v[196:199], v[228:231], v[64:67]
	s_barrier
	s_setprio 0
	s_add_i32 s10, s82, s66
	s_mov_b32 m0, s10
	ds_read_b128 v[200:203], v181 offset:16384
	ds_read_b128 v[204:207], v181 offset:17408
	ds_read_b128 v[208:211], v181 offset:18432
	global_load_lds_dwordx4 v138, s[62:63]
	s_add_i32 m0, s10, 0x2000
	ds_read_b128 v[212:215], v181 offset:19456
	global_load_lds_dwordx4 v142, s[62:63]
	s_add_u32 s62, s62, 0x40000
	s_addc_u32 s63, s63, 0
	s_add_i32 s10, s83, s66
	s_mov_b32 m0, s10
	ds_read_b128 v[216:219], v181 offset:20480
	global_load_lds_dwordx4 v138, s[62:63]
	s_add_i32 m0, s10, 0x2000
	ds_read_b128 v[220:223], v181 offset:21504
	global_load_lds_dwordx4 v142, s[62:63]
	s_mov_b32 m0, s29
	ds_read_b128 v[224:227], v181 offset:22528
	global_load_lds_dwordx4 v136, s[64:65]
	s_mov_b32 m0, s31
	ds_read_b128 v[228:231], v181 offset:23552
	global_load_lds_dwordx4 v140, s[64:65]
	s_waitcnt vmcnt(8)
	s_waitcnt lgkmcnt(0)
	s_setprio 1
	s_barrier
	v_mfma_f32_16x16x32_bf16 v[60:63], v[132:135], v[200:203], 0
	v_mfma_f32_16x16x32_bf16 v[56:59], v[162:165], v[200:203], 0
	v_mfma_f32_16x16x32_bf16 v[44:47], v[132:135], v[208:211], 0
	v_mfma_f32_16x16x32_bf16 v[40:43], v[162:165], v[208:211], 0
	v_mfma_f32_16x16x32_bf16 v[28:31], v[132:135], v[216:219], 0
	v_mfma_f32_16x16x32_bf16 v[24:27], v[162:165], v[216:219], 0
	v_mfma_f32_16x16x32_bf16 v[12:15], v[132:135], v[224:227], 0
	v_mfma_f32_16x16x32_bf16 v[8:11], v[162:165], v[224:227], 0
	v_mfma_f32_16x16x32_bf16 v[60:63], v[158:161], v[204:207], v[60:63]
	v_mfma_f32_16x16x32_bf16 v[56:59], v[166:169], v[204:207], v[56:59]
	v_mfma_f32_16x16x32_bf16 v[44:47], v[158:161], v[212:215], v[44:47]
	v_mfma_f32_16x16x32_bf16 v[40:43], v[166:169], v[212:215], v[40:43]
	v_mfma_f32_16x16x32_bf16 v[28:31], v[158:161], v[220:223], v[28:31]
	v_mfma_f32_16x16x32_bf16 v[24:27], v[166:169], v[220:223], v[24:27]
	v_mfma_f32_16x16x32_bf16 v[12:15], v[158:161], v[228:231], v[12:15]
	v_mfma_f32_16x16x32_bf16 v[8:11], v[166:169], v[228:231], v[8:11]
	s_setprio 0
	s_setprio 1
	v_mfma_f32_16x16x32_bf16 v[52:55], v[184:187], v[200:203], 0
	v_mfma_f32_16x16x32_bf16 v[48:51], v[192:195], v[200:203], 0
	v_mfma_f32_16x16x32_bf16 v[36:39], v[184:187], v[208:211], 0
	v_mfma_f32_16x16x32_bf16 v[32:35], v[192:195], v[208:211], 0
	v_mfma_f32_16x16x32_bf16 v[20:23], v[184:187], v[216:219], 0
	v_mfma_f32_16x16x32_bf16 v[16:19], v[192:195], v[216:219], 0
	v_mfma_f32_16x16x32_bf16 v[4:7], v[184:187], v[224:227], 0
	v_mfma_f32_16x16x32_bf16 v[0:3], v[192:195], v[224:227], 0
	v_mfma_f32_16x16x32_bf16 v[52:55], v[188:191], v[204:207], v[52:55]
	v_mfma_f32_16x16x32_bf16 v[48:51], v[196:199], v[204:207], v[48:51]
	v_mfma_f32_16x16x32_bf16 v[36:39], v[188:191], v[212:215], v[36:39]
	v_mfma_f32_16x16x32_bf16 v[32:35], v[196:199], v[212:215], v[32:35]
	v_mfma_f32_16x16x32_bf16 v[20:23], v[188:191], v[220:223], v[20:23]
	v_mfma_f32_16x16x32_bf16 v[16:19], v[196:199], v[220:223], v[16:19]
	v_mfma_f32_16x16x32_bf16 v[4:7], v[188:191], v[228:231], v[4:7]
	v_mfma_f32_16x16x32_bf16 v[0:3], v[196:199], v[228:231], v[0:3]
	s_barrier
	s_setprio 0
	s_add_i32 s10, 0, 0x18000
	v_add_u32_e32 v144, s10, v171
	s_add_i32 s93, 0, 0x1c000
	ds_read_b128 v[132:135], v144
	ds_read_b128 v[158:161], v144 offset:1024
	ds_read_b128 v[162:165], v144 offset:2048
	ds_read_b128 v[166:169], v144 offset:3072
	v_add_u32_e32 v144, s93, v171
	ds_read_b128 v[184:187], v144
	ds_read_b128 v[188:191], v144 offset:1024
	ds_read_b128 v[192:195], v144 offset:2048
	ds_read_b128 v[196:199], v144 offset:3072
	s_add_u32 s62, s64, 0x40000
	s_addc_u32 s63, s65, 0
	s_mov_b32 m0, s67
	ds_read_b128 v[200:203], v181 offset:32768
	ds_read_b128 v[204:207], v181 offset:33792
	ds_read_b128 v[208:211], v181 offset:34816
	ds_read_b128 v[212:215], v181 offset:35840
	ds_read_b128 v[216:219], v181 offset:36864
	ds_read_b128 v[220:223], v181 offset:37888
	ds_read_b128 v[224:227], v181 offset:38912
	global_load_lds_dwordx4 v136, s[62:63]
	s_mov_b32 m0, s68
	ds_read_b128 v[228:231], v181 offset:39936
	global_load_lds_dwordx4 v140, s[62:63]
	s_waitcnt vmcnt(8)
	s_waitcnt lgkmcnt(0)
	s_setprio 1
	s_barrier
	v_mfma_f32_16x16x32_bf16 v[124:127], v[132:135], v[200:203], v[124:127]
	v_mfma_f32_16x16x32_bf16 v[120:123], v[162:165], v[200:203], v[120:123]
	v_mfma_f32_16x16x32_bf16 v[108:111], v[132:135], v[208:211], v[108:111]
	v_mfma_f32_16x16x32_bf16 v[104:107], v[162:165], v[208:211], v[104:107]
	v_mfma_f32_16x16x32_bf16 v[92:95], v[132:135], v[216:219], v[92:95]
	v_mfma_f32_16x16x32_bf16 v[88:91], v[162:165], v[216:219], v[88:91]
	v_mfma_f32_16x16x32_bf16 v[76:79], v[132:135], v[224:227], v[76:79]
	v_mfma_f32_16x16x32_bf16 v[72:75], v[162:165], v[224:227], v[72:75]
	v_mfma_f32_16x16x32_bf16 v[124:127], v[158:161], v[204:207], v[124:127]
	v_mfma_f32_16x16x32_bf16 v[120:123], v[166:169], v[204:207], v[120:123]
	v_mfma_f32_16x16x32_bf16 v[108:111], v[158:161], v[212:215], v[108:111]
	v_mfma_f32_16x16x32_bf16 v[104:107], v[166:169], v[212:215], v[104:107]
	v_mfma_f32_16x16x32_bf16 v[92:95], v[158:161], v[220:223], v[92:95]
	v_mfma_f32_16x16x32_bf16 v[88:91], v[166:169], v[220:223], v[88:91]
	v_mfma_f32_16x16x32_bf16 v[76:79], v[158:161], v[228:231], v[76:79]
	v_mfma_f32_16x16x32_bf16 v[72:75], v[166:169], v[228:231], v[72:75]
	s_setprio 0
	s_setprio 1
	v_mfma_f32_16x16x32_bf16 v[116:119], v[184:187], v[200:203], v[116:119]
	v_mfma_f32_16x16x32_bf16 v[112:115], v[192:195], v[200:203], v[112:115]
	v_mfma_f32_16x16x32_bf16 v[100:103], v[184:187], v[208:211], v[100:103]
	v_mfma_f32_16x16x32_bf16 v[96:99], v[192:195], v[208:211], v[96:99]
	v_mfma_f32_16x16x32_bf16 v[84:87], v[184:187], v[216:219], v[84:87]
	v_mfma_f32_16x16x32_bf16 v[80:83], v[192:195], v[216:219], v[80:83]
	v_mfma_f32_16x16x32_bf16 v[68:71], v[184:187], v[224:227], v[68:71]
	v_mfma_f32_16x16x32_bf16 v[64:67], v[192:195], v[224:227], v[64:67]
	v_mfma_f32_16x16x32_bf16 v[116:119], v[188:191], v[204:207], v[116:119]
	v_mfma_f32_16x16x32_bf16 v[112:115], v[196:199], v[204:207], v[112:115]
	v_mfma_f32_16x16x32_bf16 v[100:103], v[188:191], v[212:215], v[100:103]
	v_mfma_f32_16x16x32_bf16 v[96:99], v[196:199], v[212:215], v[96:99]
	v_mfma_f32_16x16x32_bf16 v[84:87], v[188:191], v[220:223], v[84:87]
	v_mfma_f32_16x16x32_bf16 v[80:83], v[196:199], v[220:223], v[80:83]
	v_mfma_f32_16x16x32_bf16 v[68:71], v[188:191], v[228:231], v[68:71]
	v_mfma_f32_16x16x32_bf16 v[64:67], v[196:199], v[228:231], v[64:67]
	s_barrier
	s_setprio 0
	s_add_i32 s10, s10, s66
	s_mov_b32 m0, s10
	ds_read_b128 v[200:203], v181 offset:49152
	ds_read_b128 v[204:207], v181 offset:50176
	ds_read_b128 v[208:211], v181 offset:51200
	global_load_lds_dwordx4 v138, s[60:61]
	s_add_i32 m0, s10, 0x2000
	ds_read_b128 v[212:215], v181 offset:52224
	global_load_lds_dwordx4 v142, s[60:61]
	s_add_u32 s60, s60, 0x40000
	s_addc_u32 s61, s61, 0
	s_add_i32 s10, s93, s66
	s_mov_b32 m0, s10
	ds_read_b128 v[216:219], v181 offset:53248
	global_load_lds_dwordx4 v138, s[60:61]
	s_add_i32 m0, s10, 0x2000
	ds_read_b128 v[220:223], v181 offset:54272
	global_load_lds_dwordx4 v142, s[60:61]
	s_mov_b32 m0, s73
	ds_read_b128 v[224:227], v181 offset:55296
	global_load_lds_dwordx4 v136, s[58:59]
	v_lshl_add_u64 v[232:233], s[58:59], 0, v[140:141]
	s_mov_b32 m0, s78
	ds_read_b128 v[228:231], v181 offset:56320
	global_load_lds_dwordx4 v[232:233], off
	s_waitcnt vmcnt(8)
	s_waitcnt lgkmcnt(0)
	s_setprio 1
	s_barrier
	v_mfma_f32_16x16x32_bf16 v[60:63], v[132:135], v[200:203], v[60:63]
	v_mfma_f32_16x16x32_bf16 v[56:59], v[162:165], v[200:203], v[56:59]
	v_mfma_f32_16x16x32_bf16 v[44:47], v[132:135], v[208:211], v[44:47]
	v_mfma_f32_16x16x32_bf16 v[40:43], v[162:165], v[208:211], v[40:43]
	v_mfma_f32_16x16x32_bf16 v[28:31], v[132:135], v[216:219], v[28:31]
	v_mfma_f32_16x16x32_bf16 v[24:27], v[162:165], v[216:219], v[24:27]
	v_mfma_f32_16x16x32_bf16 v[12:15], v[132:135], v[224:227], v[12:15]
	v_mfma_f32_16x16x32_bf16 v[8:11], v[162:165], v[224:227], v[8:11]
	v_mfma_f32_16x16x32_bf16 v[60:63], v[158:161], v[204:207], v[60:63]
	v_mfma_f32_16x16x32_bf16 v[56:59], v[166:169], v[204:207], v[56:59]
	v_mfma_f32_16x16x32_bf16 v[44:47], v[158:161], v[212:215], v[44:47]
	v_mfma_f32_16x16x32_bf16 v[40:43], v[166:169], v[212:215], v[40:43]
	v_mfma_f32_16x16x32_bf16 v[28:31], v[158:161], v[220:223], v[28:31]
	v_mfma_f32_16x16x32_bf16 v[24:27], v[166:169], v[220:223], v[24:27]
	v_mfma_f32_16x16x32_bf16 v[12:15], v[158:161], v[228:231], v[12:15]
	v_mfma_f32_16x16x32_bf16 v[8:11], v[166:169], v[228:231], v[8:11]
	s_setprio 0
	s_setprio 1
	v_mfma_f32_16x16x32_bf16 v[52:55], v[184:187], v[200:203], v[52:55]
	v_mfma_f32_16x16x32_bf16 v[48:51], v[192:195], v[200:203], v[48:51]
	v_mfma_f32_16x16x32_bf16 v[36:39], v[184:187], v[208:211], v[36:39]
	v_mfma_f32_16x16x32_bf16 v[32:35], v[192:195], v[208:211], v[32:35]
	v_mfma_f32_16x16x32_bf16 v[20:23], v[184:187], v[216:219], v[20:23]
	v_mfma_f32_16x16x32_bf16 v[16:19], v[192:195], v[216:219], v[16:19]
	v_mfma_f32_16x16x32_bf16 v[4:7], v[184:187], v[224:227], v[4:7]
	v_mfma_f32_16x16x32_bf16 v[0:3], v[192:195], v[224:227], v[0:3]
	v_mfma_f32_16x16x32_bf16 v[52:55], v[188:191], v[204:207], v[52:55]
	v_mfma_f32_16x16x32_bf16 v[48:51], v[196:199], v[204:207], v[48:51]
	v_mfma_f32_16x16x32_bf16 v[36:39], v[188:191], v[212:215], v[36:39]
	v_mfma_f32_16x16x32_bf16 v[32:35], v[196:199], v[212:215], v[32:35]
	v_mfma_f32_16x16x32_bf16 v[20:23], v[188:191], v[220:223], v[20:23]
	v_mfma_f32_16x16x32_bf16 v[16:19], v[196:199], v[220:223], v[16:19]
	v_mfma_f32_16x16x32_bf16 v[4:7], v[188:191], v[228:231], v[4:7]
	v_mfma_f32_16x16x32_bf16 v[0:3], v[196:199], v[228:231], v[0:3]
	s_barrier
	s_setprio 0
	s_add_i32 s10, s92, 2
	s_add_u32 s56, s56, 0x100
	s_addc_u32 s57, s57, 0
	s_cmp_gt_u32 s92, 13
	s_mov_b32 s92, s10
	s_cbranch_scc1 .LBB0_169
	s_branch .LBB0_163
.LBB0_162:
	v_add_u32_e32 v144, s82, v171
	ds_read_b128 v[132:135], v144
	ds_read_b128 v[158:161], v144 offset:1024
	ds_read_b128 v[162:165], v144 offset:2048
	ds_read_b128 v[166:169], v144 offset:3072
	v_add_u32_e32 v144, s83, v171
	ds_read_b128 v[184:187], v144
	ds_read_b128 v[188:191], v144 offset:1024
	ds_read_b128 v[192:195], v144 offset:2048
	ds_read_b128 v[196:199], v144 offset:3072
	s_add_u32 s10, s64, 0x100
	s_addc_u32 s95, s65, 0
	s_and_b64 s[64:65], exec, s[62:63]
	s_cselect_b32 s65, s23, s95
	s_cselect_b32 s64, s90, s10
	s_add_u32 s10, s94, 0x100
	s_addc_u32 s93, s93, 0
	s_and_b64 s[62:63], exec, s[62:63]
	s_cselect_b32 s63, s21, s93
	s_cselect_b32 s62, s91, s10
	v_lshl_add_u64 v[232:233], v[128:129], 0, s[56:57]
	s_add_i32 m0, s29, 0xc000
	ds_read_b128 v[200:203], v181
	ds_read_b128 v[204:207], v181 offset:1024
	ds_read_b128 v[208:211], v181 offset:2048
	ds_read_b128 v[212:215], v181 offset:3072
	ds_read_b128 v[216:219], v181 offset:4096
	ds_read_b128 v[220:223], v181 offset:5120
	ds_read_b128 v[224:227], v181 offset:6144
	global_load_lds_dwordx4 v[232:233], off
	v_lshl_add_u64 v[232:233], v[130:131], 0, s[56:57]
	s_add_i32 m0, s29, 0xe000
	ds_read_b128 v[228:231], v181 offset:7168
	global_load_lds_dwordx4 v[232:233], off
	s_waitcnt vmcnt(8)
	s_waitcnt lgkmcnt(0)
	s_setprio 1
	s_barrier
	v_mfma_f32_16x16x32_bf16 v[124:127], v[132:135], v[200:203], v[124:127]
	v_mfma_f32_16x16x32_bf16 v[120:123], v[162:165], v[200:203], v[120:123]
	v_mfma_f32_16x16x32_bf16 v[108:111], v[132:135], v[208:211], v[108:111]
	v_mfma_f32_16x16x32_bf16 v[104:107], v[162:165], v[208:211], v[104:107]
	v_mfma_f32_16x16x32_bf16 v[92:95], v[132:135], v[216:219], v[92:95]
	v_mfma_f32_16x16x32_bf16 v[88:91], v[162:165], v[216:219], v[88:91]
	v_mfma_f32_16x16x32_bf16 v[76:79], v[132:135], v[224:227], v[76:79]
	v_mfma_f32_16x16x32_bf16 v[72:75], v[162:165], v[224:227], v[72:75]
	v_mfma_f32_16x16x32_bf16 v[124:127], v[158:161], v[204:207], v[124:127]
	v_mfma_f32_16x16x32_bf16 v[120:123], v[166:169], v[204:207], v[120:123]
	v_mfma_f32_16x16x32_bf16 v[108:111], v[158:161], v[212:215], v[108:111]
	v_mfma_f32_16x16x32_bf16 v[104:107], v[166:169], v[212:215], v[104:107]
	v_mfma_f32_16x16x32_bf16 v[92:95], v[158:161], v[220:223], v[92:95]
	v_mfma_f32_16x16x32_bf16 v[88:91], v[166:169], v[220:223], v[88:91]
	v_mfma_f32_16x16x32_bf16 v[76:79], v[158:161], v[228:231], v[76:79]
	v_mfma_f32_16x16x32_bf16 v[72:75], v[166:169], v[228:231], v[72:75]
	s_setprio 0
	s_setprio 1
	v_mfma_f32_16x16x32_bf16 v[116:119], v[184:187], v[200:203], v[116:119]
	v_mfma_f32_16x16x32_bf16 v[112:115], v[192:195], v[200:203], v[112:115]
	v_mfma_f32_16x16x32_bf16 v[100:103], v[184:187], v[208:211], v[100:103]
	v_mfma_f32_16x16x32_bf16 v[96:99], v[192:195], v[208:211], v[96:99]
	v_mfma_f32_16x16x32_bf16 v[84:87], v[184:187], v[216:219], v[84:87]
	v_mfma_f32_16x16x32_bf16 v[80:83], v[192:195], v[216:219], v[80:83]
	v_mfma_f32_16x16x32_bf16 v[68:71], v[184:187], v[224:227], v[68:71]
	v_mfma_f32_16x16x32_bf16 v[64:67], v[192:195], v[224:227], v[64:67]
	v_mfma_f32_16x16x32_bf16 v[116:119], v[188:191], v[204:207], v[116:119]
	v_mfma_f32_16x16x32_bf16 v[112:115], v[196:199], v[204:207], v[112:115]
	v_mfma_f32_16x16x32_bf16 v[100:103], v[188:191], v[212:215], v[100:103]
	v_mfma_f32_16x16x32_bf16 v[96:99], v[196:199], v[212:215], v[96:99]
	v_mfma_f32_16x16x32_bf16 v[84:87], v[188:191], v[220:223], v[84:87]
	v_mfma_f32_16x16x32_bf16 v[80:83], v[196:199], v[220:223], v[80:83]
	v_mfma_f32_16x16x32_bf16 v[68:71], v[188:191], v[228:231], v[68:71]
	v_mfma_f32_16x16x32_bf16 v[64:67], v[196:199], v[228:231], v[64:67]
	s_barrier
	s_setprio 0
	s_add_i32 s10, s82, s66
	s_mov_b32 m0, s10
	ds_read_b128 v[200:203], v181 offset:16384
	ds_read_b128 v[204:207], v181 offset:17408
	ds_read_b128 v[208:211], v181 offset:18432
	global_load_lds_dwordx4 v138, s[62:63]
	s_add_i32 m0, s10, 0x2000
	ds_read_b128 v[212:215], v181 offset:19456
	global_load_lds_dwordx4 v142, s[62:63]
	s_add_u32 s62, s62, 0x40000
	s_addc_u32 s63, s63, 0
	s_add_i32 s10, s83, s66
	s_mov_b32 m0, s10
	ds_read_b128 v[216:219], v181 offset:20480
	global_load_lds_dwordx4 v138, s[62:63]
	s_add_i32 m0, s10, 0x2000
	ds_read_b128 v[220:223], v181 offset:21504
	global_load_lds_dwordx4 v142, s[62:63]
	s_mov_b32 m0, s29
	ds_read_b128 v[224:227], v181 offset:22528
	global_load_lds_dwordx4 v136, s[64:65]
	s_mov_b32 m0, s31
	ds_read_b128 v[228:231], v181 offset:23552
	global_load_lds_dwordx4 v140, s[64:65]
	s_waitcnt vmcnt(8)
	s_waitcnt lgkmcnt(0)
	s_setprio 1
	s_barrier
	v_mfma_f32_16x16x32_bf16 v[60:63], v[132:135], v[200:203], v[60:63]
	v_mfma_f32_16x16x32_bf16 v[56:59], v[162:165], v[200:203], v[56:59]
	v_mfma_f32_16x16x32_bf16 v[44:47], v[132:135], v[208:211], v[44:47]
	v_mfma_f32_16x16x32_bf16 v[40:43], v[162:165], v[208:211], v[40:43]
	v_mfma_f32_16x16x32_bf16 v[28:31], v[132:135], v[216:219], v[28:31]
	v_mfma_f32_16x16x32_bf16 v[24:27], v[162:165], v[216:219], v[24:27]
	v_mfma_f32_16x16x32_bf16 v[12:15], v[132:135], v[224:227], v[12:15]
	v_mfma_f32_16x16x32_bf16 v[8:11], v[162:165], v[224:227], v[8:11]
	v_mfma_f32_16x16x32_bf16 v[60:63], v[158:161], v[204:207], v[60:63]
	v_mfma_f32_16x16x32_bf16 v[56:59], v[166:169], v[204:207], v[56:59]
	v_mfma_f32_16x16x32_bf16 v[44:47], v[158:161], v[212:215], v[44:47]
	v_mfma_f32_16x16x32_bf16 v[40:43], v[166:169], v[212:215], v[40:43]
	v_mfma_f32_16x16x32_bf16 v[28:31], v[158:161], v[220:223], v[28:31]
	v_mfma_f32_16x16x32_bf16 v[24:27], v[166:169], v[220:223], v[24:27]
	v_mfma_f32_16x16x32_bf16 v[12:15], v[158:161], v[228:231], v[12:15]
	v_mfma_f32_16x16x32_bf16 v[8:11], v[166:169], v[228:231], v[8:11]
	s_setprio 0
	s_setprio 1
	v_mfma_f32_16x16x32_bf16 v[52:55], v[184:187], v[200:203], v[52:55]
	v_mfma_f32_16x16x32_bf16 v[48:51], v[192:195], v[200:203], v[48:51]
	v_mfma_f32_16x16x32_bf16 v[36:39], v[184:187], v[208:211], v[36:39]
	v_mfma_f32_16x16x32_bf16 v[32:35], v[192:195], v[208:211], v[32:35]
	v_mfma_f32_16x16x32_bf16 v[20:23], v[184:187], v[216:219], v[20:23]
	v_mfma_f32_16x16x32_bf16 v[16:19], v[192:195], v[216:219], v[16:19]
	v_mfma_f32_16x16x32_bf16 v[4:7], v[184:187], v[224:227], v[4:7]
	v_mfma_f32_16x16x32_bf16 v[0:3], v[192:195], v[224:227], v[0:3]
	v_mfma_f32_16x16x32_bf16 v[52:55], v[188:191], v[204:207], v[52:55]
	v_mfma_f32_16x16x32_bf16 v[48:51], v[196:199], v[204:207], v[48:51]
	v_mfma_f32_16x16x32_bf16 v[36:39], v[188:191], v[212:215], v[36:39]
	v_mfma_f32_16x16x32_bf16 v[32:35], v[196:199], v[212:215], v[32:35]
	v_mfma_f32_16x16x32_bf16 v[20:23], v[188:191], v[220:223], v[20:23]
	v_mfma_f32_16x16x32_bf16 v[16:19], v[196:199], v[220:223], v[16:19]
	v_mfma_f32_16x16x32_bf16 v[4:7], v[188:191], v[228:231], v[4:7]
	v_mfma_f32_16x16x32_bf16 v[0:3], v[196:199], v[228:231], v[0:3]
	s_barrier
	s_setprio 0
	s_add_i32 s10, 0, 0x18000
	v_add_u32_e32 v144, s10, v171
	s_add_i32 s93, 0, 0x1c000
	ds_read_b128 v[132:135], v144
	ds_read_b128 v[158:161], v144 offset:1024
	ds_read_b128 v[162:165], v144 offset:2048
	ds_read_b128 v[166:169], v144 offset:3072
	v_add_u32_e32 v144, s93, v171
	ds_read_b128 v[184:187], v144
	ds_read_b128 v[188:191], v144 offset:1024
	ds_read_b128 v[192:195], v144 offset:2048
	ds_read_b128 v[196:199], v144 offset:3072
	s_add_u32 s62, s64, 0x40000
	s_addc_u32 s63, s65, 0
	s_mov_b32 m0, s67
	ds_read_b128 v[200:203], v181 offset:32768
	ds_read_b128 v[204:207], v181 offset:33792
	ds_read_b128 v[208:211], v181 offset:34816
	ds_read_b128 v[212:215], v181 offset:35840
	ds_read_b128 v[216:219], v181 offset:36864
	ds_read_b128 v[220:223], v181 offset:37888
	ds_read_b128 v[224:227], v181 offset:38912
	global_load_lds_dwordx4 v136, s[62:63]
	s_mov_b32 m0, s68
	ds_read_b128 v[228:231], v181 offset:39936
	global_load_lds_dwordx4 v140, s[62:63]
	s_waitcnt vmcnt(8)
	s_waitcnt lgkmcnt(0)
	s_setprio 1
	s_barrier
	v_mfma_f32_16x16x32_bf16 v[124:127], v[132:135], v[200:203], v[124:127]
	v_mfma_f32_16x16x32_bf16 v[120:123], v[162:165], v[200:203], v[120:123]
	v_mfma_f32_16x16x32_bf16 v[108:111], v[132:135], v[208:211], v[108:111]
	v_mfma_f32_16x16x32_bf16 v[104:107], v[162:165], v[208:211], v[104:107]
	v_mfma_f32_16x16x32_bf16 v[92:95], v[132:135], v[216:219], v[92:95]
	v_mfma_f32_16x16x32_bf16 v[88:91], v[162:165], v[216:219], v[88:91]
	v_mfma_f32_16x16x32_bf16 v[76:79], v[132:135], v[224:227], v[76:79]
	v_mfma_f32_16x16x32_bf16 v[72:75], v[162:165], v[224:227], v[72:75]
	v_mfma_f32_16x16x32_bf16 v[124:127], v[158:161], v[204:207], v[124:127]
	v_mfma_f32_16x16x32_bf16 v[120:123], v[166:169], v[204:207], v[120:123]
	v_mfma_f32_16x16x32_bf16 v[108:111], v[158:161], v[212:215], v[108:111]
	v_mfma_f32_16x16x32_bf16 v[104:107], v[166:169], v[212:215], v[104:107]
	v_mfma_f32_16x16x32_bf16 v[92:95], v[158:161], v[220:223], v[92:95]
	v_mfma_f32_16x16x32_bf16 v[88:91], v[166:169], v[220:223], v[88:91]
	v_mfma_f32_16x16x32_bf16 v[76:79], v[158:161], v[228:231], v[76:79]
	v_mfma_f32_16x16x32_bf16 v[72:75], v[166:169], v[228:231], v[72:75]
	s_setprio 0
	s_setprio 1
	v_mfma_f32_16x16x32_bf16 v[116:119], v[184:187], v[200:203], v[116:119]
	v_mfma_f32_16x16x32_bf16 v[112:115], v[192:195], v[200:203], v[112:115]
	v_mfma_f32_16x16x32_bf16 v[100:103], v[184:187], v[208:211], v[100:103]
	v_mfma_f32_16x16x32_bf16 v[96:99], v[192:195], v[208:211], v[96:99]
	v_mfma_f32_16x16x32_bf16 v[84:87], v[184:187], v[216:219], v[84:87]
	v_mfma_f32_16x16x32_bf16 v[80:83], v[192:195], v[216:219], v[80:83]
	v_mfma_f32_16x16x32_bf16 v[68:71], v[184:187], v[224:227], v[68:71]
	v_mfma_f32_16x16x32_bf16 v[64:67], v[192:195], v[224:227], v[64:67]
	v_mfma_f32_16x16x32_bf16 v[116:119], v[188:191], v[204:207], v[116:119]
	v_mfma_f32_16x16x32_bf16 v[112:115], v[196:199], v[204:207], v[112:115]
	v_mfma_f32_16x16x32_bf16 v[100:103], v[188:191], v[212:215], v[100:103]
	v_mfma_f32_16x16x32_bf16 v[96:99], v[196:199], v[212:215], v[96:99]
	v_mfma_f32_16x16x32_bf16 v[84:87], v[188:191], v[220:223], v[84:87]
	v_mfma_f32_16x16x32_bf16 v[80:83], v[196:199], v[220:223], v[80:83]
	v_mfma_f32_16x16x32_bf16 v[68:71], v[188:191], v[228:231], v[68:71]
	v_mfma_f32_16x16x32_bf16 v[64:67], v[196:199], v[228:231], v[64:67]
	s_barrier
	s_setprio 0
	s_add_i32 s10, s10, s66
	s_mov_b32 m0, s10
	ds_read_b128 v[200:203], v181 offset:49152
	ds_read_b128 v[204:207], v181 offset:50176
	ds_read_b128 v[208:211], v181 offset:51200
	global_load_lds_dwordx4 v138, s[60:61]
	s_add_i32 m0, s10, 0x2000
	ds_read_b128 v[212:215], v181 offset:52224
	global_load_lds_dwordx4 v142, s[60:61]
	s_add_u32 s60, s60, 0x40000
	s_addc_u32 s61, s61, 0
	s_add_i32 s10, s93, s66
	s_mov_b32 m0, s10
	ds_read_b128 v[216:219], v181 offset:53248
	global_load_lds_dwordx4 v138, s[60:61]
	s_add_i32 m0, s10, 0x2000
	ds_read_b128 v[220:223], v181 offset:54272
	global_load_lds_dwordx4 v142, s[60:61]
	s_mov_b32 m0, s73
	ds_read_b128 v[224:227], v181 offset:55296
	global_load_lds_dwordx4 v136, s[58:59]
	v_lshl_add_u64 v[232:233], s[58:59], 0, v[140:141]
	s_mov_b32 m0, s78
	ds_read_b128 v[228:231], v181 offset:56320
	global_load_lds_dwordx4 v[232:233], off
	s_waitcnt vmcnt(8)
	s_waitcnt lgkmcnt(0)
	s_setprio 1
	s_barrier
	v_mfma_f32_16x16x32_bf16 v[60:63], v[132:135], v[200:203], v[60:63]
	v_mfma_f32_16x16x32_bf16 v[56:59], v[162:165], v[200:203], v[56:59]
	v_mfma_f32_16x16x32_bf16 v[44:47], v[132:135], v[208:211], v[44:47]
	v_mfma_f32_16x16x32_bf16 v[40:43], v[162:165], v[208:211], v[40:43]
	v_mfma_f32_16x16x32_bf16 v[28:31], v[132:135], v[216:219], v[28:31]
	v_mfma_f32_16x16x32_bf16 v[24:27], v[162:165], v[216:219], v[24:27]
	v_mfma_f32_16x16x32_bf16 v[12:15], v[132:135], v[224:227], v[12:15]
	v_mfma_f32_16x16x32_bf16 v[8:11], v[162:165], v[224:227], v[8:11]
	v_mfma_f32_16x16x32_bf16 v[60:63], v[158:161], v[204:207], v[60:63]
	v_mfma_f32_16x16x32_bf16 v[56:59], v[166:169], v[204:207], v[56:59]
	v_mfma_f32_16x16x32_bf16 v[44:47], v[158:161], v[212:215], v[44:47]
	v_mfma_f32_16x16x32_bf16 v[40:43], v[166:169], v[212:215], v[40:43]
	v_mfma_f32_16x16x32_bf16 v[28:31], v[158:161], v[220:223], v[28:31]
	v_mfma_f32_16x16x32_bf16 v[24:27], v[166:169], v[220:223], v[24:27]
	v_mfma_f32_16x16x32_bf16 v[12:15], v[158:161], v[228:231], v[12:15]
	v_mfma_f32_16x16x32_bf16 v[8:11], v[166:169], v[228:231], v[8:11]
	s_setprio 0
	s_setprio 1
	v_mfma_f32_16x16x32_bf16 v[52:55], v[184:187], v[200:203], v[52:55]
	v_mfma_f32_16x16x32_bf16 v[48:51], v[192:195], v[200:203], v[48:51]
	v_mfma_f32_16x16x32_bf16 v[36:39], v[184:187], v[208:211], v[36:39]
	v_mfma_f32_16x16x32_bf16 v[32:35], v[192:195], v[208:211], v[32:35]
	v_mfma_f32_16x16x32_bf16 v[20:23], v[184:187], v[216:219], v[20:23]
	v_mfma_f32_16x16x32_bf16 v[16:19], v[192:195], v[216:219], v[16:19]
	v_mfma_f32_16x16x32_bf16 v[4:7], v[184:187], v[224:227], v[4:7]
	v_mfma_f32_16x16x32_bf16 v[0:3], v[192:195], v[224:227], v[0:3]
	v_mfma_f32_16x16x32_bf16 v[52:55], v[188:191], v[204:207], v[52:55]
	v_mfma_f32_16x16x32_bf16 v[48:51], v[196:199], v[204:207], v[48:51]
	v_mfma_f32_16x16x32_bf16 v[36:39], v[188:191], v[212:215], v[36:39]
	v_mfma_f32_16x16x32_bf16 v[32:35], v[196:199], v[212:215], v[32:35]
	v_mfma_f32_16x16x32_bf16 v[20:23], v[188:191], v[220:223], v[20:23]
	v_mfma_f32_16x16x32_bf16 v[16:19], v[196:199], v[220:223], v[16:19]
	v_mfma_f32_16x16x32_bf16 v[4:7], v[188:191], v[228:231], v[4:7]
	v_mfma_f32_16x16x32_bf16 v[0:3], v[196:199], v[228:231], v[0:3]
	s_barrier
	s_setprio 0
	s_add_i32 s10, s92, 2
	s_add_u32 s56, s56, 0x100
	s_addc_u32 s57, s57, 0
	s_cmp_gt_u32 s92, 13
	s_mov_b32 s92, s10
	s_cbranch_scc1 .LBB0_169

.LBB0_612:
	s_cmp_lt_u32 s95, 8
	v_add_u32_e32 v157, s79, v155
	s_cselect_b64 s[56:57], -1, 0
	ds_read_b128 v[128:131], v157
	ds_read_b128 v[132:135], v157 offset:1024
	ds_read_b128 v[158:161], v157 offset:2048
	ds_read_b128 v[162:165], v157 offset:3072
	v_add_u32_e32 v157, s80, v155
	s_and_b64 s[96:97], s[56:57], exec
	ds_read_b128 v[166:169], v157
	ds_read_b128 v[170:173], v157 offset:1024
	ds_read_b128 v[174:177], v157 offset:2048
	ds_read_b128 v[178:181], v157 offset:3072
	s_cselect_b32 s8, 0, -8
	s_add_i32 s8, s8, s95
	s_add_i32 s8, s8, 1
	s_and_b64 s[56:57], s[56:57], exec
	s_cselect_b32 s96, s29, s85
	s_cselect_b32 s97, s28, s84
	s_lshl_b64 s[56:57], s[8:9], 7
	s_add_u32 s8, s97, s56
	s_addc_u32 s57, s96, s57
	s_add_u32 s56, s8, 0x160000
	s_addc_u32 s57, s57, 0
	s_add_i32 m0, s62, 0xc000
	ds_read_b128 v[182:185], v156
	ds_read_b128 v[186:189], v156 offset:1024
	ds_read_b128 v[190:193], v156 offset:2048
	ds_read_b128 v[194:197], v156 offset:3072
	ds_read_b128 v[198:201], v156 offset:4096
	ds_read_b128 v[202:205], v156 offset:5120
	ds_read_b128 v[206:209], v156 offset:6144
	ds_read_b128 v[210:213], v156 offset:7168
	global_load_lds_dwordx4 v136, s[56:57]
	s_add_i32 m0, s62, 0xe000
	s_nop 0
	global_load_lds_dwordx4 v140, s[56:57]
	s_waitcnt vmcnt(8)
	s_waitcnt lgkmcnt(0)
	s_setprio 1
	s_barrier
	v_mfma_f32_16x16x32_bf16 v[124:127], v[128:131], v[182:185], v[124:127]
	v_mfma_f32_16x16x32_bf16 v[120:123], v[158:161], v[182:185], v[120:123]
	v_mfma_f32_16x16x32_bf16 v[112:115], v[128:131], v[190:193], v[112:115]
	v_mfma_f32_16x16x32_bf16 v[104:107], v[158:161], v[190:193], v[104:107]
	v_mfma_f32_16x16x32_bf16 v[96:99], v[128:131], v[198:201], v[96:99]
	v_mfma_f32_16x16x32_bf16 v[88:91], v[158:161], v[198:201], v[88:91]
	v_mfma_f32_16x16x32_bf16 v[80:83], v[128:131], v[206:209], v[80:83]
	v_mfma_f32_16x16x32_bf16 v[72:75], v[158:161], v[206:209], v[72:75]
	v_mfma_f32_16x16x32_bf16 v[124:127], v[132:135], v[186:189], v[124:127]
	v_mfma_f32_16x16x32_bf16 v[120:123], v[162:165], v[186:189], v[120:123]
	v_mfma_f32_16x16x32_bf16 v[112:115], v[132:135], v[194:197], v[112:115]
	v_mfma_f32_16x16x32_bf16 v[104:107], v[162:165], v[194:197], v[104:107]
	v_mfma_f32_16x16x32_bf16 v[96:99], v[132:135], v[202:205], v[96:99]
	v_mfma_f32_16x16x32_bf16 v[88:91], v[162:165], v[202:205], v[88:91]
	v_mfma_f32_16x16x32_bf16 v[80:83], v[132:135], v[210:213], v[80:83]
	v_mfma_f32_16x16x32_bf16 v[72:75], v[162:165], v[210:213], v[72:75]
	s_setprio 0
	s_setprio 1
	v_mfma_f32_16x16x32_bf16 v[116:119], v[166:169], v[182:185], v[116:119]
	v_mfma_f32_16x16x32_bf16 v[108:111], v[174:177], v[182:185], v[108:111]
	v_mfma_f32_16x16x32_bf16 v[100:103], v[166:169], v[190:193], v[100:103]
	v_mfma_f32_16x16x32_bf16 v[92:95], v[174:177], v[190:193], v[92:95]
	v_mfma_f32_16x16x32_bf16 v[84:87], v[166:169], v[198:201], v[84:87]
	v_mfma_f32_16x16x32_bf16 v[76:79], v[174:177], v[198:201], v[76:79]
	v_mfma_f32_16x16x32_bf16 v[68:71], v[166:169], v[206:209], v[68:71]
	v_mfma_f32_16x16x32_bf16 v[64:67], v[174:177], v[206:209], v[64:67]
	v_mfma_f32_16x16x32_bf16 v[116:119], v[170:173], v[186:189], v[116:119]
	v_mfma_f32_16x16x32_bf16 v[108:111], v[178:181], v[186:189], v[108:111]
	v_mfma_f32_16x16x32_bf16 v[100:103], v[170:173], v[194:197], v[100:103]
	v_mfma_f32_16x16x32_bf16 v[92:95], v[178:181], v[194:197], v[92:95]
	v_mfma_f32_16x16x32_bf16 v[84:87], v[170:173], v[202:205], v[84:87]
	v_mfma_f32_16x16x32_bf16 v[76:79], v[178:181], v[202:205], v[76:79]
	v_mfma_f32_16x16x32_bf16 v[68:71], v[170:173], v[210:213], v[68:71]
	v_mfma_f32_16x16x32_bf16 v[64:67], v[178:181], v[210:213], v[64:67]
	s_barrier
	s_setprio 0
	s_add_i32 s8, s79, s61
	s_mov_b32 m0, s8
	ds_read_b128 v[182:185], v156 offset:16384
	ds_read_b128 v[186:189], v156 offset:17408
	ds_read_b128 v[190:193], v156 offset:18432
	ds_read_b128 v[194:197], v156 offset:19456
	ds_read_b128 v[198:201], v156 offset:20480
	ds_read_b128 v[202:205], v156 offset:21504
	ds_read_b128 v[206:209], v156 offset:22528
	ds_read_b128 v[210:213], v156 offset:23552
	global_load_lds_dwordx4 v138, s[54:55]
	s_add_i32 m0, s8, 0x2000
	s_nop 0
	global_load_lds_dwordx4 v142, s[54:55]
	s_add_u32 s54, s54, 0x20000
	s_addc_u32 s55, s55, 0
	s_add_i32 s8, s80, s61
	s_mov_b32 m0, s8
	s_nop 0
	global_load_lds_dwordx4 v138, s[54:55]
	s_add_i32 m0, s8, 0x2000
	s_nop 0
	global_load_lds_dwordx4 v142, s[54:55]
	s_mov_b32 m0, s62
	s_nop 0
	global_load_lds_dwordx4 v136, s[50:51]
	s_mov_b32 m0, s63
	s_nop 0
	global_load_lds_dwordx4 v140, s[50:51]
	s_waitcnt vmcnt(8)
	s_waitcnt lgkmcnt(0)
	s_setprio 1
	s_barrier
	v_mfma_f32_16x16x32_bf16 v[60:63], v[128:131], v[182:185], v[60:63]
	v_mfma_f32_16x16x32_bf16 v[56:59], v[158:161], v[182:185], v[56:59]
	v_mfma_f32_16x16x32_bf16 v[48:51], v[128:131], v[190:193], v[48:51]
	v_mfma_f32_16x16x32_bf16 v[40:43], v[158:161], v[190:193], v[40:43]
	v_mfma_f32_16x16x32_bf16 v[32:35], v[128:131], v[198:201], v[32:35]
	v_mfma_f32_16x16x32_bf16 v[24:27], v[158:161], v[198:201], v[24:27]
	v_mfma_f32_16x16x32_bf16 v[16:19], v[128:131], v[206:209], v[16:19]
	v_mfma_f32_16x16x32_bf16 v[8:11], v[158:161], v[206:209], v[8:11]
	v_mfma_f32_16x16x32_bf16 v[60:63], v[132:135], v[186:189], v[60:63]
	v_mfma_f32_16x16x32_bf16 v[56:59], v[162:165], v[186:189], v[56:59]
	v_mfma_f32_16x16x32_bf16 v[48:51], v[132:135], v[194:197], v[48:51]
	v_mfma_f32_16x16x32_bf16 v[40:43], v[162:165], v[194:197], v[40:43]
	v_mfma_f32_16x16x32_bf16 v[32:35], v[132:135], v[202:205], v[32:35]
	v_mfma_f32_16x16x32_bf16 v[24:27], v[162:165], v[202:205], v[24:27]
	v_mfma_f32_16x16x32_bf16 v[16:19], v[132:135], v[210:213], v[16:19]
	v_mfma_f32_16x16x32_bf16 v[8:11], v[162:165], v[210:213], v[8:11]
	s_setprio 0
	s_setprio 1
	v_mfma_f32_16x16x32_bf16 v[52:55], v[166:169], v[182:185], v[52:55]
	v_mfma_f32_16x16x32_bf16 v[44:47], v[174:177], v[182:185], v[44:47]
	v_mfma_f32_16x16x32_bf16 v[36:39], v[166:169], v[190:193], v[36:39]
	v_mfma_f32_16x16x32_bf16 v[28:31], v[174:177], v[190:193], v[28:31]
	v_mfma_f32_16x16x32_bf16 v[20:23], v[166:169], v[198:201], v[20:23]
	v_mfma_f32_16x16x32_bf16 v[12:15], v[174:177], v[198:201], v[12:15]
	v_mfma_f32_16x16x32_bf16 v[4:7], v[166:169], v[206:209], v[4:7]
	v_mfma_f32_16x16x32_bf16 v[0:3], v[174:177], v[206:209], v[0:3]
	v_mfma_f32_16x16x32_bf16 v[52:55], v[170:173], v[186:189], v[52:55]
	v_mfma_f32_16x16x32_bf16 v[44:47], v[178:181], v[186:189], v[44:47]
	v_mfma_f32_16x16x32_bf16 v[36:39], v[170:173], v[194:197], v[36:39]
	v_mfma_f32_16x16x32_bf16 v[28:31], v[178:181], v[194:197], v[28:31]
	v_mfma_f32_16x16x32_bf16 v[20:23], v[170:173], v[202:205], v[20:23]
	v_mfma_f32_16x16x32_bf16 v[12:15], v[178:181], v[202:205], v[12:15]
	v_mfma_f32_16x16x32_bf16 v[4:7], v[170:173], v[210:213], v[4:7]
	v_mfma_f32_16x16x32_bf16 v[0:3], v[178:181], v[210:213], v[0:3]
	s_barrier
	s_setprio 0
	s_add_i32 s8, 0, 0x18000
	v_add_u32_e32 v157, s8, v155
	s_add_i32 s54, 0, 0x1c000
	ds_read_b128 v[128:131], v157
	ds_read_b128 v[132:135], v157 offset:1024
	ds_read_b128 v[158:161], v157 offset:2048
	ds_read_b128 v[162:165], v157 offset:3072
	v_add_u32_e32 v157, s54, v155
	ds_read_b128 v[166:169], v157
	ds_read_b128 v[170:173], v157 offset:1024
	ds_read_b128 v[174:177], v157 offset:2048
	ds_read_b128 v[178:181], v157 offset:3072
	s_add_u32 s50, s50, 0x160000
	s_addc_u32 s51, s51, 0
	s_mov_b32 m0, s64
	ds_read_b128 v[182:185], v156 offset:32768
	ds_read_b128 v[186:189], v156 offset:33792
	ds_read_b128 v[190:193], v156 offset:34816
	ds_read_b128 v[194:197], v156 offset:35840
	ds_read_b128 v[198:201], v156 offset:36864
	ds_read_b128 v[202:205], v156 offset:37888
	ds_read_b128 v[206:209], v156 offset:38912
	ds_read_b128 v[210:213], v156 offset:39936
	global_load_lds_dwordx4 v136, s[50:51]
	s_mov_b32 m0, s65
	s_nop 0
	global_load_lds_dwordx4 v140, s[50:51]
	s_waitcnt vmcnt(8)
	s_waitcnt lgkmcnt(0)
	s_setprio 1
	s_barrier
	v_mfma_f32_16x16x32_bf16 v[124:127], v[128:131], v[182:185], v[124:127]
	v_mfma_f32_16x16x32_bf16 v[120:123], v[158:161], v[182:185], v[120:123]
	v_mfma_f32_16x16x32_bf16 v[112:115], v[128:131], v[190:193], v[112:115]
	v_mfma_f32_16x16x32_bf16 v[104:107], v[158:161], v[190:193], v[104:107]
	v_mfma_f32_16x16x32_bf16 v[96:99], v[128:131], v[198:201], v[96:99]
	v_mfma_f32_16x16x32_bf16 v[88:91], v[158:161], v[198:201], v[88:91]
	v_mfma_f32_16x16x32_bf16 v[80:83], v[128:131], v[206:209], v[80:83]
	v_mfma_f32_16x16x32_bf16 v[72:75], v[158:161], v[206:209], v[72:75]
	v_mfma_f32_16x16x32_bf16 v[124:127], v[132:135], v[186:189], v[124:127]
	v_mfma_f32_16x16x32_bf16 v[120:123], v[162:165], v[186:189], v[120:123]
	v_mfma_f32_16x16x32_bf16 v[112:115], v[132:135], v[194:197], v[112:115]
	v_mfma_f32_16x16x32_bf16 v[104:107], v[162:165], v[194:197], v[104:107]
	v_mfma_f32_16x16x32_bf16 v[96:99], v[132:135], v[202:205], v[96:99]
	v_mfma_f32_16x16x32_bf16 v[88:91], v[162:165], v[202:205], v[88:91]
	v_mfma_f32_16x16x32_bf16 v[80:83], v[132:135], v[210:213], v[80:83]
	v_mfma_f32_16x16x32_bf16 v[72:75], v[162:165], v[210:213], v[72:75]
	s_setprio 0
	s_setprio 1
	v_mfma_f32_16x16x32_bf16 v[116:119], v[166:169], v[182:185], v[116:119]
	v_mfma_f32_16x16x32_bf16 v[108:111], v[174:177], v[182:185], v[108:111]
	v_mfma_f32_16x16x32_bf16 v[100:103], v[166:169], v[190:193], v[100:103]
	v_mfma_f32_16x16x32_bf16 v[92:95], v[174:177], v[190:193], v[92:95]
	v_mfma_f32_16x16x32_bf16 v[84:87], v[166:169], v[198:201], v[84:87]
	v_mfma_f32_16x16x32_bf16 v[76:79], v[174:177], v[198:201], v[76:79]
	v_mfma_f32_16x16x32_bf16 v[68:71], v[166:169], v[206:209], v[68:71]
	v_mfma_f32_16x16x32_bf16 v[64:67], v[174:177], v[206:209], v[64:67]
	v_mfma_f32_16x16x32_bf16 v[116:119], v[170:173], v[186:189], v[116:119]
	v_mfma_f32_16x16x32_bf16 v[108:111], v[178:181], v[186:189], v[108:111]
	v_mfma_f32_16x16x32_bf16 v[100:103], v[170:173], v[194:197], v[100:103]
	v_mfma_f32_16x16x32_bf16 v[92:95], v[178:181], v[194:197], v[92:95]
	v_mfma_f32_16x16x32_bf16 v[84:87], v[170:173], v[202:205], v[84:87]
	v_mfma_f32_16x16x32_bf16 v[76:79], v[178:181], v[202:205], v[76:79]
	v_mfma_f32_16x16x32_bf16 v[68:71], v[170:173], v[210:213], v[68:71]
	v_mfma_f32_16x16x32_bf16 v[64:67], v[178:181], v[210:213], v[64:67]
	s_barrier
	s_setprio 0
	s_add_i32 s8, s8, s61
	s_mov_b32 m0, s8
	ds_read_b128 v[182:185], v156 offset:49152
	ds_read_b128 v[186:189], v156 offset:50176
	ds_read_b128 v[190:193], v156 offset:51200
	ds_read_b128 v[194:197], v156 offset:52224
	ds_read_b128 v[198:201], v156 offset:53248
	ds_read_b128 v[202:205], v156 offset:54272
	ds_read_b128 v[206:209], v156 offset:55296
	ds_read_b128 v[210:213], v156 offset:56320
	global_load_lds_dwordx4 v138, s[4:5]
	s_add_i32 m0, s8, 0x2000
	s_nop 0
	global_load_lds_dwordx4 v142, s[4:5]
	s_add_u32 s4, s4, 0x20000
	s_addc_u32 s5, s5, 0
	s_add_i32 s8, s54, s61
	s_mov_b32 m0, s8
	s_nop 0
	global_load_lds_dwordx4 v138, s[4:5]
	s_add_i32 m0, s8, 0x2000
	s_nop 0
	global_load_lds_dwordx4 v142, s[4:5]
	s_mov_b32 m0, s71
	s_nop 0
	global_load_lds_dwordx4 v136, s[52:53]
	s_mov_b32 m0, s72
	s_nop 0
	global_load_lds_dwordx4 v140, s[52:53]
	s_waitcnt vmcnt(8)
	s_waitcnt lgkmcnt(0)
	s_setprio 1
	s_barrier
	v_mfma_f32_16x16x32_bf16 v[60:63], v[128:131], v[182:185], v[60:63]
	v_mfma_f32_16x16x32_bf16 v[56:59], v[158:161], v[182:185], v[56:59]
	v_mfma_f32_16x16x32_bf16 v[48:51], v[128:131], v[190:193], v[48:51]
	v_mfma_f32_16x16x32_bf16 v[40:43], v[158:161], v[190:193], v[40:43]
	v_mfma_f32_16x16x32_bf16 v[32:35], v[128:131], v[198:201], v[32:35]
	v_mfma_f32_16x16x32_bf16 v[24:27], v[158:161], v[198:201], v[24:27]
	v_mfma_f32_16x16x32_bf16 v[16:19], v[128:131], v[206:209], v[16:19]
	v_mfma_f32_16x16x32_bf16 v[8:11], v[158:161], v[206:209], v[8:11]
	v_mfma_f32_16x16x32_bf16 v[60:63], v[132:135], v[186:189], v[60:63]
	v_mfma_f32_16x16x32_bf16 v[56:59], v[162:165], v[186:189], v[56:59]
	v_mfma_f32_16x16x32_bf16 v[48:51], v[132:135], v[194:197], v[48:51]
	v_mfma_f32_16x16x32_bf16 v[40:43], v[162:165], v[194:197], v[40:43]
	v_mfma_f32_16x16x32_bf16 v[32:35], v[132:135], v[202:205], v[32:35]
	v_mfma_f32_16x16x32_bf16 v[24:27], v[162:165], v[202:205], v[24:27]
	v_mfma_f32_16x16x32_bf16 v[16:19], v[132:135], v[210:213], v[16:19]
	v_mfma_f32_16x16x32_bf16 v[8:11], v[162:165], v[210:213], v[8:11]
	s_setprio 0
	s_setprio 1
	v_mfma_f32_16x16x32_bf16 v[52:55], v[166:169], v[182:185], v[52:55]
	v_mfma_f32_16x16x32_bf16 v[44:47], v[174:177], v[182:185], v[44:47]
	v_mfma_f32_16x16x32_bf16 v[36:39], v[166:169], v[190:193], v[36:39]
	v_mfma_f32_16x16x32_bf16 v[28:31], v[174:177], v[190:193], v[28:31]
	v_mfma_f32_16x16x32_bf16 v[20:23], v[166:169], v[198:201], v[20:23]
	v_mfma_f32_16x16x32_bf16 v[12:15], v[174:177], v[198:201], v[12:15]
	v_mfma_f32_16x16x32_bf16 v[4:7], v[166:169], v[206:209], v[4:7]
	v_mfma_f32_16x16x32_bf16 v[0:3], v[174:177], v[206:209], v[0:3]
	v_mfma_f32_16x16x32_bf16 v[52:55], v[170:173], v[186:189], v[52:55]
	v_mfma_f32_16x16x32_bf16 v[44:47], v[178:181], v[186:189], v[44:47]
	v_mfma_f32_16x16x32_bf16 v[36:39], v[170:173], v[194:197], v[36:39]
	v_mfma_f32_16x16x32_bf16 v[28:31], v[178:181], v[194:197], v[28:31]
	v_mfma_f32_16x16x32_bf16 v[20:23], v[170:173], v[202:205], v[20:23]
	v_mfma_f32_16x16x32_bf16 v[12:15], v[178:181], v[202:205], v[12:15]
	v_mfma_f32_16x16x32_bf16 v[4:7], v[170:173], v[210:213], v[4:7]
	v_mfma_f32_16x16x32_bf16 v[0:3], v[178:181], v[210:213], v[0:3]
	s_barrier
	s_setprio 0
	s_add_i32 s4, s95, 2
	s_add_u32 s48, s48, 0x100
	s_addc_u32 s49, s49, 0
	s_cmp_gt_u32 s95, 13
	s_mov_b32 s95, s4
	s_cbranch_scc1 .LBB0_635

.LBB0_713:
	s_add_u32 s19, s63, s6
	s_addc_u32 s29, s64, s7
	s_add_u32 s31, s65, s8
	s_addc_u32 s79, s66, s9
	s_ashr_i32 s23, s22, 31
	s_lshl_b64 s[6:7], s[22:23], 19
	s_add_u32 s24, s34, s6
	s_addc_u32 s25, s35, s7
	s_and_b64 s[8:9], s[4:5], exec
	s_cselect_b32 s23, s25, s45
	s_cselect_b32 s80, s24, s44
	s_ashr_i32 s21, s20, 31
	s_lshl_b64 s[8:9], s[20:21], 19
	s_add_u32 s26, s42, s8
	s_addc_u32 s27, s43, s9
	s_and_b64 s[36:37], s[4:5], exec
	s_cselect_b32 s21, s27, s39
	s_cselect_b32 s81, s26, s38
	s_add_u32 s36, s80, 0x80
	s_addc_u32 s37, s23, 0
	s_add_u32 s46, s81, 0x80
	s_addc_u32 s47, s21, 0
	v_lshl_add_u64 v[128:129], s[44:45], 0, v[156:157]
	v_lshl_add_u64 v[130:131], s[44:45], 0, v[158:159]
	s_mov_b32 s82, 0
	s_mov_b64 s[48:49], 0
	s_cmpk_eq_i32 s48, 0x700
	s_cselect_b64 s[54:55], -1, 0
	s_add_u32 s56, s44, s48
	s_addc_u32 s57, s45, s49
	s_add_u32 s84, s38, s48
	s_addc_u32 s83, s39, s49
	s_add_u32 s50, s56, 0x180
	s_addc_u32 s51, s57, 0
	s_add_u32 s52, s84, 0x180
	s_addc_u32 s53, s83, 0
	s_cmpk_eq_i32 s48, 0x700
	s_cselect_b32 s50, s36, s50
	s_cselect_b32 s51, s37, s51
	s_cselect_b32 s52, s46, s52
	s_cselect_b32 s53, s47, s53
	v_add_u32_e32 v164, s72, v171
	v_add_u32_e32 v168, s73, v171
	ds_read_b128 v[132:135], v164
	ds_read_b128 v[136:139], v164 offset:1024
	ds_read_b128 v[140:143], v164 offset:2048
	ds_read_b128 v[164:167], v164 offset:3072
	ds_read_b128 v[174:177], v168
	ds_read_b128 v[178:181], v168 offset:1024
	ds_read_b128 v[182:185], v168 offset:2048
	ds_read_b128 v[186:189], v168 offset:3072
	s_add_u32 s10, s56, 0x100
	s_addc_u32 s85, s57, 0
	s_and_b64 s[56:57], exec, s[54:55]
	s_cselect_b32 s57, s23, s85
	s_cselect_b32 s56, s80, s10
	s_add_u32 s10, s84, 0x100
	s_addc_u32 s83, s83, 0
	s_and_b64 s[54:55], exec, s[54:55]
	s_cselect_b32 s55, s21, s83
	s_cselect_b32 s54, s81, s10
	v_lshl_add_u64 v[168:169], v[128:129], 0, s[48:49]
	s_add_i32 m0, s59, 0xc000
	ds_read_b128 v[190:193], v172
	ds_read_b128 v[194:197], v172 offset:1024
	ds_read_b128 v[198:201], v172 offset:2048
	ds_read_b128 v[202:205], v172 offset:3072
	ds_read_b128 v[206:209], v172 offset:4096
	ds_read_b128 v[210:213], v172 offset:5120
	ds_read_b128 v[214:217], v172 offset:6144
	global_load_lds_dwordx4 v[168:169], off
	v_lshl_add_u64 v[168:169], v[130:131], 0, s[48:49]
	s_add_i32 m0, s59, 0xe000
	ds_read_b128 v[218:221], v172 offset:7168
	global_load_lds_dwordx4 v[168:169], off
	s_waitcnt vmcnt(8)
	s_waitcnt lgkmcnt(0)
	s_setprio 1
	s_barrier
	v_mfma_f32_16x16x32_bf16 v[124:127], v[132:135], v[190:193], 0
	v_mfma_f32_16x16x32_bf16 v[120:123], v[140:143], v[190:193], 0
	v_mfma_f32_16x16x32_bf16 v[108:111], v[132:135], v[198:201], 0
	v_mfma_f32_16x16x32_bf16 v[104:107], v[140:143], v[198:201], 0
	v_mfma_f32_16x16x32_bf16 v[92:95], v[132:135], v[206:209], 0
	v_mfma_f32_16x16x32_bf16 v[88:91], v[140:143], v[206:209], 0
	v_mfma_f32_16x16x32_bf16 v[76:79], v[132:135], v[214:217], 0
	v_mfma_f32_16x16x32_bf16 v[72:75], v[140:143], v[214:217], 0
	v_mfma_f32_16x16x32_bf16 v[124:127], v[136:139], v[194:197], v[124:127]
	v_mfma_f32_16x16x32_bf16 v[120:123], v[164:167], v[194:197], v[120:123]
	v_mfma_f32_16x16x32_bf16 v[108:111], v[136:139], v[202:205], v[108:111]
	v_mfma_f32_16x16x32_bf16 v[104:107], v[164:167], v[202:205], v[104:107]
	v_mfma_f32_16x16x32_bf16 v[92:95], v[136:139], v[210:213], v[92:95]
	v_mfma_f32_16x16x32_bf16 v[88:91], v[164:167], v[210:213], v[88:91]
	v_mfma_f32_16x16x32_bf16 v[76:79], v[136:139], v[218:221], v[76:79]
	v_mfma_f32_16x16x32_bf16 v[72:75], v[164:167], v[218:221], v[72:75]
	s_setprio 0
	s_setprio 1
	v_mfma_f32_16x16x32_bf16 v[116:119], v[174:177], v[190:193], 0
	v_mfma_f32_16x16x32_bf16 v[112:115], v[182:185], v[190:193], 0
	v_mfma_f32_16x16x32_bf16 v[100:103], v[174:177], v[198:201], 0
	v_mfma_f32_16x16x32_bf16 v[96:99], v[182:185], v[198:201], 0
	v_mfma_f32_16x16x32_bf16 v[84:87], v[174:177], v[206:209], 0
	v_mfma_f32_16x16x32_bf16 v[80:83], v[182:185], v[206:209], 0
	v_mfma_f32_16x16x32_bf16 v[68:71], v[174:177], v[214:217], 0
	v_mfma_f32_16x16x32_bf16 v[64:67], v[182:185], v[214:217], 0
	v_mfma_f32_16x16x32_bf16 v[116:119], v[178:181], v[194:197], v[116:119]
	v_mfma_f32_16x16x32_bf16 v[112:115], v[186:189], v[194:197], v[112:115]
	v_mfma_f32_16x16x32_bf16 v[100:103], v[178:181], v[202:205], v[100:103]
	v_mfma_f32_16x16x32_bf16 v[96:99], v[186:189], v[202:205], v[96:99]
	v_mfma_f32_16x16x32_bf16 v[84:87], v[178:181], v[210:213], v[84:87]
	v_mfma_f32_16x16x32_bf16 v[80:83], v[186:189], v[210:213], v[80:83]
	v_mfma_f32_16x16x32_bf16 v[68:71], v[178:181], v[218:221], v[68:71]
	v_mfma_f32_16x16x32_bf16 v[64:67], v[186:189], v[218:221], v[64:67]
	s_barrier
	s_setprio 0
	s_add_i32 s10, s72, s58
	s_mov_b32 m0, s10
	ds_read_b128 v[190:193], v172 offset:16384
	ds_read_b128 v[194:197], v172 offset:17408
	ds_read_b128 v[198:201], v172 offset:18432
	global_load_lds_dwordx4 v146, s[54:55]
	s_add_i32 m0, s10, 0x2000
	ds_read_b128 v[202:205], v172 offset:19456
	global_load_lds_dwordx4 v150, s[54:55]
	s_add_u32 s54, s54, 0x40000
	s_addc_u32 s55, s55, 0
	s_add_i32 s10, s73, s58
	s_mov_b32 m0, s10
	ds_read_b128 v[206:209], v172 offset:20480
	global_load_lds_dwordx4 v146, s[54:55]
	s_add_i32 m0, s10, 0x2000
	ds_read_b128 v[210:213], v172 offset:21504
	global_load_lds_dwordx4 v150, s[54:55]
	s_mov_b32 m0, s59
	ds_read_b128 v[214:217], v172 offset:22528
	global_load_lds_dwordx4 v144, s[56:57]
	s_mov_b32 m0, s60
	ds_read_b128 v[218:221], v172 offset:23552
	global_load_lds_dwordx4 v148, s[56:57]
	s_waitcnt vmcnt(8)
	s_waitcnt lgkmcnt(0)
	s_setprio 1
	s_barrier
	v_mfma_f32_16x16x32_bf16 v[60:63], v[132:135], v[190:193], 0
	v_mfma_f32_16x16x32_bf16 v[56:59], v[140:143], v[190:193], 0
	v_mfma_f32_16x16x32_bf16 v[44:47], v[132:135], v[198:201], 0
	v_mfma_f32_16x16x32_bf16 v[40:43], v[140:143], v[198:201], 0
	v_mfma_f32_16x16x32_bf16 v[28:31], v[132:135], v[206:209], 0
	v_mfma_f32_16x16x32_bf16 v[24:27], v[140:143], v[206:209], 0
	v_mfma_f32_16x16x32_bf16 v[12:15], v[132:135], v[214:217], 0
	v_mfma_f32_16x16x32_bf16 v[8:11], v[140:143], v[214:217], 0
	v_mfma_f32_16x16x32_bf16 v[60:63], v[136:139], v[194:197], v[60:63]
	v_mfma_f32_16x16x32_bf16 v[56:59], v[164:167], v[194:197], v[56:59]
	v_mfma_f32_16x16x32_bf16 v[44:47], v[136:139], v[202:205], v[44:47]
	v_mfma_f32_16x16x32_bf16 v[40:43], v[164:167], v[202:205], v[40:43]
	v_mfma_f32_16x16x32_bf16 v[28:31], v[136:139], v[210:213], v[28:31]
	v_mfma_f32_16x16x32_bf16 v[24:27], v[164:167], v[210:213], v[24:27]
	v_mfma_f32_16x16x32_bf16 v[12:15], v[136:139], v[218:221], v[12:15]
	v_mfma_f32_16x16x32_bf16 v[8:11], v[164:167], v[218:221], v[8:11]
	s_setprio 0
	s_setprio 1
	v_mfma_f32_16x16x32_bf16 v[52:55], v[174:177], v[190:193], 0
	v_mfma_f32_16x16x32_bf16 v[48:51], v[182:185], v[190:193], 0
	v_mfma_f32_16x16x32_bf16 v[36:39], v[174:177], v[198:201], 0
	v_mfma_f32_16x16x32_bf16 v[32:35], v[182:185], v[198:201], 0
	v_mfma_f32_16x16x32_bf16 v[20:23], v[174:177], v[206:209], 0
	v_mfma_f32_16x16x32_bf16 v[16:19], v[182:185], v[206:209], 0
	v_mfma_f32_16x16x32_bf16 v[4:7], v[174:177], v[214:217], 0
	v_mfma_f32_16x16x32_bf16 v[0:3], v[182:185], v[214:217], 0
	v_mfma_f32_16x16x32_bf16 v[52:55], v[178:181], v[194:197], v[52:55]
	v_mfma_f32_16x16x32_bf16 v[48:51], v[186:189], v[194:197], v[48:51]
	v_mfma_f32_16x16x32_bf16 v[36:39], v[178:181], v[202:205], v[36:39]
	v_mfma_f32_16x16x32_bf16 v[32:35], v[186:189], v[202:205], v[32:35]
	v_mfma_f32_16x16x32_bf16 v[20:23], v[178:181], v[210:213], v[20:23]
	v_mfma_f32_16x16x32_bf16 v[16:19], v[186:189], v[210:213], v[16:19]
	v_mfma_f32_16x16x32_bf16 v[4:7], v[178:181], v[218:221], v[4:7]
	v_mfma_f32_16x16x32_bf16 v[0:3], v[186:189], v[218:221], v[0:3]
	s_barrier
	s_setprio 0
	s_add_i32 s10, 0, 0x18000
	s_add_i32 s83, 0, 0x1c000
	v_add_u32_e32 v164, s10, v171
	v_add_u32_e32 v168, s83, v171
	ds_read_b128 v[132:135], v164
	ds_read_b128 v[136:139], v164 offset:1024
	ds_read_b128 v[140:143], v164 offset:2048
	ds_read_b128 v[164:167], v164 offset:3072
	ds_read_b128 v[174:177], v168
	ds_read_b128 v[178:181], v168 offset:1024
	ds_read_b128 v[182:185], v168 offset:2048
	ds_read_b128 v[186:189], v168 offset:3072
	s_add_u32 s54, s56, 0x40000
	s_addc_u32 s55, s57, 0
	s_mov_b32 m0, s61
	ds_read_b128 v[190:193], v172 offset:32768
	ds_read_b128 v[194:197], v172 offset:33792
	ds_read_b128 v[198:201], v172 offset:34816
	ds_read_b128 v[202:205], v172 offset:35840
	ds_read_b128 v[206:209], v172 offset:36864
	ds_read_b128 v[210:213], v172 offset:37888
	ds_read_b128 v[214:217], v172 offset:38912
	global_load_lds_dwordx4 v144, s[54:55]
	s_mov_b32 m0, s62
	ds_read_b128 v[218:221], v172 offset:39936
	global_load_lds_dwordx4 v148, s[54:55]
	s_waitcnt vmcnt(8)
	s_waitcnt lgkmcnt(0)
	s_setprio 1
	s_barrier
	v_mfma_f32_16x16x32_bf16 v[124:127], v[132:135], v[190:193], v[124:127]
	v_mfma_f32_16x16x32_bf16 v[120:123], v[140:143], v[190:193], v[120:123]
	v_mfma_f32_16x16x32_bf16 v[108:111], v[132:135], v[198:201], v[108:111]
	v_mfma_f32_16x16x32_bf16 v[104:107], v[140:143], v[198:201], v[104:107]
	v_mfma_f32_16x16x32_bf16 v[92:95], v[132:135], v[206:209], v[92:95]
	v_mfma_f32_16x16x32_bf16 v[88:91], v[140:143], v[206:209], v[88:91]
	v_mfma_f32_16x16x32_bf16 v[76:79], v[132:135], v[214:217], v[76:79]
	v_mfma_f32_16x16x32_bf16 v[72:75], v[140:143], v[214:217], v[72:75]
	v_mfma_f32_16x16x32_bf16 v[124:127], v[136:139], v[194:197], v[124:127]
	v_mfma_f32_16x16x32_bf16 v[120:123], v[164:167], v[194:197], v[120:123]
	v_mfma_f32_16x16x32_bf16 v[108:111], v[136:139], v[202:205], v[108:111]
	v_mfma_f32_16x16x32_bf16 v[104:107], v[164:167], v[202:205], v[104:107]
	v_mfma_f32_16x16x32_bf16 v[92:95], v[136:139], v[210:213], v[92:95]
	v_mfma_f32_16x16x32_bf16 v[88:91], v[164:167], v[210:213], v[88:91]
	v_mfma_f32_16x16x32_bf16 v[76:79], v[136:139], v[218:221], v[76:79]
	v_mfma_f32_16x16x32_bf16 v[72:75], v[164:167], v[218:221], v[72:75]
	s_setprio 0
	s_setprio 1
	v_mfma_f32_16x16x32_bf16 v[116:119], v[174:177], v[190:193], v[116:119]
	v_mfma_f32_16x16x32_bf16 v[112:115], v[182:185], v[190:193], v[112:115]
	v_mfma_f32_16x16x32_bf16 v[100:103], v[174:177], v[198:201], v[100:103]
	v_mfma_f32_16x16x32_bf16 v[96:99], v[182:185], v[198:201], v[96:99]
	v_mfma_f32_16x16x32_bf16 v[84:87], v[174:177], v[206:209], v[84:87]
	v_mfma_f32_16x16x32_bf16 v[80:83], v[182:185], v[206:209], v[80:83]
	v_mfma_f32_16x16x32_bf16 v[68:71], v[174:177], v[214:217], v[68:71]
	v_mfma_f32_16x16x32_bf16 v[64:67], v[182:185], v[214:217], v[64:67]
	v_mfma_f32_16x16x32_bf16 v[116:119], v[178:181], v[194:197], v[116:119]
	v_mfma_f32_16x16x32_bf16 v[112:115], v[186:189], v[194:197], v[112:115]
	v_mfma_f32_16x16x32_bf16 v[100:103], v[178:181], v[202:205], v[100:103]
	v_mfma_f32_16x16x32_bf16 v[96:99], v[186:189], v[202:205], v[96:99]
	v_mfma_f32_16x16x32_bf16 v[84:87], v[178:181], v[210:213], v[84:87]
	v_mfma_f32_16x16x32_bf16 v[80:83], v[186:189], v[210:213], v[80:83]
	v_mfma_f32_16x16x32_bf16 v[68:71], v[178:181], v[218:221], v[68:71]
	v_mfma_f32_16x16x32_bf16 v[64:67], v[186:189], v[218:221], v[64:67]
	s_barrier
	s_setprio 0
	s_add_i32 s10, s10, s58
	s_mov_b32 m0, s10
	ds_read_b128 v[190:193], v172 offset:49152
	ds_read_b128 v[194:197], v172 offset:50176
	ds_read_b128 v[198:201], v172 offset:51200
	global_load_lds_dwordx4 v146, s[52:53]
	s_add_i32 m0, s10, 0x2000
	ds_read_b128 v[202:205], v172 offset:52224
	global_load_lds_dwordx4 v150, s[52:53]
	s_add_u32 s52, s52, 0x40000
	s_addc_u32 s53, s53, 0
	s_add_i32 s10, s83, s58
	s_mov_b32 m0, s10
	ds_read_b128 v[206:209], v172 offset:53248
	global_load_lds_dwordx4 v146, s[52:53]
	s_add_i32 m0, s10, 0x2000
	ds_read_b128 v[210:213], v172 offset:54272
	global_load_lds_dwordx4 v150, s[52:53]
	s_mov_b32 m0, s68
	ds_read_b128 v[214:217], v172 offset:55296
	global_load_lds_dwordx4 v144, s[50:51]
	s_mov_b32 m0, s69
	ds_read_b128 v[218:221], v172 offset:56320
	global_load_lds_dwordx4 v148, s[50:51]
	s_waitcnt vmcnt(8)
	s_waitcnt lgkmcnt(0)
	s_setprio 1
	s_barrier
	v_mfma_f32_16x16x32_bf16 v[60:63], v[132:135], v[190:193], v[60:63]
	v_mfma_f32_16x16x32_bf16 v[56:59], v[140:143], v[190:193], v[56:59]
	v_mfma_f32_16x16x32_bf16 v[44:47], v[132:135], v[198:201], v[44:47]
	v_mfma_f32_16x16x32_bf16 v[40:43], v[140:143], v[198:201], v[40:43]
	v_mfma_f32_16x16x32_bf16 v[28:31], v[132:135], v[206:209], v[28:31]
	v_mfma_f32_16x16x32_bf16 v[24:27], v[140:143], v[206:209], v[24:27]
	v_mfma_f32_16x16x32_bf16 v[12:15], v[132:135], v[214:217], v[12:15]
	v_mfma_f32_16x16x32_bf16 v[8:11], v[140:143], v[214:217], v[8:11]
	v_mfma_f32_16x16x32_bf16 v[60:63], v[136:139], v[194:197], v[60:63]
	v_mfma_f32_16x16x32_bf16 v[56:59], v[164:167], v[194:197], v[56:59]
	v_mfma_f32_16x16x32_bf16 v[44:47], v[136:139], v[202:205], v[44:47]
	v_mfma_f32_16x16x32_bf16 v[40:43], v[164:167], v[202:205], v[40:43]
	v_mfma_f32_16x16x32_bf16 v[28:31], v[136:139], v[210:213], v[28:31]
	v_mfma_f32_16x16x32_bf16 v[24:27], v[164:167], v[210:213], v[24:27]
	v_mfma_f32_16x16x32_bf16 v[12:15], v[136:139], v[218:221], v[12:15]
	v_mfma_f32_16x16x32_bf16 v[8:11], v[164:167], v[218:221], v[8:11]
	s_setprio 0
	s_setprio 1
	v_mfma_f32_16x16x32_bf16 v[52:55], v[174:177], v[190:193], v[52:55]
	v_mfma_f32_16x16x32_bf16 v[48:51], v[182:185], v[190:193], v[48:51]
	v_mfma_f32_16x16x32_bf16 v[36:39], v[174:177], v[198:201], v[36:39]
	v_mfma_f32_16x16x32_bf16 v[32:35], v[182:185], v[198:201], v[32:35]
	v_mfma_f32_16x16x32_bf16 v[20:23], v[174:177], v[206:209], v[20:23]
	v_mfma_f32_16x16x32_bf16 v[16:19], v[182:185], v[206:209], v[16:19]
	v_mfma_f32_16x16x32_bf16 v[4:7], v[174:177], v[214:217], v[4:7]
	v_mfma_f32_16x16x32_bf16 v[0:3], v[182:185], v[214:217], v[0:3]
	v_mfma_f32_16x16x32_bf16 v[52:55], v[178:181], v[194:197], v[52:55]
	v_mfma_f32_16x16x32_bf16 v[48:51], v[186:189], v[194:197], v[48:51]
	v_mfma_f32_16x16x32_bf16 v[36:39], v[178:181], v[202:205], v[36:39]
	v_mfma_f32_16x16x32_bf16 v[32:35], v[186:189], v[202:205], v[32:35]
	v_mfma_f32_16x16x32_bf16 v[20:23], v[178:181], v[210:213], v[20:23]
	v_mfma_f32_16x16x32_bf16 v[16:19], v[186:189], v[210:213], v[16:19]
	v_mfma_f32_16x16x32_bf16 v[4:7], v[178:181], v[218:221], v[4:7]
	v_mfma_f32_16x16x32_bf16 v[0:3], v[186:189], v[218:221], v[0:3]
	s_barrier
	s_setprio 0
	s_add_i32 s10, s82, 2
	s_add_u32 s48, s48, 0x100
	s_addc_u32 s49, s49, 0
	s_cmp_gt_u32 s82, 13
	s_mov_b32 s82, s10
	s_cbranch_scc1 .LBB0_721
	s_branch .LBB0_715
.LBB0_714:
	v_add_u32_e32 v164, s72, v171
	v_add_u32_e32 v168, s73, v171
	ds_read_b128 v[132:135], v164
	ds_read_b128 v[136:139], v164 offset:1024
	ds_read_b128 v[140:143], v164 offset:2048
	ds_read_b128 v[164:167], v164 offset:3072
	ds_read_b128 v[174:177], v168
	ds_read_b128 v[178:181], v168 offset:1024
	ds_read_b128 v[182:185], v168 offset:2048
	ds_read_b128 v[186:189], v168 offset:3072
	s_add_u32 s10, s56, 0x100
	s_addc_u32 s85, s57, 0
	s_and_b64 s[56:57], exec, s[54:55]
	s_cselect_b32 s57, s23, s85
	s_cselect_b32 s56, s80, s10
	s_add_u32 s10, s84, 0x100
	s_addc_u32 s83, s83, 0
	s_and_b64 s[54:55], exec, s[54:55]
	s_cselect_b32 s55, s21, s83
	s_cselect_b32 s54, s81, s10
	v_lshl_add_u64 v[168:169], v[128:129], 0, s[48:49]
	s_add_i32 m0, s59, 0xc000
	ds_read_b128 v[190:193], v172
	ds_read_b128 v[194:197], v172 offset:1024
	ds_read_b128 v[198:201], v172 offset:2048
	ds_read_b128 v[202:205], v172 offset:3072
	ds_read_b128 v[206:209], v172 offset:4096
	ds_read_b128 v[210:213], v172 offset:5120
	ds_read_b128 v[214:217], v172 offset:6144
	global_load_lds_dwordx4 v[168:169], off
	v_lshl_add_u64 v[168:169], v[130:131], 0, s[48:49]
	s_add_i32 m0, s59, 0xe000
	ds_read_b128 v[218:221], v172 offset:7168
	global_load_lds_dwordx4 v[168:169], off
	s_waitcnt vmcnt(8)
	s_waitcnt lgkmcnt(0)
	s_setprio 1
	s_barrier
	v_mfma_f32_16x16x32_bf16 v[124:127], v[132:135], v[190:193], v[124:127]
	v_mfma_f32_16x16x32_bf16 v[120:123], v[140:143], v[190:193], v[120:123]
	v_mfma_f32_16x16x32_bf16 v[108:111], v[132:135], v[198:201], v[108:111]
	v_mfma_f32_16x16x32_bf16 v[104:107], v[140:143], v[198:201], v[104:107]
	v_mfma_f32_16x16x32_bf16 v[92:95], v[132:135], v[206:209], v[92:95]
	v_mfma_f32_16x16x32_bf16 v[88:91], v[140:143], v[206:209], v[88:91]
	v_mfma_f32_16x16x32_bf16 v[76:79], v[132:135], v[214:217], v[76:79]
	v_mfma_f32_16x16x32_bf16 v[72:75], v[140:143], v[214:217], v[72:75]
	v_mfma_f32_16x16x32_bf16 v[124:127], v[136:139], v[194:197], v[124:127]
	v_mfma_f32_16x16x32_bf16 v[120:123], v[164:167], v[194:197], v[120:123]
	v_mfma_f32_16x16x32_bf16 v[108:111], v[136:139], v[202:205], v[108:111]
	v_mfma_f32_16x16x32_bf16 v[104:107], v[164:167], v[202:205], v[104:107]
	v_mfma_f32_16x16x32_bf16 v[92:95], v[136:139], v[210:213], v[92:95]
	v_mfma_f32_16x16x32_bf16 v[88:91], v[164:167], v[210:213], v[88:91]
	v_mfma_f32_16x16x32_bf16 v[76:79], v[136:139], v[218:221], v[76:79]
	v_mfma_f32_16x16x32_bf16 v[72:75], v[164:167], v[218:221], v[72:75]
	s_setprio 0
	s_setprio 1
	v_mfma_f32_16x16x32_bf16 v[116:119], v[174:177], v[190:193], v[116:119]
	v_mfma_f32_16x16x32_bf16 v[112:115], v[182:185], v[190:193], v[112:115]
	v_mfma_f32_16x16x32_bf16 v[100:103], v[174:177], v[198:201], v[100:103]
	v_mfma_f32_16x16x32_bf16 v[96:99], v[182:185], v[198:201], v[96:99]
	v_mfma_f32_16x16x32_bf16 v[84:87], v[174:177], v[206:209], v[84:87]
	v_mfma_f32_16x16x32_bf16 v[80:83], v[182:185], v[206:209], v[80:83]
	v_mfma_f32_16x16x32_bf16 v[68:71], v[174:177], v[214:217], v[68:71]
	v_mfma_f32_16x16x32_bf16 v[64:67], v[182:185], v[214:217], v[64:67]
	v_mfma_f32_16x16x32_bf16 v[116:119], v[178:181], v[194:197], v[116:119]
	v_mfma_f32_16x16x32_bf16 v[112:115], v[186:189], v[194:197], v[112:115]
	v_mfma_f32_16x16x32_bf16 v[100:103], v[178:181], v[202:205], v[100:103]
	v_mfma_f32_16x16x32_bf16 v[96:99], v[186:189], v[202:205], v[96:99]
	v_mfma_f32_16x16x32_bf16 v[84:87], v[178:181], v[210:213], v[84:87]
	v_mfma_f32_16x16x32_bf16 v[80:83], v[186:189], v[210:213], v[80:83]
	v_mfma_f32_16x16x32_bf16 v[68:71], v[178:181], v[218:221], v[68:71]
	v_mfma_f32_16x16x32_bf16 v[64:67], v[186:189], v[218:221], v[64:67]
	s_barrier
	s_setprio 0
	s_add_i32 s10, s72, s58
	s_mov_b32 m0, s10
	ds_read_b128 v[190:193], v172 offset:16384
	ds_read_b128 v[194:197], v172 offset:17408
	ds_read_b128 v[198:201], v172 offset:18432
	global_load_lds_dwordx4 v146, s[54:55]
	s_add_i32 m0, s10, 0x2000
	ds_read_b128 v[202:205], v172 offset:19456
	global_load_lds_dwordx4 v150, s[54:55]
	s_add_u32 s54, s54, 0x40000
	s_addc_u32 s55, s55, 0
	s_add_i32 s10, s73, s58
	s_mov_b32 m0, s10
	ds_read_b128 v[206:209], v172 offset:20480
	global_load_lds_dwordx4 v146, s[54:55]
	s_add_i32 m0, s10, 0x2000
	ds_read_b128 v[210:213], v172 offset:21504
	global_load_lds_dwordx4 v150, s[54:55]
	s_mov_b32 m0, s59
	ds_read_b128 v[214:217], v172 offset:22528
	global_load_lds_dwordx4 v144, s[56:57]
	s_mov_b32 m0, s60
	ds_read_b128 v[218:221], v172 offset:23552
	global_load_lds_dwordx4 v148, s[56:57]
	s_waitcnt vmcnt(8)
	s_waitcnt lgkmcnt(0)
	s_setprio 1
	s_barrier
	v_mfma_f32_16x16x32_bf16 v[60:63], v[132:135], v[190:193], v[60:63]
	v_mfma_f32_16x16x32_bf16 v[56:59], v[140:143], v[190:193], v[56:59]
	v_mfma_f32_16x16x32_bf16 v[44:47], v[132:135], v[198:201], v[44:47]
	v_mfma_f32_16x16x32_bf16 v[40:43], v[140:143], v[198:201], v[40:43]
	v_mfma_f32_16x16x32_bf16 v[28:31], v[132:135], v[206:209], v[28:31]
	v_mfma_f32_16x16x32_bf16 v[24:27], v[140:143], v[206:209], v[24:27]
	v_mfma_f32_16x16x32_bf16 v[12:15], v[132:135], v[214:217], v[12:15]
	v_mfma_f32_16x16x32_bf16 v[8:11], v[140:143], v[214:217], v[8:11]
	v_mfma_f32_16x16x32_bf16 v[60:63], v[136:139], v[194:197], v[60:63]
	v_mfma_f32_16x16x32_bf16 v[56:59], v[164:167], v[194:197], v[56:59]
	v_mfma_f32_16x16x32_bf16 v[44:47], v[136:139], v[202:205], v[44:47]
	v_mfma_f32_16x16x32_bf16 v[40:43], v[164:167], v[202:205], v[40:43]
	v_mfma_f32_16x16x32_bf16 v[28:31], v[136:139], v[210:213], v[28:31]
	v_mfma_f32_16x16x32_bf16 v[24:27], v[164:167], v[210:213], v[24:27]
	v_mfma_f32_16x16x32_bf16 v[12:15], v[136:139], v[218:221], v[12:15]
	v_mfma_f32_16x16x32_bf16 v[8:11], v[164:167], v[218:221], v[8:11]
	s_setprio 0
	s_setprio 1
	v_mfma_f32_16x16x32_bf16 v[52:55], v[174:177], v[190:193], v[52:55]
	v_mfma_f32_16x16x32_bf16 v[48:51], v[182:185], v[190:193], v[48:51]
	v_mfma_f32_16x16x32_bf16 v[36:39], v[174:177], v[198:201], v[36:39]
	v_mfma_f32_16x16x32_bf16 v[32:35], v[182:185], v[198:201], v[32:35]
	v_mfma_f32_16x16x32_bf16 v[20:23], v[174:177], v[206:209], v[20:23]
	v_mfma_f32_16x16x32_bf16 v[16:19], v[182:185], v[206:209], v[16:19]
	v_mfma_f32_16x16x32_bf16 v[4:7], v[174:177], v[214:217], v[4:7]
	v_mfma_f32_16x16x32_bf16 v[0:3], v[182:185], v[214:217], v[0:3]
	v_mfma_f32_16x16x32_bf16 v[52:55], v[178:181], v[194:197], v[52:55]
	v_mfma_f32_16x16x32_bf16 v[48:51], v[186:189], v[194:197], v[48:51]
	v_mfma_f32_16x16x32_bf16 v[36:39], v[178:181], v[202:205], v[36:39]
	v_mfma_f32_16x16x32_bf16 v[32:35], v[186:189], v[202:205], v[32:35]
	v_mfma_f32_16x16x32_bf16 v[20:23], v[178:181], v[210:213], v[20:23]
	v_mfma_f32_16x16x32_bf16 v[16:19], v[186:189], v[210:213], v[16:19]
	v_mfma_f32_16x16x32_bf16 v[4:7], v[178:181], v[218:221], v[4:7]
	v_mfma_f32_16x16x32_bf16 v[0:3], v[186:189], v[218:221], v[0:3]
	s_barrier
	s_setprio 0
	s_add_i32 s10, 0, 0x18000
	s_add_i32 s83, 0, 0x1c000
	v_add_u32_e32 v164, s10, v171
	v_add_u32_e32 v168, s83, v171
	ds_read_b128 v[132:135], v164
	ds_read_b128 v[136:139], v164 offset:1024
	ds_read_b128 v[140:143], v164 offset:2048
	ds_read_b128 v[164:167], v164 offset:3072
	ds_read_b128 v[174:177], v168
	ds_read_b128 v[178:181], v168 offset:1024
	ds_read_b128 v[182:185], v168 offset:2048
	ds_read_b128 v[186:189], v168 offset:3072
	s_add_u32 s54, s56, 0x40000
	s_addc_u32 s55, s57, 0
	s_mov_b32 m0, s61
	ds_read_b128 v[190:193], v172 offset:32768
	ds_read_b128 v[194:197], v172 offset:33792
	ds_read_b128 v[198:201], v172 offset:34816
	ds_read_b128 v[202:205], v172 offset:35840
	ds_read_b128 v[206:209], v172 offset:36864
	ds_read_b128 v[210:213], v172 offset:37888
	ds_read_b128 v[214:217], v172 offset:38912
	global_load_lds_dwordx4 v144, s[54:55]
	s_mov_b32 m0, s62
	ds_read_b128 v[218:221], v172 offset:39936
	global_load_lds_dwordx4 v148, s[54:55]
	s_waitcnt vmcnt(8)
	s_waitcnt lgkmcnt(0)
	s_setprio 1
	s_barrier
	v_mfma_f32_16x16x32_bf16 v[124:127], v[132:135], v[190:193], v[124:127]
	v_mfma_f32_16x16x32_bf16 v[120:123], v[140:143], v[190:193], v[120:123]
	v_mfma_f32_16x16x32_bf16 v[108:111], v[132:135], v[198:201], v[108:111]
	v_mfma_f32_16x16x32_bf16 v[104:107], v[140:143], v[198:201], v[104:107]
	v_mfma_f32_16x16x32_bf16 v[92:95], v[132:135], v[206:209], v[92:95]
	v_mfma_f32_16x16x32_bf16 v[88:91], v[140:143], v[206:209], v[88:91]
	v_mfma_f32_16x16x32_bf16 v[76:79], v[132:135], v[214:217], v[76:79]
	v_mfma_f32_16x16x32_bf16 v[72:75], v[140:143], v[214:217], v[72:75]
	v_mfma_f32_16x16x32_bf16 v[124:127], v[136:139], v[194:197], v[124:127]
	v_mfma_f32_16x16x32_bf16 v[120:123], v[164:167], v[194:197], v[120:123]
	v_mfma_f32_16x16x32_bf16 v[108:111], v[136:139], v[202:205], v[108:111]
	v_mfma_f32_16x16x32_bf16 v[104:107], v[164:167], v[202:205], v[104:107]
	v_mfma_f32_16x16x32_bf16 v[92:95], v[136:139], v[210:213], v[92:95]
	v_mfma_f32_16x16x32_bf16 v[88:91], v[164:167], v[210:213], v[88:91]
	v_mfma_f32_16x16x32_bf16 v[76:79], v[136:139], v[218:221], v[76:79]
	v_mfma_f32_16x16x32_bf16 v[72:75], v[164:167], v[218:221], v[72:75]
	s_setprio 0
	s_setprio 1
	v_mfma_f32_16x16x32_bf16 v[116:119], v[174:177], v[190:193], v[116:119]
	v_mfma_f32_16x16x32_bf16 v[112:115], v[182:185], v[190:193], v[112:115]
	v_mfma_f32_16x16x32_bf16 v[100:103], v[174:177], v[198:201], v[100:103]
	v_mfma_f32_16x16x32_bf16 v[96:99], v[182:185], v[198:201], v[96:99]
	v_mfma_f32_16x16x32_bf16 v[84:87], v[174:177], v[206:209], v[84:87]
	v_mfma_f32_16x16x32_bf16 v[80:83], v[182:185], v[206:209], v[80:83]
	v_mfma_f32_16x16x32_bf16 v[68:71], v[174:177], v[214:217], v[68:71]
	v_mfma_f32_16x16x32_bf16 v[64:67], v[182:185], v[214:217], v[64:67]
	v_mfma_f32_16x16x32_bf16 v[116:119], v[178:181], v[194:197], v[116:119]
	v_mfma_f32_16x16x32_bf16 v[112:115], v[186:189], v[194:197], v[112:115]
	v_mfma_f32_16x16x32_bf16 v[100:103], v[178:181], v[202:205], v[100:103]
	v_mfma_f32_16x16x32_bf16 v[96:99], v[186:189], v[202:205], v[96:99]
	v_mfma_f32_16x16x32_bf16 v[84:87], v[178:181], v[210:213], v[84:87]
	v_mfma_f32_16x16x32_bf16 v[80:83], v[186:189], v[210:213], v[80:83]
	v_mfma_f32_16x16x32_bf16 v[68:71], v[178:181], v[218:221], v[68:71]
	v_mfma_f32_16x16x32_bf16 v[64:67], v[186:189], v[218:221], v[64:67]
	s_barrier
	s_setprio 0
	s_add_i32 s10, s10, s58
	s_mov_b32 m0, s10
	ds_read_b128 v[190:193], v172 offset:49152
	ds_read_b128 v[194:197], v172 offset:50176
	ds_read_b128 v[198:201], v172 offset:51200
	global_load_lds_dwordx4 v146, s[52:53]
	s_add_i32 m0, s10, 0x2000
	ds_read_b128 v[202:205], v172 offset:52224
	global_load_lds_dwordx4 v150, s[52:53]
	s_add_u32 s52, s52, 0x40000
	s_addc_u32 s53, s53, 0
	s_add_i32 s10, s83, s58
	s_mov_b32 m0, s10
	ds_read_b128 v[206:209], v172 offset:53248
	global_load_lds_dwordx4 v146, s[52:53]
	s_add_i32 m0, s10, 0x2000
	ds_read_b128 v[210:213], v172 offset:54272
	global_load_lds_dwordx4 v150, s[52:53]
	s_mov_b32 m0, s68
	ds_read_b128 v[214:217], v172 offset:55296
	global_load_lds_dwordx4 v144, s[50:51]
	s_mov_b32 m0, s69
	ds_read_b128 v[218:221], v172 offset:56320
	global_load_lds_dwordx4 v148, s[50:51]
	s_waitcnt vmcnt(8)
	s_waitcnt lgkmcnt(0)
	s_setprio 1
	s_barrier
	v_mfma_f32_16x16x32_bf16 v[60:63], v[132:135], v[190:193], v[60:63]
	v_mfma_f32_16x16x32_bf16 v[56:59], v[140:143], v[190:193], v[56:59]
	v_mfma_f32_16x16x32_bf16 v[44:47], v[132:135], v[198:201], v[44:47]
	v_mfma_f32_16x16x32_bf16 v[40:43], v[140:143], v[198:201], v[40:43]
	v_mfma_f32_16x16x32_bf16 v[28:31], v[132:135], v[206:209], v[28:31]
	v_mfma_f32_16x16x32_bf16 v[24:27], v[140:143], v[206:209], v[24:27]
	v_mfma_f32_16x16x32_bf16 v[12:15], v[132:135], v[214:217], v[12:15]
	v_mfma_f32_16x16x32_bf16 v[8:11], v[140:143], v[214:217], v[8:11]
	v_mfma_f32_16x16x32_bf16 v[60:63], v[136:139], v[194:197], v[60:63]
	v_mfma_f32_16x16x32_bf16 v[56:59], v[164:167], v[194:197], v[56:59]
	v_mfma_f32_16x16x32_bf16 v[44:47], v[136:139], v[202:205], v[44:47]
	v_mfma_f32_16x16x32_bf16 v[40:43], v[164:167], v[202:205], v[40:43]
	v_mfma_f32_16x16x32_bf16 v[28:31], v[136:139], v[210:213], v[28:31]
	v_mfma_f32_16x16x32_bf16 v[24:27], v[164:167], v[210:213], v[24:27]
	v_mfma_f32_16x16x32_bf16 v[12:15], v[136:139], v[218:221], v[12:15]
	v_mfma_f32_16x16x32_bf16 v[8:11], v[164:167], v[218:221], v[8:11]
	s_setprio 0
	s_setprio 1
	v_mfma_f32_16x16x32_bf16 v[52:55], v[174:177], v[190:193], v[52:55]
	v_mfma_f32_16x16x32_bf16 v[48:51], v[182:185], v[190:193], v[48:51]
	v_mfma_f32_16x16x32_bf16 v[36:39], v[174:177], v[198:201], v[36:39]
	v_mfma_f32_16x16x32_bf16 v[32:35], v[182:185], v[198:201], v[32:35]
	v_mfma_f32_16x16x32_bf16 v[20:23], v[174:177], v[206:209], v[20:23]
	v_mfma_f32_16x16x32_bf16 v[16:19], v[182:185], v[206:209], v[16:19]
	v_mfma_f32_16x16x32_bf16 v[4:7], v[174:177], v[214:217], v[4:7]
	v_mfma_f32_16x16x32_bf16 v[0:3], v[182:185], v[214:217], v[0:3]
	v_mfma_f32_16x16x32_bf16 v[52:55], v[178:181], v[194:197], v[52:55]
	v_mfma_f32_16x16x32_bf16 v[48:51], v[186:189], v[194:197], v[48:51]
	v_mfma_f32_16x16x32_bf16 v[36:39], v[178:181], v[202:205], v[36:39]
	v_mfma_f32_16x16x32_bf16 v[32:35], v[186:189], v[202:205], v[32:35]
	v_mfma_f32_16x16x32_bf16 v[20:23], v[178:181], v[210:213], v[20:23]
	v_mfma_f32_16x16x32_bf16 v[16:19], v[186:189], v[210:213], v[16:19]
	v_mfma_f32_16x16x32_bf16 v[4:7], v[178:181], v[218:221], v[4:7]
	v_mfma_f32_16x16x32_bf16 v[0:3], v[186:189], v[218:221], v[0:3]
	s_barrier
	s_setprio 0
	s_add_i32 s10, s82, 2
	s_add_u32 s48, s48, 0x100
	s_addc_u32 s49, s49, 0
	s_cmp_gt_u32 s82, 13
	s_mov_b32 s82, s10
	s_cbranch_scc1 .LBB0_721

.LBB0_805:
	s_add_u32 s27, s61, s4
	s_addc_u32 s72, s62, s5
	s_add_u32 s73, s63, s6
	s_addc_u32 s78, s64, s7
	s_ashr_i32 s21, s20, 31
	s_lshl_b64 s[4:5], s[20:21], 19
	s_add_u32 s22, s40, s4
	s_addc_u32 s23, s41, s5
	s_and_b64 s[6:7], s[0:1], exec
	s_cselect_b32 s21, s23, s31
	s_cselect_b32 s79, s22, s30
	s_ashr_i32 s19, s18, 31
	s_lshl_b64 s[6:7], s[18:19], 19
	s_add_u32 s24, s42, s6
	s_addc_u32 s25, s43, s7
	s_and_b64 s[36:37], s[0:1], exec
	s_cselect_b32 s19, s25, s29
	s_cselect_b32 s80, s24, s28
	s_add_u32 s36, s79, 0x80
	s_addc_u32 s37, s21, 0
	s_add_u32 s38, s80, 0x80
	s_addc_u32 s39, s19, 0
	v_lshl_add_u64 v[148:149], s[30:31], 0, v[140:141]
	v_lshl_add_u64 v[150:151], s[30:31], 0, v[142:143]
	s_mov_b32 s81, 0
	s_mov_b64 s[44:45], 0
	s_cmpk_eq_i32 s44, 0x700
	s_cselect_b64 s[50:51], -1, 0
	s_add_u32 s52, s30, s44
	s_addc_u32 s53, s31, s45
	s_add_u32 s83, s28, s44
	s_addc_u32 s82, s29, s45
	s_add_u32 s46, s52, 0x180
	s_addc_u32 s47, s53, 0
	s_add_u32 s48, s83, 0x180
	s_addc_u32 s49, s82, 0
	s_cmpk_eq_i32 s44, 0x700
	s_cselect_b32 s46, s36, s46
	s_cselect_b32 s47, s37, s47
	s_cselect_b32 s48, s38, s48
	s_cselect_b32 s49, s39, s49
	v_add_u32_e32 v152, s68, v157
	ds_read_b128 v[166:169], v152
	ds_read_b128 v[170:173], v152 offset:1024
	ds_read_b128 v[174:177], v152 offset:2048
	ds_read_b128 v[178:181], v152 offset:3072
	v_add_u32_e32 v152, s69, v157
	ds_read_b128 v[182:185], v152
	ds_read_b128 v[186:189], v152 offset:1024
	ds_read_b128 v[190:193], v152 offset:2048
	ds_read_b128 v[194:197], v152 offset:3072
	s_add_u32 s8, s52, 0x100
	s_addc_u32 s84, s53, 0
	s_and_b64 s[52:53], exec, s[50:51]
	s_cselect_b32 s53, s21, s84
	s_cselect_b32 s52, s79, s8
	s_add_u32 s8, s83, 0x100
	s_addc_u32 s82, s82, 0
	s_and_b64 s[50:51], exec, s[50:51]
	s_cselect_b32 s51, s19, s82
	s_cselect_b32 s50, s80, s8
	v_lshl_add_u64 v[154:155], v[148:149], 0, s[44:45]
	s_add_i32 m0, s57, 0xc000
	ds_read_b128 v[198:201], v161
	ds_read_b128 v[202:205], v161 offset:1024
	ds_read_b128 v[206:209], v161 offset:2048
	ds_read_b128 v[210:213], v161 offset:3072
	ds_read_b128 v[214:217], v161 offset:4096
	ds_read_b128 v[218:221], v161 offset:5120
	ds_read_b128 v[222:225], v161 offset:6144
	global_load_lds_dwordx4 v[154:155], off
	v_lshl_add_u64 v[154:155], v[150:151], 0, s[44:45]
	s_add_i32 m0, s57, 0xe000
	ds_read_b128 v[226:229], v161 offset:7168
	global_load_lds_dwordx4 v[154:155], off
	s_waitcnt vmcnt(8)
	s_waitcnt lgkmcnt(0)
	s_setprio 1
	s_barrier
	v_mfma_f32_16x16x32_bf16 v[124:127], v[166:169], v[198:201], 0
	v_mfma_f32_16x16x32_bf16 v[120:123], v[174:177], v[198:201], 0
	v_mfma_f32_16x16x32_bf16 v[108:111], v[166:169], v[206:209], 0
	v_mfma_f32_16x16x32_bf16 v[104:107], v[174:177], v[206:209], 0
	v_mfma_f32_16x16x32_bf16 v[92:95], v[166:169], v[214:217], 0
	v_mfma_f32_16x16x32_bf16 v[88:91], v[174:177], v[214:217], 0
	v_mfma_f32_16x16x32_bf16 v[76:79], v[166:169], v[222:225], 0
	v_mfma_f32_16x16x32_bf16 v[72:75], v[174:177], v[222:225], 0
	v_mfma_f32_16x16x32_bf16 v[124:127], v[170:173], v[202:205], v[124:127]
	v_mfma_f32_16x16x32_bf16 v[120:123], v[178:181], v[202:205], v[120:123]
	v_mfma_f32_16x16x32_bf16 v[108:111], v[170:173], v[210:213], v[108:111]
	v_mfma_f32_16x16x32_bf16 v[104:107], v[178:181], v[210:213], v[104:107]
	v_mfma_f32_16x16x32_bf16 v[92:95], v[170:173], v[218:221], v[92:95]
	v_mfma_f32_16x16x32_bf16 v[88:91], v[178:181], v[218:221], v[88:91]
	v_mfma_f32_16x16x32_bf16 v[76:79], v[170:173], v[226:229], v[76:79]
	v_mfma_f32_16x16x32_bf16 v[72:75], v[178:181], v[226:229], v[72:75]
	s_setprio 0
	s_setprio 1
	v_mfma_f32_16x16x32_bf16 v[116:119], v[182:185], v[198:201], 0
	v_mfma_f32_16x16x32_bf16 v[112:115], v[190:193], v[198:201], 0
	v_mfma_f32_16x16x32_bf16 v[100:103], v[182:185], v[206:209], 0
	v_mfma_f32_16x16x32_bf16 v[96:99], v[190:193], v[206:209], 0
	v_mfma_f32_16x16x32_bf16 v[84:87], v[182:185], v[214:217], 0
	v_mfma_f32_16x16x32_bf16 v[80:83], v[190:193], v[214:217], 0
	v_mfma_f32_16x16x32_bf16 v[68:71], v[182:185], v[222:225], 0
	v_mfma_f32_16x16x32_bf16 v[64:67], v[190:193], v[222:225], 0
	v_mfma_f32_16x16x32_bf16 v[116:119], v[186:189], v[202:205], v[116:119]
	v_mfma_f32_16x16x32_bf16 v[112:115], v[194:197], v[202:205], v[112:115]
	v_mfma_f32_16x16x32_bf16 v[100:103], v[186:189], v[210:213], v[100:103]
	v_mfma_f32_16x16x32_bf16 v[96:99], v[194:197], v[210:213], v[96:99]
	v_mfma_f32_16x16x32_bf16 v[84:87], v[186:189], v[218:221], v[84:87]
	v_mfma_f32_16x16x32_bf16 v[80:83], v[194:197], v[218:221], v[80:83]
	v_mfma_f32_16x16x32_bf16 v[68:71], v[186:189], v[226:229], v[68:71]
	v_mfma_f32_16x16x32_bf16 v[64:67], v[194:197], v[226:229], v[64:67]
	s_barrier
	s_setprio 0
	s_add_i32 s8, s68, s54
	s_mov_b32 m0, s8
	ds_read_b128 v[198:201], v161 offset:16384
	ds_read_b128 v[202:205], v161 offset:17408
	ds_read_b128 v[206:209], v161 offset:18432
	global_load_lds_dwordx4 v128, s[50:51]
	s_add_i32 m0, s8, 0x2000
	ds_read_b128 v[210:213], v161 offset:19456
	global_load_lds_dwordx4 v130, s[50:51]
	s_add_u32 s50, s50, 0x40000
	s_addc_u32 s51, s51, 0
	s_add_i32 s8, s69, s54
	s_mov_b32 m0, s8
	ds_read_b128 v[214:217], v161 offset:20480
	global_load_lds_dwordx4 v128, s[50:51]
	s_add_i32 m0, s8, 0x2000
	ds_read_b128 v[218:221], v161 offset:21504
	global_load_lds_dwordx4 v130, s[50:51]
	s_mov_b32 m0, s57
	ds_read_b128 v[222:225], v161 offset:22528
	global_load_lds_dwordx4 v134, s[52:53]
	s_mov_b32 m0, s58
	ds_read_b128 v[226:229], v161 offset:23552
	global_load_lds_dwordx4 v132, s[52:53]
	s_waitcnt vmcnt(8)
	s_waitcnt lgkmcnt(0)
	s_setprio 1
	s_barrier
	v_mfma_f32_16x16x32_bf16 v[60:63], v[166:169], v[198:201], 0
	v_mfma_f32_16x16x32_bf16 v[56:59], v[174:177], v[198:201], 0
	v_mfma_f32_16x16x32_bf16 v[44:47], v[166:169], v[206:209], 0
	v_mfma_f32_16x16x32_bf16 v[40:43], v[174:177], v[206:209], 0
	v_mfma_f32_16x16x32_bf16 v[28:31], v[166:169], v[214:217], 0
	v_mfma_f32_16x16x32_bf16 v[24:27], v[174:177], v[214:217], 0
	v_mfma_f32_16x16x32_bf16 v[12:15], v[166:169], v[222:225], 0
	v_mfma_f32_16x16x32_bf16 v[8:11], v[174:177], v[222:225], 0
	v_mfma_f32_16x16x32_bf16 v[60:63], v[170:173], v[202:205], v[60:63]
	v_mfma_f32_16x16x32_bf16 v[56:59], v[178:181], v[202:205], v[56:59]
	v_mfma_f32_16x16x32_bf16 v[44:47], v[170:173], v[210:213], v[44:47]
	v_mfma_f32_16x16x32_bf16 v[40:43], v[178:181], v[210:213], v[40:43]
	v_mfma_f32_16x16x32_bf16 v[28:31], v[170:173], v[218:221], v[28:31]
	v_mfma_f32_16x16x32_bf16 v[24:27], v[178:181], v[218:221], v[24:27]
	v_mfma_f32_16x16x32_bf16 v[12:15], v[170:173], v[226:229], v[12:15]
	v_mfma_f32_16x16x32_bf16 v[8:11], v[178:181], v[226:229], v[8:11]
	s_setprio 0
	s_setprio 1
	v_mfma_f32_16x16x32_bf16 v[52:55], v[182:185], v[198:201], 0
	v_mfma_f32_16x16x32_bf16 v[48:51], v[190:193], v[198:201], 0
	v_mfma_f32_16x16x32_bf16 v[36:39], v[182:185], v[206:209], 0
	v_mfma_f32_16x16x32_bf16 v[32:35], v[190:193], v[206:209], 0
	v_mfma_f32_16x16x32_bf16 v[20:23], v[182:185], v[214:217], 0
	v_mfma_f32_16x16x32_bf16 v[16:19], v[190:193], v[214:217], 0
	v_mfma_f32_16x16x32_bf16 v[4:7], v[182:185], v[222:225], 0
	v_mfma_f32_16x16x32_bf16 v[0:3], v[190:193], v[222:225], 0
	v_mfma_f32_16x16x32_bf16 v[52:55], v[186:189], v[202:205], v[52:55]
	v_mfma_f32_16x16x32_bf16 v[48:51], v[194:197], v[202:205], v[48:51]
	v_mfma_f32_16x16x32_bf16 v[36:39], v[186:189], v[210:213], v[36:39]
	v_mfma_f32_16x16x32_bf16 v[32:35], v[194:197], v[210:213], v[32:35]
	v_mfma_f32_16x16x32_bf16 v[20:23], v[186:189], v[218:221], v[20:23]
	v_mfma_f32_16x16x32_bf16 v[16:19], v[194:197], v[218:221], v[16:19]
	v_mfma_f32_16x16x32_bf16 v[4:7], v[186:189], v[226:229], v[4:7]
	v_mfma_f32_16x16x32_bf16 v[0:3], v[194:197], v[226:229], v[0:3]
	s_barrier
	s_setprio 0
	s_add_i32 s8, 0, 0x18000
	v_add_u32_e32 v152, s8, v157
	s_add_i32 s82, 0, 0x1c000
	ds_read_b128 v[166:169], v152
	ds_read_b128 v[170:173], v152 offset:1024
	ds_read_b128 v[174:177], v152 offset:2048
	ds_read_b128 v[178:181], v152 offset:3072
	v_add_u32_e32 v152, s82, v157
	ds_read_b128 v[182:185], v152
	ds_read_b128 v[186:189], v152 offset:1024
	ds_read_b128 v[190:193], v152 offset:2048
	ds_read_b128 v[194:197], v152 offset:3072
	s_add_u32 s50, s52, 0x40000
	s_addc_u32 s51, s53, 0
	s_mov_b32 m0, s59
	ds_read_b128 v[198:201], v161 offset:32768
	ds_read_b128 v[202:205], v161 offset:33792
	ds_read_b128 v[206:209], v161 offset:34816
	ds_read_b128 v[210:213], v161 offset:35840
	ds_read_b128 v[214:217], v161 offset:36864
	ds_read_b128 v[218:221], v161 offset:37888
	ds_read_b128 v[222:225], v161 offset:38912
	global_load_lds_dwordx4 v134, s[50:51]
	s_mov_b32 m0, s60
	ds_read_b128 v[226:229], v161 offset:39936
	global_load_lds_dwordx4 v132, s[50:51]
	s_waitcnt vmcnt(8)
	s_waitcnt lgkmcnt(0)
	s_setprio 1
	s_barrier
	v_mfma_f32_16x16x32_bf16 v[124:127], v[166:169], v[198:201], v[124:127]
	v_mfma_f32_16x16x32_bf16 v[120:123], v[174:177], v[198:201], v[120:123]
	v_mfma_f32_16x16x32_bf16 v[108:111], v[166:169], v[206:209], v[108:111]
	v_mfma_f32_16x16x32_bf16 v[104:107], v[174:177], v[206:209], v[104:107]
	v_mfma_f32_16x16x32_bf16 v[92:95], v[166:169], v[214:217], v[92:95]
	v_mfma_f32_16x16x32_bf16 v[88:91], v[174:177], v[214:217], v[88:91]
	v_mfma_f32_16x16x32_bf16 v[76:79], v[166:169], v[222:225], v[76:79]
	v_mfma_f32_16x16x32_bf16 v[72:75], v[174:177], v[222:225], v[72:75]
	v_mfma_f32_16x16x32_bf16 v[124:127], v[170:173], v[202:205], v[124:127]
	v_mfma_f32_16x16x32_bf16 v[120:123], v[178:181], v[202:205], v[120:123]
	v_mfma_f32_16x16x32_bf16 v[108:111], v[170:173], v[210:213], v[108:111]
	v_mfma_f32_16x16x32_bf16 v[104:107], v[178:181], v[210:213], v[104:107]
	v_mfma_f32_16x16x32_bf16 v[92:95], v[170:173], v[218:221], v[92:95]
	v_mfma_f32_16x16x32_bf16 v[88:91], v[178:181], v[218:221], v[88:91]
	v_mfma_f32_16x16x32_bf16 v[76:79], v[170:173], v[226:229], v[76:79]
	v_mfma_f32_16x16x32_bf16 v[72:75], v[178:181], v[226:229], v[72:75]
	s_setprio 0
	s_setprio 1
	v_mfma_f32_16x16x32_bf16 v[116:119], v[182:185], v[198:201], v[116:119]
	v_mfma_f32_16x16x32_bf16 v[112:115], v[190:193], v[198:201], v[112:115]
	v_mfma_f32_16x16x32_bf16 v[100:103], v[182:185], v[206:209], v[100:103]
	v_mfma_f32_16x16x32_bf16 v[96:99], v[190:193], v[206:209], v[96:99]
	v_mfma_f32_16x16x32_bf16 v[84:87], v[182:185], v[214:217], v[84:87]
	v_mfma_f32_16x16x32_bf16 v[80:83], v[190:193], v[214:217], v[80:83]
	v_mfma_f32_16x16x32_bf16 v[68:71], v[182:185], v[222:225], v[68:71]
	v_mfma_f32_16x16x32_bf16 v[64:67], v[190:193], v[222:225], v[64:67]
	v_mfma_f32_16x16x32_bf16 v[116:119], v[186:189], v[202:205], v[116:119]
	v_mfma_f32_16x16x32_bf16 v[112:115], v[194:197], v[202:205], v[112:115]
	v_mfma_f32_16x16x32_bf16 v[100:103], v[186:189], v[210:213], v[100:103]
	v_mfma_f32_16x16x32_bf16 v[96:99], v[194:197], v[210:213], v[96:99]
	v_mfma_f32_16x16x32_bf16 v[84:87], v[186:189], v[218:221], v[84:87]
	v_mfma_f32_16x16x32_bf16 v[80:83], v[194:197], v[218:221], v[80:83]
	v_mfma_f32_16x16x32_bf16 v[68:71], v[186:189], v[226:229], v[68:71]
	v_mfma_f32_16x16x32_bf16 v[64:67], v[194:197], v[226:229], v[64:67]
	s_barrier
	s_setprio 0
	s_add_i32 s8, s8, s54
	s_mov_b32 m0, s8
	ds_read_b128 v[198:201], v161 offset:49152
	ds_read_b128 v[202:205], v161 offset:50176
	ds_read_b128 v[206:209], v161 offset:51200
	global_load_lds_dwordx4 v128, s[48:49]
	s_add_i32 m0, s8, 0x2000
	ds_read_b128 v[210:213], v161 offset:52224
	global_load_lds_dwordx4 v130, s[48:49]
	s_add_u32 s48, s48, 0x40000
	s_addc_u32 s49, s49, 0
	s_add_i32 s8, s82, s54
	s_mov_b32 m0, s8
	ds_read_b128 v[214:217], v161 offset:53248
	global_load_lds_dwordx4 v128, s[48:49]
	s_add_i32 m0, s8, 0x2000
	ds_read_b128 v[218:221], v161 offset:54272
	global_load_lds_dwordx4 v130, s[48:49]
	s_mov_b32 m0, s65
	ds_read_b128 v[222:225], v161 offset:55296
	global_load_lds_dwordx4 v134, s[46:47]
	s_mov_b32 m0, s66
	ds_read_b128 v[226:229], v161 offset:56320
	global_load_lds_dwordx4 v132, s[46:47]
	s_waitcnt vmcnt(8)
	s_waitcnt lgkmcnt(0)
	s_setprio 1
	s_barrier
	v_mfma_f32_16x16x32_bf16 v[60:63], v[166:169], v[198:201], v[60:63]
	v_mfma_f32_16x16x32_bf16 v[56:59], v[174:177], v[198:201], v[56:59]
	v_mfma_f32_16x16x32_bf16 v[44:47], v[166:169], v[206:209], v[44:47]
	v_mfma_f32_16x16x32_bf16 v[40:43], v[174:177], v[206:209], v[40:43]
	v_mfma_f32_16x16x32_bf16 v[28:31], v[166:169], v[214:217], v[28:31]
	v_mfma_f32_16x16x32_bf16 v[24:27], v[174:177], v[214:217], v[24:27]
	v_mfma_f32_16x16x32_bf16 v[12:15], v[166:169], v[222:225], v[12:15]
	v_mfma_f32_16x16x32_bf16 v[8:11], v[174:177], v[222:225], v[8:11]
	v_mfma_f32_16x16x32_bf16 v[60:63], v[170:173], v[202:205], v[60:63]
	v_mfma_f32_16x16x32_bf16 v[56:59], v[178:181], v[202:205], v[56:59]
	v_mfma_f32_16x16x32_bf16 v[44:47], v[170:173], v[210:213], v[44:47]
	v_mfma_f32_16x16x32_bf16 v[40:43], v[178:181], v[210:213], v[40:43]
	v_mfma_f32_16x16x32_bf16 v[28:31], v[170:173], v[218:221], v[28:31]
	v_mfma_f32_16x16x32_bf16 v[24:27], v[178:181], v[218:221], v[24:27]
	v_mfma_f32_16x16x32_bf16 v[12:15], v[170:173], v[226:229], v[12:15]
	v_mfma_f32_16x16x32_bf16 v[8:11], v[178:181], v[226:229], v[8:11]
	s_setprio 0
	s_setprio 1
	v_mfma_f32_16x16x32_bf16 v[52:55], v[182:185], v[198:201], v[52:55]
	v_mfma_f32_16x16x32_bf16 v[48:51], v[190:193], v[198:201], v[48:51]
	v_mfma_f32_16x16x32_bf16 v[36:39], v[182:185], v[206:209], v[36:39]
	v_mfma_f32_16x16x32_bf16 v[32:35], v[190:193], v[206:209], v[32:35]
	v_mfma_f32_16x16x32_bf16 v[20:23], v[182:185], v[214:217], v[20:23]
	v_mfma_f32_16x16x32_bf16 v[16:19], v[190:193], v[214:217], v[16:19]
	v_mfma_f32_16x16x32_bf16 v[4:7], v[182:185], v[222:225], v[4:7]
	v_mfma_f32_16x16x32_bf16 v[0:3], v[190:193], v[222:225], v[0:3]
	v_mfma_f32_16x16x32_bf16 v[52:55], v[186:189], v[202:205], v[52:55]
	v_mfma_f32_16x16x32_bf16 v[48:51], v[194:197], v[202:205], v[48:51]
	v_mfma_f32_16x16x32_bf16 v[36:39], v[186:189], v[210:213], v[36:39]
	v_mfma_f32_16x16x32_bf16 v[32:35], v[194:197], v[210:213], v[32:35]
	v_mfma_f32_16x16x32_bf16 v[20:23], v[186:189], v[218:221], v[20:23]
	v_mfma_f32_16x16x32_bf16 v[16:19], v[194:197], v[218:221], v[16:19]
	v_mfma_f32_16x16x32_bf16 v[4:7], v[186:189], v[226:229], v[4:7]
	v_mfma_f32_16x16x32_bf16 v[0:3], v[194:197], v[226:229], v[0:3]
	s_barrier
	s_setprio 0
	s_add_i32 s8, s81, 2
	s_add_u32 s44, s44, 0x100
	s_addc_u32 s45, s45, 0
	s_cmp_gt_u32 s81, 13
	s_mov_b32 s81, s8
	s_cbranch_scc1 .LBB0_813
	s_branch .LBB0_807
.LBB0_806:
	v_add_u32_e32 v152, s68, v157
	ds_read_b128 v[166:169], v152
	ds_read_b128 v[170:173], v152 offset:1024
	ds_read_b128 v[174:177], v152 offset:2048
	ds_read_b128 v[178:181], v152 offset:3072
	v_add_u32_e32 v152, s69, v157
	ds_read_b128 v[182:185], v152
	ds_read_b128 v[186:189], v152 offset:1024
	ds_read_b128 v[190:193], v152 offset:2048
	ds_read_b128 v[194:197], v152 offset:3072
	s_add_u32 s8, s52, 0x100
	s_addc_u32 s84, s53, 0
	s_and_b64 s[52:53], exec, s[50:51]
	s_cselect_b32 s53, s21, s84
	s_cselect_b32 s52, s79, s8
	s_add_u32 s8, s83, 0x100
	s_addc_u32 s82, s82, 0
	s_and_b64 s[50:51], exec, s[50:51]
	s_cselect_b32 s51, s19, s82
	s_cselect_b32 s50, s80, s8
	v_lshl_add_u64 v[154:155], v[148:149], 0, s[44:45]
	s_add_i32 m0, s57, 0xc000
	ds_read_b128 v[198:201], v161
	ds_read_b128 v[202:205], v161 offset:1024
	ds_read_b128 v[206:209], v161 offset:2048
	ds_read_b128 v[210:213], v161 offset:3072
	ds_read_b128 v[214:217], v161 offset:4096
	ds_read_b128 v[218:221], v161 offset:5120
	ds_read_b128 v[222:225], v161 offset:6144
	global_load_lds_dwordx4 v[154:155], off
	v_lshl_add_u64 v[154:155], v[150:151], 0, s[44:45]
	s_add_i32 m0, s57, 0xe000
	ds_read_b128 v[226:229], v161 offset:7168
	global_load_lds_dwordx4 v[154:155], off
	s_waitcnt vmcnt(8)
	s_waitcnt lgkmcnt(0)
	s_setprio 1
	s_barrier
	v_mfma_f32_16x16x32_bf16 v[124:127], v[166:169], v[198:201], v[124:127]
	v_mfma_f32_16x16x32_bf16 v[120:123], v[174:177], v[198:201], v[120:123]
	v_mfma_f32_16x16x32_bf16 v[108:111], v[166:169], v[206:209], v[108:111]
	v_mfma_f32_16x16x32_bf16 v[104:107], v[174:177], v[206:209], v[104:107]
	v_mfma_f32_16x16x32_bf16 v[92:95], v[166:169], v[214:217], v[92:95]
	v_mfma_f32_16x16x32_bf16 v[88:91], v[174:177], v[214:217], v[88:91]
	v_mfma_f32_16x16x32_bf16 v[76:79], v[166:169], v[222:225], v[76:79]
	v_mfma_f32_16x16x32_bf16 v[72:75], v[174:177], v[222:225], v[72:75]
	v_mfma_f32_16x16x32_bf16 v[124:127], v[170:173], v[202:205], v[124:127]
	v_mfma_f32_16x16x32_bf16 v[120:123], v[178:181], v[202:205], v[120:123]
	v_mfma_f32_16x16x32_bf16 v[108:111], v[170:173], v[210:213], v[108:111]
	v_mfma_f32_16x16x32_bf16 v[104:107], v[178:181], v[210:213], v[104:107]
	v_mfma_f32_16x16x32_bf16 v[92:95], v[170:173], v[218:221], v[92:95]
	v_mfma_f32_16x16x32_bf16 v[88:91], v[178:181], v[218:221], v[88:91]
	v_mfma_f32_16x16x32_bf16 v[76:79], v[170:173], v[226:229], v[76:79]
	v_mfma_f32_16x16x32_bf16 v[72:75], v[178:181], v[226:229], v[72:75]
	s_setprio 0
	s_setprio 1
	v_mfma_f32_16x16x32_bf16 v[116:119], v[182:185], v[198:201], v[116:119]
	v_mfma_f32_16x16x32_bf16 v[112:115], v[190:193], v[198:201], v[112:115]
	v_mfma_f32_16x16x32_bf16 v[100:103], v[182:185], v[206:209], v[100:103]
	v_mfma_f32_16x16x32_bf16 v[96:99], v[190:193], v[206:209], v[96:99]
	v_mfma_f32_16x16x32_bf16 v[84:87], v[182:185], v[214:217], v[84:87]
	v_mfma_f32_16x16x32_bf16 v[80:83], v[190:193], v[214:217], v[80:83]
	v_mfma_f32_16x16x32_bf16 v[68:71], v[182:185], v[222:225], v[68:71]
	v_mfma_f32_16x16x32_bf16 v[64:67], v[190:193], v[222:225], v[64:67]
	v_mfma_f32_16x16x32_bf16 v[116:119], v[186:189], v[202:205], v[116:119]
	v_mfma_f32_16x16x32_bf16 v[112:115], v[194:197], v[202:205], v[112:115]
	v_mfma_f32_16x16x32_bf16 v[100:103], v[186:189], v[210:213], v[100:103]
	v_mfma_f32_16x16x32_bf16 v[96:99], v[194:197], v[210:213], v[96:99]
	v_mfma_f32_16x16x32_bf16 v[84:87], v[186:189], v[218:221], v[84:87]
	v_mfma_f32_16x16x32_bf16 v[80:83], v[194:197], v[218:221], v[80:83]
	v_mfma_f32_16x16x32_bf16 v[68:71], v[186:189], v[226:229], v[68:71]
	v_mfma_f32_16x16x32_bf16 v[64:67], v[194:197], v[226:229], v[64:67]
	s_barrier
	s_setprio 0
	s_add_i32 s8, s68, s54
	s_mov_b32 m0, s8
	ds_read_b128 v[198:201], v161 offset:16384
	ds_read_b128 v[202:205], v161 offset:17408
	ds_read_b128 v[206:209], v161 offset:18432
	global_load_lds_dwordx4 v128, s[50:51]
	s_add_i32 m0, s8, 0x2000
	ds_read_b128 v[210:213], v161 offset:19456
	global_load_lds_dwordx4 v130, s[50:51]
	s_add_u32 s50, s50, 0x40000
	s_addc_u32 s51, s51, 0
	s_add_i32 s8, s69, s54
	s_mov_b32 m0, s8
	ds_read_b128 v[214:217], v161 offset:20480
	global_load_lds_dwordx4 v128, s[50:51]
	s_add_i32 m0, s8, 0x2000
	ds_read_b128 v[218:221], v161 offset:21504
	global_load_lds_dwordx4 v130, s[50:51]
	s_mov_b32 m0, s57
	ds_read_b128 v[222:225], v161 offset:22528
	global_load_lds_dwordx4 v134, s[52:53]
	s_mov_b32 m0, s58
	ds_read_b128 v[226:229], v161 offset:23552
	global_load_lds_dwordx4 v132, s[52:53]
	s_waitcnt vmcnt(8)
	s_waitcnt lgkmcnt(0)
	s_setprio 1
	s_barrier
	v_mfma_f32_16x16x32_bf16 v[60:63], v[166:169], v[198:201], v[60:63]
	v_mfma_f32_16x16x32_bf16 v[56:59], v[174:177], v[198:201], v[56:59]
	v_mfma_f32_16x16x32_bf16 v[44:47], v[166:169], v[206:209], v[44:47]
	v_mfma_f32_16x16x32_bf16 v[40:43], v[174:177], v[206:209], v[40:43]
	v_mfma_f32_16x16x32_bf16 v[28:31], v[166:169], v[214:217], v[28:31]
	v_mfma_f32_16x16x32_bf16 v[24:27], v[174:177], v[214:217], v[24:27]
	v_mfma_f32_16x16x32_bf16 v[12:15], v[166:169], v[222:225], v[12:15]
	v_mfma_f32_16x16x32_bf16 v[8:11], v[174:177], v[222:225], v[8:11]
	v_mfma_f32_16x16x32_bf16 v[60:63], v[170:173], v[202:205], v[60:63]
	v_mfma_f32_16x16x32_bf16 v[56:59], v[178:181], v[202:205], v[56:59]
	v_mfma_f32_16x16x32_bf16 v[44:47], v[170:173], v[210:213], v[44:47]
	v_mfma_f32_16x16x32_bf16 v[40:43], v[178:181], v[210:213], v[40:43]
	v_mfma_f32_16x16x32_bf16 v[28:31], v[170:173], v[218:221], v[28:31]
	v_mfma_f32_16x16x32_bf16 v[24:27], v[178:181], v[218:221], v[24:27]
	v_mfma_f32_16x16x32_bf16 v[12:15], v[170:173], v[226:229], v[12:15]
	v_mfma_f32_16x16x32_bf16 v[8:11], v[178:181], v[226:229], v[8:11]
	s_setprio 0
	s_setprio 1
	v_mfma_f32_16x16x32_bf16 v[52:55], v[182:185], v[198:201], v[52:55]
	v_mfma_f32_16x16x32_bf16 v[48:51], v[190:193], v[198:201], v[48:51]
	v_mfma_f32_16x16x32_bf16 v[36:39], v[182:185], v[206:209], v[36:39]
	v_mfma_f32_16x16x32_bf16 v[32:35], v[190:193], v[206:209], v[32:35]
	v_mfma_f32_16x16x32_bf16 v[20:23], v[182:185], v[214:217], v[20:23]
	v_mfma_f32_16x16x32_bf16 v[16:19], v[190:193], v[214:217], v[16:19]
	v_mfma_f32_16x16x32_bf16 v[4:7], v[182:185], v[222:225], v[4:7]
	v_mfma_f32_16x16x32_bf16 v[0:3], v[190:193], v[222:225], v[0:3]
	v_mfma_f32_16x16x32_bf16 v[52:55], v[186:189], v[202:205], v[52:55]
	v_mfma_f32_16x16x32_bf16 v[48:51], v[194:197], v[202:205], v[48:51]
	v_mfma_f32_16x16x32_bf16 v[36:39], v[186:189], v[210:213], v[36:39]
	v_mfma_f32_16x16x32_bf16 v[32:35], v[194:197], v[210:213], v[32:35]
	v_mfma_f32_16x16x32_bf16 v[20:23], v[186:189], v[218:221], v[20:23]
	v_mfma_f32_16x16x32_bf16 v[16:19], v[194:197], v[218:221], v[16:19]
	v_mfma_f32_16x16x32_bf16 v[4:7], v[186:189], v[226:229], v[4:7]
	v_mfma_f32_16x16x32_bf16 v[0:3], v[194:197], v[226:229], v[0:3]
	s_barrier
	s_setprio 0
	s_add_i32 s8, 0, 0x18000
	v_add_u32_e32 v152, s8, v157
	s_add_i32 s82, 0, 0x1c000
	ds_read_b128 v[166:169], v152
	ds_read_b128 v[170:173], v152 offset:1024
	ds_read_b128 v[174:177], v152 offset:2048
	ds_read_b128 v[178:181], v152 offset:3072
	v_add_u32_e32 v152, s82, v157
	ds_read_b128 v[182:185], v152
	ds_read_b128 v[186:189], v152 offset:1024
	ds_read_b128 v[190:193], v152 offset:2048
	ds_read_b128 v[194:197], v152 offset:3072
	s_add_u32 s50, s52, 0x40000
	s_addc_u32 s51, s53, 0
	s_mov_b32 m0, s59
	ds_read_b128 v[198:201], v161 offset:32768
	ds_read_b128 v[202:205], v161 offset:33792
	ds_read_b128 v[206:209], v161 offset:34816
	ds_read_b128 v[210:213], v161 offset:35840
	ds_read_b128 v[214:217], v161 offset:36864
	ds_read_b128 v[218:221], v161 offset:37888
	ds_read_b128 v[222:225], v161 offset:38912
	global_load_lds_dwordx4 v134, s[50:51]
	s_mov_b32 m0, s60
	ds_read_b128 v[226:229], v161 offset:39936
	global_load_lds_dwordx4 v132, s[50:51]
	s_waitcnt vmcnt(8)
	s_waitcnt lgkmcnt(0)
	s_setprio 1
	s_barrier
	v_mfma_f32_16x16x32_bf16 v[124:127], v[166:169], v[198:201], v[124:127]
	v_mfma_f32_16x16x32_bf16 v[120:123], v[174:177], v[198:201], v[120:123]
	v_mfma_f32_16x16x32_bf16 v[108:111], v[166:169], v[206:209], v[108:111]
	v_mfma_f32_16x16x32_bf16 v[104:107], v[174:177], v[206:209], v[104:107]
	v_mfma_f32_16x16x32_bf16 v[92:95], v[166:169], v[214:217], v[92:95]
	v_mfma_f32_16x16x32_bf16 v[88:91], v[174:177], v[214:217], v[88:91]
	v_mfma_f32_16x16x32_bf16 v[76:79], v[166:169], v[222:225], v[76:79]
	v_mfma_f32_16x16x32_bf16 v[72:75], v[174:177], v[222:225], v[72:75]
	v_mfma_f32_16x16x32_bf16 v[124:127], v[170:173], v[202:205], v[124:127]
	v_mfma_f32_16x16x32_bf16 v[120:123], v[178:181], v[202:205], v[120:123]
	v_mfma_f32_16x16x32_bf16 v[108:111], v[170:173], v[210:213], v[108:111]
	v_mfma_f32_16x16x32_bf16 v[104:107], v[178:181], v[210:213], v[104:107]
	v_mfma_f32_16x16x32_bf16 v[92:95], v[170:173], v[218:221], v[92:95]
	v_mfma_f32_16x16x32_bf16 v[88:91], v[178:181], v[218:221], v[88:91]
	v_mfma_f32_16x16x32_bf16 v[76:79], v[170:173], v[226:229], v[76:79]
	v_mfma_f32_16x16x32_bf16 v[72:75], v[178:181], v[226:229], v[72:75]
	s_setprio 0
	s_setprio 1
	v_mfma_f32_16x16x32_bf16 v[116:119], v[182:185], v[198:201], v[116:119]
	v_mfma_f32_16x16x32_bf16 v[112:115], v[190:193], v[198:201], v[112:115]
	v_mfma_f32_16x16x32_bf16 v[100:103], v[182:185], v[206:209], v[100:103]
	v_mfma_f32_16x16x32_bf16 v[96:99], v[190:193], v[206:209], v[96:99]
	v_mfma_f32_16x16x32_bf16 v[84:87], v[182:185], v[214:217], v[84:87]
	v_mfma_f32_16x16x32_bf16 v[80:83], v[190:193], v[214:217], v[80:83]
	v_mfma_f32_16x16x32_bf16 v[68:71], v[182:185], v[222:225], v[68:71]
	v_mfma_f32_16x16x32_bf16 v[64:67], v[190:193], v[222:225], v[64:67]
	v_mfma_f32_16x16x32_bf16 v[116:119], v[186:189], v[202:205], v[116:119]
	v_mfma_f32_16x16x32_bf16 v[112:115], v[194:197], v[202:205], v[112:115]
	v_mfma_f32_16x16x32_bf16 v[100:103], v[186:189], v[210:213], v[100:103]
	v_mfma_f32_16x16x32_bf16 v[96:99], v[194:197], v[210:213], v[96:99]
	v_mfma_f32_16x16x32_bf16 v[84:87], v[186:189], v[218:221], v[84:87]
	v_mfma_f32_16x16x32_bf16 v[80:83], v[194:197], v[218:221], v[80:83]
	v_mfma_f32_16x16x32_bf16 v[68:71], v[186:189], v[226:229], v[68:71]
	v_mfma_f32_16x16x32_bf16 v[64:67], v[194:197], v[226:229], v[64:67]
	s_barrier
	s_setprio 0
	s_add_i32 s8, s8, s54
	s_mov_b32 m0, s8
	ds_read_b128 v[198:201], v161 offset:49152
	ds_read_b128 v[202:205], v161 offset:50176
	ds_read_b128 v[206:209], v161 offset:51200
	global_load_lds_dwordx4 v128, s[48:49]
	s_add_i32 m0, s8, 0x2000
	ds_read_b128 v[210:213], v161 offset:52224
	global_load_lds_dwordx4 v130, s[48:49]
	s_add_u32 s48, s48, 0x40000
	s_addc_u32 s49, s49, 0
	s_add_i32 s8, s82, s54
	s_mov_b32 m0, s8
	ds_read_b128 v[214:217], v161 offset:53248
	global_load_lds_dwordx4 v128, s[48:49]
	s_add_i32 m0, s8, 0x2000
	ds_read_b128 v[218:221], v161 offset:54272
	global_load_lds_dwordx4 v130, s[48:49]
	s_mov_b32 m0, s65
	ds_read_b128 v[222:225], v161 offset:55296
	global_load_lds_dwordx4 v134, s[46:47]
	s_mov_b32 m0, s66
	ds_read_b128 v[226:229], v161 offset:56320
	global_load_lds_dwordx4 v132, s[46:47]
	s_waitcnt vmcnt(8)
	s_waitcnt lgkmcnt(0)
	s_setprio 1
	s_barrier
	v_mfma_f32_16x16x32_bf16 v[60:63], v[166:169], v[198:201], v[60:63]
	v_mfma_f32_16x16x32_bf16 v[56:59], v[174:177], v[198:201], v[56:59]
	v_mfma_f32_16x16x32_bf16 v[44:47], v[166:169], v[206:209], v[44:47]
	v_mfma_f32_16x16x32_bf16 v[40:43], v[174:177], v[206:209], v[40:43]
	v_mfma_f32_16x16x32_bf16 v[28:31], v[166:169], v[214:217], v[28:31]
	v_mfma_f32_16x16x32_bf16 v[24:27], v[174:177], v[214:217], v[24:27]
	v_mfma_f32_16x16x32_bf16 v[12:15], v[166:169], v[222:225], v[12:15]
	v_mfma_f32_16x16x32_bf16 v[8:11], v[174:177], v[222:225], v[8:11]
	v_mfma_f32_16x16x32_bf16 v[60:63], v[170:173], v[202:205], v[60:63]
	v_mfma_f32_16x16x32_bf16 v[56:59], v[178:181], v[202:205], v[56:59]
	v_mfma_f32_16x16x32_bf16 v[44:47], v[170:173], v[210:213], v[44:47]
	v_mfma_f32_16x16x32_bf16 v[40:43], v[178:181], v[210:213], v[40:43]
	v_mfma_f32_16x16x32_bf16 v[28:31], v[170:173], v[218:221], v[28:31]
	v_mfma_f32_16x16x32_bf16 v[24:27], v[178:181], v[218:221], v[24:27]
	v_mfma_f32_16x16x32_bf16 v[12:15], v[170:173], v[226:229], v[12:15]
	v_mfma_f32_16x16x32_bf16 v[8:11], v[178:181], v[226:229], v[8:11]
	s_setprio 0
	s_setprio 1
	v_mfma_f32_16x16x32_bf16 v[52:55], v[182:185], v[198:201], v[52:55]
	v_mfma_f32_16x16x32_bf16 v[48:51], v[190:193], v[198:201], v[48:51]
	v_mfma_f32_16x16x32_bf16 v[36:39], v[182:185], v[206:209], v[36:39]
	v_mfma_f32_16x16x32_bf16 v[32:35], v[190:193], v[206:209], v[32:35]
	v_mfma_f32_16x16x32_bf16 v[20:23], v[182:185], v[214:217], v[20:23]
	v_mfma_f32_16x16x32_bf16 v[16:19], v[190:193], v[214:217], v[16:19]
	v_mfma_f32_16x16x32_bf16 v[4:7], v[182:185], v[222:225], v[4:7]
	v_mfma_f32_16x16x32_bf16 v[0:3], v[190:193], v[222:225], v[0:3]
	v_mfma_f32_16x16x32_bf16 v[52:55], v[186:189], v[202:205], v[52:55]
	v_mfma_f32_16x16x32_bf16 v[48:51], v[194:197], v[202:205], v[48:51]
	v_mfma_f32_16x16x32_bf16 v[36:39], v[186:189], v[210:213], v[36:39]
	v_mfma_f32_16x16x32_bf16 v[32:35], v[194:197], v[210:213], v[32:35]
	v_mfma_f32_16x16x32_bf16 v[20:23], v[186:189], v[218:221], v[20:23]
	v_mfma_f32_16x16x32_bf16 v[16:19], v[194:197], v[218:221], v[16:19]
	v_mfma_f32_16x16x32_bf16 v[4:7], v[186:189], v[226:229], v[4:7]
	v_mfma_f32_16x16x32_bf16 v[0:3], v[194:197], v[226:229], v[0:3]
	s_barrier
	s_setprio 0
	s_add_i32 s8, s81, 2
	s_add_u32 s44, s44, 0x100
	s_addc_u32 s45, s45, 0
	s_cmp_gt_u32 s81, 13
	s_mov_b32 s81, s8
	s_cbranch_scc1 .LBB0_813

.LBB0_895:
	s_add_u32 s70, s55, s28
	s_addc_u32 s71, s56, s29
	s_add_u32 s72, s57, s30
	s_addc_u32 s73, s58, s31
	s_add_u32 s28, s4, 0x80
	s_addc_u32 s29, s5, 0
	s_add_u32 s30, s20, 0x80
	s_addc_u32 s31, s21, 0
	v_lshl_add_u64 v[128:129], s[26:27], 0, v[148:149]
	v_lshl_add_u64 v[130:131], s[26:27], 0, v[150:151]
	s_mov_b32 s78, 0
	s_mov_b64 s[36:37], 0
	s_cmpk_eq_i32 s36, 0x1500
	s_cselect_b64 s[44:45], -1, 0
	s_add_u32 s46, s26, s36
	s_addc_u32 s47, s27, s37
	s_add_u32 s80, s24, s36
	s_addc_u32 s79, s25, s37
	s_add_u32 s38, s46, 0x180
	s_addc_u32 s39, s47, 0
	s_add_u32 s40, s80, 0x180
	s_addc_u32 s41, s79, 0
	s_cmpk_eq_i32 s36, 0x1500
	s_cselect_b32 s38, s28, s38
	s_cselect_b32 s39, s29, s39
	s_cselect_b32 s40, s30, s40
	s_cselect_b32 s41, s31, s41
	v_add_u32_e32 v167, s64, v165
	ds_read_b128 v[132:135], v167
	ds_read_b128 v[156:159], v167 offset:1024
	ds_read_b128 v[160:163], v167 offset:2048
	ds_read_b128 v[168:171], v167 offset:3072
	v_add_u32_e32 v167, s65, v165
	ds_read_b128 v[172:175], v167
	ds_read_b128 v[176:179], v167 offset:1024
	ds_read_b128 v[180:183], v167 offset:2048
	ds_read_b128 v[184:187], v167 offset:3072
	s_add_u32 s8, s46, 0x100
	s_addc_u32 s81, s47, 0
	s_and_b64 s[46:47], exec, s[44:45]
	s_cselect_b32 s47, s5, s81
	s_cselect_b32 s46, s4, s8
	s_add_u32 s8, s80, 0x100
	s_addc_u32 s79, s79, 0
	s_and_b64 s[44:45], exec, s[44:45]
	s_cselect_b32 s45, s21, s79
	s_cselect_b32 s44, s20, s8
	v_lshl_add_u64 v[220:221], v[128:129], 0, s[36:37]
	s_add_i32 m0, s51, 0xc000
	ds_read_b128 v[188:191], v166
	ds_read_b128 v[192:195], v166 offset:1024
	ds_read_b128 v[196:199], v166 offset:2048
	ds_read_b128 v[200:203], v166 offset:3072
	ds_read_b128 v[204:207], v166 offset:4096
	ds_read_b128 v[208:211], v166 offset:5120
	ds_read_b128 v[212:215], v166 offset:6144
	global_load_lds_dwordx4 v[220:221], off
	v_lshl_add_u64 v[220:221], v[130:131], 0, s[36:37]
	s_add_i32 m0, s51, 0xe000
	ds_read_b128 v[216:219], v166 offset:7168
	global_load_lds_dwordx4 v[220:221], off
	s_waitcnt vmcnt(8)
	s_waitcnt lgkmcnt(0)
	s_setprio 1
	s_barrier
	v_mfma_f32_16x16x32_bf16 v[124:127], v[132:135], v[188:191], 0
	v_mfma_f32_16x16x32_bf16 v[120:123], v[160:163], v[188:191], 0
	v_mfma_f32_16x16x32_bf16 v[108:111], v[132:135], v[196:199], 0
	v_mfma_f32_16x16x32_bf16 v[104:107], v[160:163], v[196:199], 0
	v_mfma_f32_16x16x32_bf16 v[92:95], v[132:135], v[204:207], 0
	v_mfma_f32_16x16x32_bf16 v[88:91], v[160:163], v[204:207], 0
	v_mfma_f32_16x16x32_bf16 v[76:79], v[132:135], v[212:215], 0
	v_mfma_f32_16x16x32_bf16 v[72:75], v[160:163], v[212:215], 0
	v_mfma_f32_16x16x32_bf16 v[124:127], v[156:159], v[192:195], v[124:127]
	v_mfma_f32_16x16x32_bf16 v[120:123], v[168:171], v[192:195], v[120:123]
	v_mfma_f32_16x16x32_bf16 v[108:111], v[156:159], v[200:203], v[108:111]
	v_mfma_f32_16x16x32_bf16 v[104:107], v[168:171], v[200:203], v[104:107]
	v_mfma_f32_16x16x32_bf16 v[92:95], v[156:159], v[208:211], v[92:95]
	v_mfma_f32_16x16x32_bf16 v[88:91], v[168:171], v[208:211], v[88:91]
	v_mfma_f32_16x16x32_bf16 v[76:79], v[156:159], v[216:219], v[76:79]
	v_mfma_f32_16x16x32_bf16 v[72:75], v[168:171], v[216:219], v[72:75]
	s_setprio 0
	s_setprio 1
	v_mfma_f32_16x16x32_bf16 v[116:119], v[172:175], v[188:191], 0
	v_mfma_f32_16x16x32_bf16 v[112:115], v[180:183], v[188:191], 0
	v_mfma_f32_16x16x32_bf16 v[100:103], v[172:175], v[196:199], 0
	v_mfma_f32_16x16x32_bf16 v[96:99], v[180:183], v[196:199], 0
	v_mfma_f32_16x16x32_bf16 v[84:87], v[172:175], v[204:207], 0
	v_mfma_f32_16x16x32_bf16 v[80:83], v[180:183], v[204:207], 0
	v_mfma_f32_16x16x32_bf16 v[68:71], v[172:175], v[212:215], 0
	v_mfma_f32_16x16x32_bf16 v[64:67], v[180:183], v[212:215], 0
	v_mfma_f32_16x16x32_bf16 v[116:119], v[176:179], v[192:195], v[116:119]
	v_mfma_f32_16x16x32_bf16 v[112:115], v[184:187], v[192:195], v[112:115]
	v_mfma_f32_16x16x32_bf16 v[100:103], v[176:179], v[200:203], v[100:103]
	v_mfma_f32_16x16x32_bf16 v[96:99], v[184:187], v[200:203], v[96:99]
	v_mfma_f32_16x16x32_bf16 v[84:87], v[176:179], v[208:211], v[84:87]
	v_mfma_f32_16x16x32_bf16 v[80:83], v[184:187], v[208:211], v[80:83]
	v_mfma_f32_16x16x32_bf16 v[68:71], v[176:179], v[216:219], v[68:71]
	v_mfma_f32_16x16x32_bf16 v[64:67], v[184:187], v[216:219], v[64:67]
	s_barrier
	s_setprio 0
	s_add_i32 s8, s64, s50
	s_mov_b32 m0, s8
	ds_read_b128 v[188:191], v166 offset:16384
	ds_read_b128 v[192:195], v166 offset:17408
	ds_read_b128 v[196:199], v166 offset:18432
	global_load_lds_dwordx4 v138, s[44:45]
	s_add_i32 m0, s8, 0x2000
	ds_read_b128 v[200:203], v166 offset:19456
	global_load_lds_dwordx4 v142, s[44:45]
	s_add_u32 s44, s44, 0xb0000
	s_addc_u32 s45, s45, 0
	s_add_i32 s8, s65, s50
	s_mov_b32 m0, s8
	ds_read_b128 v[204:207], v166 offset:20480
	global_load_lds_dwordx4 v138, s[44:45]
	s_add_i32 m0, s8, 0x2000
	ds_read_b128 v[208:211], v166 offset:21504
	global_load_lds_dwordx4 v142, s[44:45]
	s_mov_b32 m0, s51
	ds_read_b128 v[212:215], v166 offset:22528
	global_load_lds_dwordx4 v136, s[46:47]
	s_mov_b32 m0, s52
	ds_read_b128 v[216:219], v166 offset:23552
	global_load_lds_dwordx4 v140, s[46:47]
	s_waitcnt vmcnt(8)
	s_waitcnt lgkmcnt(0)
	s_setprio 1
	s_barrier
	v_mfma_f32_16x16x32_bf16 v[60:63], v[132:135], v[188:191], 0
	v_mfma_f32_16x16x32_bf16 v[56:59], v[160:163], v[188:191], 0
	v_mfma_f32_16x16x32_bf16 v[44:47], v[132:135], v[196:199], 0
	v_mfma_f32_16x16x32_bf16 v[40:43], v[160:163], v[196:199], 0
	v_mfma_f32_16x16x32_bf16 v[28:31], v[132:135], v[204:207], 0
	v_mfma_f32_16x16x32_bf16 v[24:27], v[160:163], v[204:207], 0
	v_mfma_f32_16x16x32_bf16 v[12:15], v[132:135], v[212:215], 0
	v_mfma_f32_16x16x32_bf16 v[8:11], v[160:163], v[212:215], 0
	v_mfma_f32_16x16x32_bf16 v[60:63], v[156:159], v[192:195], v[60:63]
	v_mfma_f32_16x16x32_bf16 v[56:59], v[168:171], v[192:195], v[56:59]
	v_mfma_f32_16x16x32_bf16 v[44:47], v[156:159], v[200:203], v[44:47]
	v_mfma_f32_16x16x32_bf16 v[40:43], v[168:171], v[200:203], v[40:43]
	v_mfma_f32_16x16x32_bf16 v[28:31], v[156:159], v[208:211], v[28:31]
	v_mfma_f32_16x16x32_bf16 v[24:27], v[168:171], v[208:211], v[24:27]
	v_mfma_f32_16x16x32_bf16 v[12:15], v[156:159], v[216:219], v[12:15]
	v_mfma_f32_16x16x32_bf16 v[8:11], v[168:171], v[216:219], v[8:11]
	s_setprio 0
	s_setprio 1
	v_mfma_f32_16x16x32_bf16 v[52:55], v[172:175], v[188:191], 0
	v_mfma_f32_16x16x32_bf16 v[48:51], v[180:183], v[188:191], 0
	v_mfma_f32_16x16x32_bf16 v[36:39], v[172:175], v[196:199], 0
	v_mfma_f32_16x16x32_bf16 v[32:35], v[180:183], v[196:199], 0
	v_mfma_f32_16x16x32_bf16 v[20:23], v[172:175], v[204:207], 0
	v_mfma_f32_16x16x32_bf16 v[16:19], v[180:183], v[204:207], 0
	v_mfma_f32_16x16x32_bf16 v[4:7], v[172:175], v[212:215], 0
	v_mfma_f32_16x16x32_bf16 v[0:3], v[180:183], v[212:215], 0
	v_mfma_f32_16x16x32_bf16 v[52:55], v[176:179], v[192:195], v[52:55]
	v_mfma_f32_16x16x32_bf16 v[48:51], v[184:187], v[192:195], v[48:51]
	v_mfma_f32_16x16x32_bf16 v[36:39], v[176:179], v[200:203], v[36:39]
	v_mfma_f32_16x16x32_bf16 v[32:35], v[184:187], v[200:203], v[32:35]
	v_mfma_f32_16x16x32_bf16 v[20:23], v[176:179], v[208:211], v[20:23]
	v_mfma_f32_16x16x32_bf16 v[16:19], v[184:187], v[208:211], v[16:19]
	v_mfma_f32_16x16x32_bf16 v[4:7], v[176:179], v[216:219], v[4:7]
	v_mfma_f32_16x16x32_bf16 v[0:3], v[184:187], v[216:219], v[0:3]
	s_barrier
	s_setprio 0
	s_add_i32 s8, 0, 0x18000
	v_add_u32_e32 v167, s8, v165
	s_add_i32 s79, 0, 0x1c000
	ds_read_b128 v[132:135], v167
	ds_read_b128 v[156:159], v167 offset:1024
	ds_read_b128 v[160:163], v167 offset:2048
	ds_read_b128 v[168:171], v167 offset:3072
	v_add_u32_e32 v167, s79, v165
	ds_read_b128 v[172:175], v167
	ds_read_b128 v[176:179], v167 offset:1024
	ds_read_b128 v[180:183], v167 offset:2048
	ds_read_b128 v[184:187], v167 offset:3072
	s_add_u32 s44, s46, 0xb0000
	s_addc_u32 s45, s47, 0
	s_mov_b32 m0, s53
	ds_read_b128 v[188:191], v166 offset:32768
	ds_read_b128 v[192:195], v166 offset:33792
	ds_read_b128 v[196:199], v166 offset:34816
	ds_read_b128 v[200:203], v166 offset:35840
	ds_read_b128 v[204:207], v166 offset:36864
	ds_read_b128 v[208:211], v166 offset:37888
	ds_read_b128 v[212:215], v166 offset:38912
	global_load_lds_dwordx4 v136, s[44:45]
	s_mov_b32 m0, s54
	ds_read_b128 v[216:219], v166 offset:39936
	global_load_lds_dwordx4 v140, s[44:45]
	s_waitcnt vmcnt(8)
	s_waitcnt lgkmcnt(0)
	s_setprio 1
	s_barrier
	v_mfma_f32_16x16x32_bf16 v[124:127], v[132:135], v[188:191], v[124:127]
	v_mfma_f32_16x16x32_bf16 v[120:123], v[160:163], v[188:191], v[120:123]
	v_mfma_f32_16x16x32_bf16 v[108:111], v[132:135], v[196:199], v[108:111]
	v_mfma_f32_16x16x32_bf16 v[104:107], v[160:163], v[196:199], v[104:107]
	v_mfma_f32_16x16x32_bf16 v[92:95], v[132:135], v[204:207], v[92:95]
	v_mfma_f32_16x16x32_bf16 v[88:91], v[160:163], v[204:207], v[88:91]
	v_mfma_f32_16x16x32_bf16 v[76:79], v[132:135], v[212:215], v[76:79]
	v_mfma_f32_16x16x32_bf16 v[72:75], v[160:163], v[212:215], v[72:75]
	v_mfma_f32_16x16x32_bf16 v[124:127], v[156:159], v[192:195], v[124:127]
	v_mfma_f32_16x16x32_bf16 v[120:123], v[168:171], v[192:195], v[120:123]
	v_mfma_f32_16x16x32_bf16 v[108:111], v[156:159], v[200:203], v[108:111]
	v_mfma_f32_16x16x32_bf16 v[104:107], v[168:171], v[200:203], v[104:107]
	v_mfma_f32_16x16x32_bf16 v[92:95], v[156:159], v[208:211], v[92:95]
	v_mfma_f32_16x16x32_bf16 v[88:91], v[168:171], v[208:211], v[88:91]
	v_mfma_f32_16x16x32_bf16 v[76:79], v[156:159], v[216:219], v[76:79]
	v_mfma_f32_16x16x32_bf16 v[72:75], v[168:171], v[216:219], v[72:75]
	s_setprio 0
	s_setprio 1
	v_mfma_f32_16x16x32_bf16 v[116:119], v[172:175], v[188:191], v[116:119]
	v_mfma_f32_16x16x32_bf16 v[112:115], v[180:183], v[188:191], v[112:115]
	v_mfma_f32_16x16x32_bf16 v[100:103], v[172:175], v[196:199], v[100:103]
	v_mfma_f32_16x16x32_bf16 v[96:99], v[180:183], v[196:199], v[96:99]
	v_mfma_f32_16x16x32_bf16 v[84:87], v[172:175], v[204:207], v[84:87]
	v_mfma_f32_16x16x32_bf16 v[80:83], v[180:183], v[204:207], v[80:83]
	v_mfma_f32_16x16x32_bf16 v[68:71], v[172:175], v[212:215], v[68:71]
	v_mfma_f32_16x16x32_bf16 v[64:67], v[180:183], v[212:215], v[64:67]
	v_mfma_f32_16x16x32_bf16 v[116:119], v[176:179], v[192:195], v[116:119]
	v_mfma_f32_16x16x32_bf16 v[112:115], v[184:187], v[192:195], v[112:115]
	v_mfma_f32_16x16x32_bf16 v[100:103], v[176:179], v[200:203], v[100:103]
	v_mfma_f32_16x16x32_bf16 v[96:99], v[184:187], v[200:203], v[96:99]
	v_mfma_f32_16x16x32_bf16 v[84:87], v[176:179], v[208:211], v[84:87]
	v_mfma_f32_16x16x32_bf16 v[80:83], v[184:187], v[208:211], v[80:83]
	v_mfma_f32_16x16x32_bf16 v[68:71], v[176:179], v[216:219], v[68:71]
	v_mfma_f32_16x16x32_bf16 v[64:67], v[184:187], v[216:219], v[64:67]
	s_barrier
	s_setprio 0
	s_add_i32 s8, s8, s50
	s_mov_b32 m0, s8
	ds_read_b128 v[188:191], v166 offset:49152
	ds_read_b128 v[192:195], v166 offset:50176
	ds_read_b128 v[196:199], v166 offset:51200
	global_load_lds_dwordx4 v138, s[40:41]
	s_add_i32 m0, s8, 0x2000
	ds_read_b128 v[200:203], v166 offset:52224
	global_load_lds_dwordx4 v142, s[40:41]
	s_add_u32 s40, s40, 0xb0000
	s_addc_u32 s41, s41, 0
	s_add_i32 s8, s79, s50
	s_mov_b32 m0, s8
	ds_read_b128 v[204:207], v166 offset:53248
	global_load_lds_dwordx4 v138, s[40:41]
	s_add_i32 m0, s8, 0x2000
	ds_read_b128 v[208:211], v166 offset:54272
	global_load_lds_dwordx4 v142, s[40:41]
	s_mov_b32 m0, s60
	ds_read_b128 v[212:215], v166 offset:55296
	global_load_lds_dwordx4 v136, s[38:39]
	s_mov_b32 m0, s61
	ds_read_b128 v[216:219], v166 offset:56320
	global_load_lds_dwordx4 v140, s[38:39]
	s_waitcnt vmcnt(8)
	s_waitcnt lgkmcnt(0)
	s_setprio 1
	s_barrier
	v_mfma_f32_16x16x32_bf16 v[60:63], v[132:135], v[188:191], v[60:63]
	v_mfma_f32_16x16x32_bf16 v[56:59], v[160:163], v[188:191], v[56:59]
	v_mfma_f32_16x16x32_bf16 v[44:47], v[132:135], v[196:199], v[44:47]
	v_mfma_f32_16x16x32_bf16 v[40:43], v[160:163], v[196:199], v[40:43]
	v_mfma_f32_16x16x32_bf16 v[28:31], v[132:135], v[204:207], v[28:31]
	v_mfma_f32_16x16x32_bf16 v[24:27], v[160:163], v[204:207], v[24:27]
	v_mfma_f32_16x16x32_bf16 v[12:15], v[132:135], v[212:215], v[12:15]
	v_mfma_f32_16x16x32_bf16 v[8:11], v[160:163], v[212:215], v[8:11]
	v_mfma_f32_16x16x32_bf16 v[60:63], v[156:159], v[192:195], v[60:63]
	v_mfma_f32_16x16x32_bf16 v[56:59], v[168:171], v[192:195], v[56:59]
	v_mfma_f32_16x16x32_bf16 v[44:47], v[156:159], v[200:203], v[44:47]
	v_mfma_f32_16x16x32_bf16 v[40:43], v[168:171], v[200:203], v[40:43]
	v_mfma_f32_16x16x32_bf16 v[28:31], v[156:159], v[208:211], v[28:31]
	v_mfma_f32_16x16x32_bf16 v[24:27], v[168:171], v[208:211], v[24:27]
	v_mfma_f32_16x16x32_bf16 v[12:15], v[156:159], v[216:219], v[12:15]
	v_mfma_f32_16x16x32_bf16 v[8:11], v[168:171], v[216:219], v[8:11]
	s_setprio 0
	s_setprio 1
	v_mfma_f32_16x16x32_bf16 v[52:55], v[172:175], v[188:191], v[52:55]
	v_mfma_f32_16x16x32_bf16 v[48:51], v[180:183], v[188:191], v[48:51]
	v_mfma_f32_16x16x32_bf16 v[36:39], v[172:175], v[196:199], v[36:39]
	v_mfma_f32_16x16x32_bf16 v[32:35], v[180:183], v[196:199], v[32:35]
	v_mfma_f32_16x16x32_bf16 v[20:23], v[172:175], v[204:207], v[20:23]
	v_mfma_f32_16x16x32_bf16 v[16:19], v[180:183], v[204:207], v[16:19]
	v_mfma_f32_16x16x32_bf16 v[4:7], v[172:175], v[212:215], v[4:7]
	v_mfma_f32_16x16x32_bf16 v[0:3], v[180:183], v[212:215], v[0:3]
	v_mfma_f32_16x16x32_bf16 v[52:55], v[176:179], v[192:195], v[52:55]
	v_mfma_f32_16x16x32_bf16 v[48:51], v[184:187], v[192:195], v[48:51]
	v_mfma_f32_16x16x32_bf16 v[36:39], v[176:179], v[200:203], v[36:39]
	v_mfma_f32_16x16x32_bf16 v[32:35], v[184:187], v[200:203], v[32:35]
	v_mfma_f32_16x16x32_bf16 v[20:23], v[176:179], v[208:211], v[20:23]
	v_mfma_f32_16x16x32_bf16 v[16:19], v[184:187], v[208:211], v[16:19]
	v_mfma_f32_16x16x32_bf16 v[4:7], v[176:179], v[216:219], v[4:7]
	v_mfma_f32_16x16x32_bf16 v[0:3], v[184:187], v[216:219], v[0:3]
	s_barrier
	s_setprio 0
	s_add_i32 s8, s78, 2
	s_add_u32 s36, s36, 0x100
	s_addc_u32 s37, s37, 0
	s_cmp_gt_u32 s78, 41
	s_mov_b32 s78, s8
	s_cbranch_scc1 .LBB0_903
	s_branch .LBB0_897
.LBB0_896:
	v_add_u32_e32 v167, s64, v165
	ds_read_b128 v[132:135], v167
	ds_read_b128 v[156:159], v167 offset:1024
	ds_read_b128 v[160:163], v167 offset:2048
	ds_read_b128 v[168:171], v167 offset:3072
	v_add_u32_e32 v167, s65, v165
	ds_read_b128 v[172:175], v167
	ds_read_b128 v[176:179], v167 offset:1024
	ds_read_b128 v[180:183], v167 offset:2048
	ds_read_b128 v[184:187], v167 offset:3072
	s_add_u32 s8, s46, 0x100
	s_addc_u32 s81, s47, 0
	s_and_b64 s[46:47], exec, s[44:45]
	s_cselect_b32 s47, s5, s81
	s_cselect_b32 s46, s4, s8
	s_add_u32 s8, s80, 0x100
	s_addc_u32 s79, s79, 0
	s_and_b64 s[44:45], exec, s[44:45]
	s_cselect_b32 s45, s21, s79
	s_cselect_b32 s44, s20, s8
	v_lshl_add_u64 v[220:221], v[128:129], 0, s[36:37]
	s_add_i32 m0, s51, 0xc000
	ds_read_b128 v[188:191], v166
	ds_read_b128 v[192:195], v166 offset:1024
	ds_read_b128 v[196:199], v166 offset:2048
	ds_read_b128 v[200:203], v166 offset:3072
	ds_read_b128 v[204:207], v166 offset:4096
	ds_read_b128 v[208:211], v166 offset:5120
	ds_read_b128 v[212:215], v166 offset:6144
	global_load_lds_dwordx4 v[220:221], off
	v_lshl_add_u64 v[220:221], v[130:131], 0, s[36:37]
	s_add_i32 m0, s51, 0xe000
	ds_read_b128 v[216:219], v166 offset:7168
	global_load_lds_dwordx4 v[220:221], off
	s_waitcnt vmcnt(8)
	s_waitcnt lgkmcnt(0)
	s_setprio 1
	s_barrier
	v_mfma_f32_16x16x32_bf16 v[124:127], v[132:135], v[188:191], v[124:127]
	v_mfma_f32_16x16x32_bf16 v[120:123], v[160:163], v[188:191], v[120:123]
	v_mfma_f32_16x16x32_bf16 v[108:111], v[132:135], v[196:199], v[108:111]
	v_mfma_f32_16x16x32_bf16 v[104:107], v[160:163], v[196:199], v[104:107]
	v_mfma_f32_16x16x32_bf16 v[92:95], v[132:135], v[204:207], v[92:95]
	v_mfma_f32_16x16x32_bf16 v[88:91], v[160:163], v[204:207], v[88:91]
	v_mfma_f32_16x16x32_bf16 v[76:79], v[132:135], v[212:215], v[76:79]
	v_mfma_f32_16x16x32_bf16 v[72:75], v[160:163], v[212:215], v[72:75]
	v_mfma_f32_16x16x32_bf16 v[124:127], v[156:159], v[192:195], v[124:127]
	v_mfma_f32_16x16x32_bf16 v[120:123], v[168:171], v[192:195], v[120:123]
	v_mfma_f32_16x16x32_bf16 v[108:111], v[156:159], v[200:203], v[108:111]
	v_mfma_f32_16x16x32_bf16 v[104:107], v[168:171], v[200:203], v[104:107]
	v_mfma_f32_16x16x32_bf16 v[92:95], v[156:159], v[208:211], v[92:95]
	v_mfma_f32_16x16x32_bf16 v[88:91], v[168:171], v[208:211], v[88:91]
	v_mfma_f32_16x16x32_bf16 v[76:79], v[156:159], v[216:219], v[76:79]
	v_mfma_f32_16x16x32_bf16 v[72:75], v[168:171], v[216:219], v[72:75]
	s_setprio 0
	s_setprio 1
	v_mfma_f32_16x16x32_bf16 v[116:119], v[172:175], v[188:191], v[116:119]
	v_mfma_f32_16x16x32_bf16 v[112:115], v[180:183], v[188:191], v[112:115]
	v_mfma_f32_16x16x32_bf16 v[100:103], v[172:175], v[196:199], v[100:103]
	v_mfma_f32_16x16x32_bf16 v[96:99], v[180:183], v[196:199], v[96:99]
	v_mfma_f32_16x16x32_bf16 v[84:87], v[172:175], v[204:207], v[84:87]
	v_mfma_f32_16x16x32_bf16 v[80:83], v[180:183], v[204:207], v[80:83]
	v_mfma_f32_16x16x32_bf16 v[68:71], v[172:175], v[212:215], v[68:71]
	v_mfma_f32_16x16x32_bf16 v[64:67], v[180:183], v[212:215], v[64:67]
	v_mfma_f32_16x16x32_bf16 v[116:119], v[176:179], v[192:195], v[116:119]
	v_mfma_f32_16x16x32_bf16 v[112:115], v[184:187], v[192:195], v[112:115]
	v_mfma_f32_16x16x32_bf16 v[100:103], v[176:179], v[200:203], v[100:103]
	v_mfma_f32_16x16x32_bf16 v[96:99], v[184:187], v[200:203], v[96:99]
	v_mfma_f32_16x16x32_bf16 v[84:87], v[176:179], v[208:211], v[84:87]
	v_mfma_f32_16x16x32_bf16 v[80:83], v[184:187], v[208:211], v[80:83]
	v_mfma_f32_16x16x32_bf16 v[68:71], v[176:179], v[216:219], v[68:71]
	v_mfma_f32_16x16x32_bf16 v[64:67], v[184:187], v[216:219], v[64:67]
	s_barrier
	s_setprio 0
	s_add_i32 s8, s64, s50
	s_mov_b32 m0, s8
	ds_read_b128 v[188:191], v166 offset:16384
	ds_read_b128 v[192:195], v166 offset:17408
	ds_read_b128 v[196:199], v166 offset:18432
	global_load_lds_dwordx4 v138, s[44:45]
	s_add_i32 m0, s8, 0x2000
	ds_read_b128 v[200:203], v166 offset:19456
	global_load_lds_dwordx4 v142, s[44:45]
	s_add_u32 s44, s44, 0xb0000
	s_addc_u32 s45, s45, 0
	s_add_i32 s8, s65, s50
	s_mov_b32 m0, s8
	ds_read_b128 v[204:207], v166 offset:20480
	global_load_lds_dwordx4 v138, s[44:45]
	s_add_i32 m0, s8, 0x2000
	ds_read_b128 v[208:211], v166 offset:21504
	global_load_lds_dwordx4 v142, s[44:45]
	s_mov_b32 m0, s51
	ds_read_b128 v[212:215], v166 offset:22528
	global_load_lds_dwordx4 v136, s[46:47]
	s_mov_b32 m0, s52
	ds_read_b128 v[216:219], v166 offset:23552
	global_load_lds_dwordx4 v140, s[46:47]
	s_waitcnt vmcnt(8)
	s_waitcnt lgkmcnt(0)
	s_setprio 1
	s_barrier
	v_mfma_f32_16x16x32_bf16 v[60:63], v[132:135], v[188:191], v[60:63]
	v_mfma_f32_16x16x32_bf16 v[56:59], v[160:163], v[188:191], v[56:59]
	v_mfma_f32_16x16x32_bf16 v[44:47], v[132:135], v[196:199], v[44:47]
	v_mfma_f32_16x16x32_bf16 v[40:43], v[160:163], v[196:199], v[40:43]
	v_mfma_f32_16x16x32_bf16 v[28:31], v[132:135], v[204:207], v[28:31]
	v_mfma_f32_16x16x32_bf16 v[24:27], v[160:163], v[204:207], v[24:27]
	v_mfma_f32_16x16x32_bf16 v[12:15], v[132:135], v[212:215], v[12:15]
	v_mfma_f32_16x16x32_bf16 v[8:11], v[160:163], v[212:215], v[8:11]
	v_mfma_f32_16x16x32_bf16 v[60:63], v[156:159], v[192:195], v[60:63]
	v_mfma_f32_16x16x32_bf16 v[56:59], v[168:171], v[192:195], v[56:59]
	v_mfma_f32_16x16x32_bf16 v[44:47], v[156:159], v[200:203], v[44:47]
	v_mfma_f32_16x16x32_bf16 v[40:43], v[168:171], v[200:203], v[40:43]
	v_mfma_f32_16x16x32_bf16 v[28:31], v[156:159], v[208:211], v[28:31]
	v_mfma_f32_16x16x32_bf16 v[24:27], v[168:171], v[208:211], v[24:27]
	v_mfma_f32_16x16x32_bf16 v[12:15], v[156:159], v[216:219], v[12:15]
	v_mfma_f32_16x16x32_bf16 v[8:11], v[168:171], v[216:219], v[8:11]
	s_setprio 0
	s_setprio 1
	v_mfma_f32_16x16x32_bf16 v[52:55], v[172:175], v[188:191], v[52:55]
	v_mfma_f32_16x16x32_bf16 v[48:51], v[180:183], v[188:191], v[48:51]
	v_mfma_f32_16x16x32_bf16 v[36:39], v[172:175], v[196:199], v[36:39]
	v_mfma_f32_16x16x32_bf16 v[32:35], v[180:183], v[196:199], v[32:35]
	v_mfma_f32_16x16x32_bf16 v[20:23], v[172:175], v[204:207], v[20:23]
	v_mfma_f32_16x16x32_bf16 v[16:19], v[180:183], v[204:207], v[16:19]
	v_mfma_f32_16x16x32_bf16 v[4:7], v[172:175], v[212:215], v[4:7]
	v_mfma_f32_16x16x32_bf16 v[0:3], v[180:183], v[212:215], v[0:3]
	v_mfma_f32_16x16x32_bf16 v[52:55], v[176:179], v[192:195], v[52:55]
	v_mfma_f32_16x16x32_bf16 v[48:51], v[184:187], v[192:195], v[48:51]
	v_mfma_f32_16x16x32_bf16 v[36:39], v[176:179], v[200:203], v[36:39]
	v_mfma_f32_16x16x32_bf16 v[32:35], v[184:187], v[200:203], v[32:35]
	v_mfma_f32_16x16x32_bf16 v[20:23], v[176:179], v[208:211], v[20:23]
	v_mfma_f32_16x16x32_bf16 v[16:19], v[184:187], v[208:211], v[16:19]
	v_mfma_f32_16x16x32_bf16 v[4:7], v[176:179], v[216:219], v[4:7]
	v_mfma_f32_16x16x32_bf16 v[0:3], v[184:187], v[216:219], v[0:3]
	s_barrier
	s_setprio 0
	s_add_i32 s8, 0, 0x18000
	v_add_u32_e32 v167, s8, v165
	s_add_i32 s79, 0, 0x1c000
	ds_read_b128 v[132:135], v167
	ds_read_b128 v[156:159], v167 offset:1024
	ds_read_b128 v[160:163], v167 offset:2048
	ds_read_b128 v[168:171], v167 offset:3072
	v_add_u32_e32 v167, s79, v165
	ds_read_b128 v[172:175], v167
	ds_read_b128 v[176:179], v167 offset:1024
	ds_read_b128 v[180:183], v167 offset:2048
	ds_read_b128 v[184:187], v167 offset:3072
	s_add_u32 s44, s46, 0xb0000
	s_addc_u32 s45, s47, 0
	s_mov_b32 m0, s53
	ds_read_b128 v[188:191], v166 offset:32768
	ds_read_b128 v[192:195], v166 offset:33792
	ds_read_b128 v[196:199], v166 offset:34816
	ds_read_b128 v[200:203], v166 offset:35840
	ds_read_b128 v[204:207], v166 offset:36864
	ds_read_b128 v[208:211], v166 offset:37888
	ds_read_b128 v[212:215], v166 offset:38912
	global_load_lds_dwordx4 v136, s[44:45]
	s_mov_b32 m0, s54
	ds_read_b128 v[216:219], v166 offset:39936
	global_load_lds_dwordx4 v140, s[44:45]
	s_waitcnt vmcnt(8)
	s_waitcnt lgkmcnt(0)
	s_setprio 1
	s_barrier
	v_mfma_f32_16x16x32_bf16 v[124:127], v[132:135], v[188:191], v[124:127]
	v_mfma_f32_16x16x32_bf16 v[120:123], v[160:163], v[188:191], v[120:123]
	v_mfma_f32_16x16x32_bf16 v[108:111], v[132:135], v[196:199], v[108:111]
	v_mfma_f32_16x16x32_bf16 v[104:107], v[160:163], v[196:199], v[104:107]
	v_mfma_f32_16x16x32_bf16 v[92:95], v[132:135], v[204:207], v[92:95]
	v_mfma_f32_16x16x32_bf16 v[88:91], v[160:163], v[204:207], v[88:91]
	v_mfma_f32_16x16x32_bf16 v[76:79], v[132:135], v[212:215], v[76:79]
	v_mfma_f32_16x16x32_bf16 v[72:75], v[160:163], v[212:215], v[72:75]
	v_mfma_f32_16x16x32_bf16 v[124:127], v[156:159], v[192:195], v[124:127]
	v_mfma_f32_16x16x32_bf16 v[120:123], v[168:171], v[192:195], v[120:123]
	v_mfma_f32_16x16x32_bf16 v[108:111], v[156:159], v[200:203], v[108:111]
	v_mfma_f32_16x16x32_bf16 v[104:107], v[168:171], v[200:203], v[104:107]
	v_mfma_f32_16x16x32_bf16 v[92:95], v[156:159], v[208:211], v[92:95]
	v_mfma_f32_16x16x32_bf16 v[88:91], v[168:171], v[208:211], v[88:91]
	v_mfma_f32_16x16x32_bf16 v[76:79], v[156:159], v[216:219], v[76:79]
	v_mfma_f32_16x16x32_bf16 v[72:75], v[168:171], v[216:219], v[72:75]
	s_setprio 0
	s_setprio 1
	v_mfma_f32_16x16x32_bf16 v[116:119], v[172:175], v[188:191], v[116:119]
	v_mfma_f32_16x16x32_bf16 v[112:115], v[180:183], v[188:191], v[112:115]
	v_mfma_f32_16x16x32_bf16 v[100:103], v[172:175], v[196:199], v[100:103]
	v_mfma_f32_16x16x32_bf16 v[96:99], v[180:183], v[196:199], v[96:99]
	v_mfma_f32_16x16x32_bf16 v[84:87], v[172:175], v[204:207], v[84:87]
	v_mfma_f32_16x16x32_bf16 v[80:83], v[180:183], v[204:207], v[80:83]
	v_mfma_f32_16x16x32_bf16 v[68:71], v[172:175], v[212:215], v[68:71]
	v_mfma_f32_16x16x32_bf16 v[64:67], v[180:183], v[212:215], v[64:67]
	v_mfma_f32_16x16x32_bf16 v[116:119], v[176:179], v[192:195], v[116:119]
	v_mfma_f32_16x16x32_bf16 v[112:115], v[184:187], v[192:195], v[112:115]
	v_mfma_f32_16x16x32_bf16 v[100:103], v[176:179], v[200:203], v[100:103]
	v_mfma_f32_16x16x32_bf16 v[96:99], v[184:187], v[200:203], v[96:99]
	v_mfma_f32_16x16x32_bf16 v[84:87], v[176:179], v[208:211], v[84:87]
	v_mfma_f32_16x16x32_bf16 v[80:83], v[184:187], v[208:211], v[80:83]
	v_mfma_f32_16x16x32_bf16 v[68:71], v[176:179], v[216:219], v[68:71]
	v_mfma_f32_16x16x32_bf16 v[64:67], v[184:187], v[216:219], v[64:67]
	s_barrier
	s_setprio 0
	s_add_i32 s8, s8, s50
	s_mov_b32 m0, s8
	ds_read_b128 v[188:191], v166 offset:49152
	ds_read_b128 v[192:195], v166 offset:50176
	ds_read_b128 v[196:199], v166 offset:51200
	global_load_lds_dwordx4 v138, s[40:41]
	s_add_i32 m0, s8, 0x2000
	ds_read_b128 v[200:203], v166 offset:52224
	global_load_lds_dwordx4 v142, s[40:41]
	s_add_u32 s40, s40, 0xb0000
	s_addc_u32 s41, s41, 0
	s_add_i32 s8, s79, s50
	s_mov_b32 m0, s8
	ds_read_b128 v[204:207], v166 offset:53248
	global_load_lds_dwordx4 v138, s[40:41]
	s_add_i32 m0, s8, 0x2000
	ds_read_b128 v[208:211], v166 offset:54272
	global_load_lds_dwordx4 v142, s[40:41]
	s_mov_b32 m0, s60
	ds_read_b128 v[212:215], v166 offset:55296
	global_load_lds_dwordx4 v136, s[38:39]
	s_mov_b32 m0, s61
	ds_read_b128 v[216:219], v166 offset:56320
	global_load_lds_dwordx4 v140, s[38:39]
	s_waitcnt vmcnt(8)
	s_waitcnt lgkmcnt(0)
	s_setprio 1
	s_barrier
	v_mfma_f32_16x16x32_bf16 v[60:63], v[132:135], v[188:191], v[60:63]
	v_mfma_f32_16x16x32_bf16 v[56:59], v[160:163], v[188:191], v[56:59]
	v_mfma_f32_16x16x32_bf16 v[44:47], v[132:135], v[196:199], v[44:47]
	v_mfma_f32_16x16x32_bf16 v[40:43], v[160:163], v[196:199], v[40:43]
	v_mfma_f32_16x16x32_bf16 v[28:31], v[132:135], v[204:207], v[28:31]
	v_mfma_f32_16x16x32_bf16 v[24:27], v[160:163], v[204:207], v[24:27]
	v_mfma_f32_16x16x32_bf16 v[12:15], v[132:135], v[212:215], v[12:15]
	v_mfma_f32_16x16x32_bf16 v[8:11], v[160:163], v[212:215], v[8:11]
	v_mfma_f32_16x16x32_bf16 v[60:63], v[156:159], v[192:195], v[60:63]
	v_mfma_f32_16x16x32_bf16 v[56:59], v[168:171], v[192:195], v[56:59]
	v_mfma_f32_16x16x32_bf16 v[44:47], v[156:159], v[200:203], v[44:47]
	v_mfma_f32_16x16x32_bf16 v[40:43], v[168:171], v[200:203], v[40:43]
	v_mfma_f32_16x16x32_bf16 v[28:31], v[156:159], v[208:211], v[28:31]
	v_mfma_f32_16x16x32_bf16 v[24:27], v[168:171], v[208:211], v[24:27]
	v_mfma_f32_16x16x32_bf16 v[12:15], v[156:159], v[216:219], v[12:15]
	v_mfma_f32_16x16x32_bf16 v[8:11], v[168:171], v[216:219], v[8:11]
	s_setprio 0
	s_setprio 1
	v_mfma_f32_16x16x32_bf16 v[52:55], v[172:175], v[188:191], v[52:55]
	v_mfma_f32_16x16x32_bf16 v[48:51], v[180:183], v[188:191], v[48:51]
	v_mfma_f32_16x16x32_bf16 v[36:39], v[172:175], v[196:199], v[36:39]
	v_mfma_f32_16x16x32_bf16 v[32:35], v[180:183], v[196:199], v[32:35]
	v_mfma_f32_16x16x32_bf16 v[20:23], v[172:175], v[204:207], v[20:23]
	v_mfma_f32_16x16x32_bf16 v[16:19], v[180:183], v[204:207], v[16:19]
	v_mfma_f32_16x16x32_bf16 v[4:7], v[172:175], v[212:215], v[4:7]
	v_mfma_f32_16x16x32_bf16 v[0:3], v[180:183], v[212:215], v[0:3]
	v_mfma_f32_16x16x32_bf16 v[52:55], v[176:179], v[192:195], v[52:55]
	v_mfma_f32_16x16x32_bf16 v[48:51], v[184:187], v[192:195], v[48:51]
	v_mfma_f32_16x16x32_bf16 v[36:39], v[176:179], v[200:203], v[36:39]
	v_mfma_f32_16x16x32_bf16 v[32:35], v[184:187], v[200:203], v[32:35]
	v_mfma_f32_16x16x32_bf16 v[20:23], v[176:179], v[208:211], v[20:23]
	v_mfma_f32_16x16x32_bf16 v[16:19], v[184:187], v[208:211], v[16:19]
	v_mfma_f32_16x16x32_bf16 v[4:7], v[176:179], v[216:219], v[4:7]
	v_mfma_f32_16x16x32_bf16 v[0:3], v[184:187], v[216:219], v[0:3]
	s_barrier
	s_setprio 0
	s_add_i32 s8, s78, 2
	s_add_u32 s36, s36, 0x100
	s_addc_u32 s37, s37, 0
	s_cmp_gt_u32 s78, 41
	s_mov_b32 s78, s8
	s_cbranch_scc1 .LBB0_903

.LBB0_995:
	ds_read_b128 v[0:3], v145
	ds_read_b128 v[4:7], v145 offset:1024
	ds_read_b128 v[8:11], v145 offset:2048
	ds_read_b128 v[12:15], v145 offset:3072
	ds_read_b128 v[16:19], v146
	ds_read_b128 v[20:23], v146 offset:1024
	ds_read_b128 v[24:27], v146 offset:2048
	ds_read_b128 v[28:31], v146 offset:3072
	s_ashr_i32 s25, s24, 31
	s_lshl_b64 s[28:29], s[24:25], 17
	s_add_u32 s28, s44, s28
	s_addc_u32 s29, s45, s29
	s_and_b64 s[30:31], s[0:1], exec
	s_cselect_b32 s43, s29, s37
	s_cselect_b32 s42, s28, s36
	s_ashr_i32 s23, s22, 31
	s_lshl_b64 s[30:31], s[22:23], 17
	s_add_u32 s30, s46, s30
	s_addc_u32 s31, s47, s31
	s_and_b64 s[40:41], s[0:1], exec
	s_cselect_b32 s41, s31, s39
	s_cselect_b32 s40, s30, s38
	s_add_u32 s64, s36, 0x10080
	s_addc_u32 s65, s37, 0
	s_mov_b32 m0, s56
	ds_read_b128 v[32:35], v147
	ds_read_b128 v[36:39], v147 offset:1024
	ds_read_b128 v[40:43], v147 offset:2048
	ds_read_b128 v[44:47], v147 offset:3072
	ds_read_b128 v[48:51], v147 offset:4096
	ds_read_b128 v[52:55], v147 offset:5120
	ds_read_b128 v[56:59], v147 offset:6144
	ds_read_b128 v[60:63], v147 offset:7168
	global_load_lds_dwordx4 v128, s[64:65]
	s_mov_b32 m0, s57
	s_nop 0
	global_load_lds_dwordx4 v132, s[64:65]
	s_waitcnt vmcnt(8)
	s_waitcnt lgkmcnt(0)
	s_setprio 1
	s_barrier
	v_mfma_f32_16x16x32_bf16 v[64:67], v[0:3], v[32:35], 0
	v_mfma_f32_16x16x32_bf16 v[68:71], v[8:11], v[32:35], 0
	v_mfma_f32_16x16x32_bf16 v[72:75], v[0:3], v[40:43], 0
	v_mfma_f32_16x16x32_bf16 v[76:79], v[8:11], v[40:43], 0
	v_mfma_f32_16x16x32_bf16 v[80:83], v[0:3], v[48:51], 0
	v_mfma_f32_16x16x32_bf16 v[84:87], v[8:11], v[48:51], 0
	v_mfma_f32_16x16x32_bf16 v[88:91], v[0:3], v[56:59], 0
	v_mfma_f32_16x16x32_bf16 v[92:95], v[8:11], v[56:59], 0
	v_mfma_f32_16x16x32_bf16 v[64:67], v[4:7], v[36:39], v[64:67]
	v_mfma_f32_16x16x32_bf16 v[68:71], v[12:15], v[36:39], v[68:71]
	v_mfma_f32_16x16x32_bf16 v[72:75], v[4:7], v[44:47], v[72:75]
	v_mfma_f32_16x16x32_bf16 v[76:79], v[12:15], v[44:47], v[76:79]
	v_mfma_f32_16x16x32_bf16 v[80:83], v[4:7], v[52:55], v[80:83]
	v_mfma_f32_16x16x32_bf16 v[84:87], v[12:15], v[52:55], v[84:87]
	v_mfma_f32_16x16x32_bf16 v[88:91], v[4:7], v[60:63], v[88:91]
	v_mfma_f32_16x16x32_bf16 v[92:95], v[12:15], v[60:63], v[92:95]
	s_setprio 0
	s_setprio 1
	v_mfma_f32_16x16x32_bf16 v[96:99], v[16:19], v[32:35], 0
	v_mfma_f32_16x16x32_bf16 v[32:35], v[24:27], v[32:35], 0
	v_mfma_f32_16x16x32_bf16 v[96:99], v[20:23], v[36:39], v[96:99]
	v_mfma_f32_16x16x32_bf16 v[32:35], v[28:31], v[36:39], v[32:35]
	v_mfma_f32_16x16x32_bf16 v[36:39], v[16:19], v[40:43], 0
	v_mfma_f32_16x16x32_bf16 v[40:43], v[24:27], v[40:43], 0
	v_mfma_f32_16x16x32_bf16 v[36:39], v[20:23], v[44:47], v[36:39]
	v_mfma_f32_16x16x32_bf16 v[40:43], v[28:31], v[44:47], v[40:43]
	v_mfma_f32_16x16x32_bf16 v[44:47], v[16:19], v[48:51], 0
	v_mfma_f32_16x16x32_bf16 v[48:51], v[24:27], v[48:51], 0
	v_mfma_f32_16x16x32_bf16 v[44:47], v[20:23], v[52:55], v[44:47]
	v_mfma_f32_16x16x32_bf16 v[48:51], v[28:31], v[52:55], v[48:51]
	v_mfma_f32_16x16x32_bf16 v[52:55], v[16:19], v[56:59], 0
	v_mfma_f32_16x16x32_bf16 v[56:59], v[24:27], v[56:59], 0
	v_mfma_f32_16x16x32_bf16 v[52:55], v[20:23], v[60:63], v[52:55]
	v_mfma_f32_16x16x32_bf16 v[56:59], v[28:31], v[60:63], v[56:59]
	s_barrier
	s_setprio 0
	v_lshl_add_u64 v[214:215], s[38:39], 0, v[130:131]
	s_mov_b32 m0, s58
	v_lshl_add_u64 v[150:151], v[214:215], 0, s[18:19]
	v_lshl_add_u64 v[216:217], s[38:39], 0, v[134:135]
	s_add_u32 s64, s38, 0x10100
	ds_read_b128 v[60:63], v147 offset:16384
	ds_read_b128 v[100:103], v147 offset:17408
	ds_read_b128 v[104:107], v147 offset:18432
	ds_read_b128 v[108:111], v147 offset:19456
	ds_read_b128 v[112:115], v147 offset:20480
	ds_read_b128 v[116:119], v147 offset:21504
	ds_read_b128 v[120:123], v147 offset:22528
	ds_read_b128 v[124:127], v147 offset:23552
	global_load_lds_dwordx4 v[150:151], off
	v_lshl_add_u64 v[150:151], v[216:217], 0, s[18:19]
	s_mov_b32 m0, s59
	s_addc_u32 s65, s39, 0
	global_load_lds_dwordx4 v[150:151], off
	s_mov_b32 m0, s60
	v_lshl_add_u64 v[218:219], s[36:37], 0, v[128:129]
	global_load_lds_dwordx4 v130, s[64:65]
	s_mov_b32 m0, s61
	v_lshl_add_u64 v[220:221], s[36:37], 0, v[132:133]
	global_load_lds_dwordx4 v134, s[64:65]
	v_lshl_add_u64 v[150:151], v[218:219], 0, s[18:19]
	s_mov_b32 m0, s49
	s_nop 0
	global_load_lds_dwordx4 v[150:151], off
	v_lshl_add_u64 v[150:151], v[220:221], 0, s[18:19]
	s_mov_b32 m0, s50
	s_nop 0
	global_load_lds_dwordx4 v[150:151], off
	s_waitcnt vmcnt(8)
	s_waitcnt lgkmcnt(0)
	s_setprio 1
	s_barrier
	v_mfma_f32_16x16x32_bf16 v[150:153], v[0:3], v[60:63], 0
	v_mfma_f32_16x16x32_bf16 v[158:161], v[0:3], v[104:107], 0
	v_mfma_f32_16x16x32_bf16 v[166:169], v[0:3], v[112:115], 0
	v_mfma_f32_16x16x32_bf16 v[0:3], v[0:3], v[120:123], 0
	v_mfma_f32_16x16x32_bf16 v[150:153], v[4:7], v[100:103], v[150:153]
	v_mfma_f32_16x16x32_bf16 v[158:161], v[4:7], v[108:111], v[158:161]
	v_mfma_f32_16x16x32_bf16 v[166:169], v[4:7], v[116:119], v[166:169]
	v_mfma_f32_16x16x32_bf16 v[0:3], v[4:7], v[124:127], v[0:3]
	v_mfma_f32_16x16x32_bf16 v[4:7], v[8:11], v[120:123], 0
	v_mfma_f32_16x16x32_bf16 v[154:157], v[8:11], v[60:63], 0
	v_mfma_f32_16x16x32_bf16 v[162:165], v[8:11], v[104:107], 0
	v_mfma_f32_16x16x32_bf16 v[170:173], v[8:11], v[112:115], 0
	v_mfma_f32_16x16x32_bf16 v[4:7], v[12:15], v[124:127], v[4:7]
	v_mfma_f32_16x16x32_bf16 v[154:157], v[12:15], v[100:103], v[154:157]
	v_mfma_f32_16x16x32_bf16 v[162:165], v[12:15], v[108:111], v[162:165]
	v_mfma_f32_16x16x32_bf16 v[170:173], v[12:15], v[116:119], v[170:173]
	s_setprio 0
	s_setprio 1
	v_mfma_f32_16x16x32_bf16 v[8:11], v[16:19], v[60:63], 0
	v_mfma_f32_16x16x32_bf16 v[12:15], v[24:27], v[60:63], 0
	v_mfma_f32_16x16x32_bf16 v[8:11], v[20:23], v[100:103], v[8:11]
	v_mfma_f32_16x16x32_bf16 v[12:15], v[28:31], v[100:103], v[12:15]
	v_mfma_f32_16x16x32_bf16 v[60:63], v[16:19], v[104:107], 0
	v_mfma_f32_16x16x32_bf16 v[100:103], v[24:27], v[104:107], 0
	v_mfma_f32_16x16x32_bf16 v[104:107], v[16:19], v[112:115], 0
	v_mfma_f32_16x16x32_bf16 v[16:19], v[16:19], v[120:123], 0
	v_mfma_f32_16x16x32_bf16 v[60:63], v[20:23], v[108:111], v[60:63]
	v_mfma_f32_16x16x32_bf16 v[100:103], v[28:31], v[108:111], v[100:103]
	v_mfma_f32_16x16x32_bf16 v[104:107], v[20:23], v[116:119], v[104:107]
	v_mfma_f32_16x16x32_bf16 v[108:111], v[24:27], v[112:115], 0
	v_mfma_f32_16x16x32_bf16 v[16:19], v[20:23], v[124:127], v[16:19]
	v_mfma_f32_16x16x32_bf16 v[20:23], v[24:27], v[120:123], 0
	v_mfma_f32_16x16x32_bf16 v[108:111], v[28:31], v[116:119], v[108:111]
	v_mfma_f32_16x16x32_bf16 v[20:23], v[28:31], v[124:127], v[20:23]
	s_barrier
	s_setprio 0
	s_add_i32 s25, 0, 0x1c000
	v_add_u32_e32 v149, s25, v144
	ds_read_b128 v[24:27], v148
	ds_read_b128 v[28:31], v148 offset:1024
	ds_read_b128 v[112:115], v148 offset:2048
	ds_read_b128 v[116:119], v148 offset:3072
	ds_read_b128 v[120:123], v149
	ds_read_b128 v[124:127], v149 offset:1024
	ds_read_b128 v[174:177], v149 offset:2048
	ds_read_b128 v[178:181], v149 offset:3072
	s_add_u32 s64, s36, 0x10100
	s_addc_u32 s65, s37, 0
	s_mov_b32 m0, s51
	ds_read_b128 v[182:185], v147 offset:32768
	ds_read_b128 v[186:189], v147 offset:33792
	ds_read_b128 v[190:193], v147 offset:34816
	ds_read_b128 v[194:197], v147 offset:35840
	ds_read_b128 v[198:201], v147 offset:36864
	ds_read_b128 v[202:205], v147 offset:37888
	ds_read_b128 v[206:209], v147 offset:38912
	ds_read_b128 v[210:213], v147 offset:39936
	global_load_lds_dwordx4 v128, s[64:65]
	s_mov_b32 m0, s52
	s_nop 0
	global_load_lds_dwordx4 v132, s[64:65]
	s_waitcnt vmcnt(8)
	s_waitcnt lgkmcnt(0)
	s_setprio 1
	s_barrier
	v_mfma_f32_16x16x32_bf16 v[64:67], v[24:27], v[182:185], v[64:67]
	v_mfma_f32_16x16x32_bf16 v[68:71], v[112:115], v[182:185], v[68:71]
	v_mfma_f32_16x16x32_bf16 v[72:75], v[24:27], v[190:193], v[72:75]
	v_mfma_f32_16x16x32_bf16 v[76:79], v[112:115], v[190:193], v[76:79]
	v_mfma_f32_16x16x32_bf16 v[80:83], v[24:27], v[198:201], v[80:83]
	v_mfma_f32_16x16x32_bf16 v[84:87], v[112:115], v[198:201], v[84:87]
	v_mfma_f32_16x16x32_bf16 v[88:91], v[24:27], v[206:209], v[88:91]
	v_mfma_f32_16x16x32_bf16 v[92:95], v[112:115], v[206:209], v[92:95]
	v_mfma_f32_16x16x32_bf16 v[64:67], v[28:31], v[186:189], v[64:67]
	v_mfma_f32_16x16x32_bf16 v[68:71], v[116:119], v[186:189], v[68:71]
	v_mfma_f32_16x16x32_bf16 v[72:75], v[28:31], v[194:197], v[72:75]
	v_mfma_f32_16x16x32_bf16 v[76:79], v[116:119], v[194:197], v[76:79]
	v_mfma_f32_16x16x32_bf16 v[80:83], v[28:31], v[202:205], v[80:83]
	v_mfma_f32_16x16x32_bf16 v[84:87], v[116:119], v[202:205], v[84:87]
	v_mfma_f32_16x16x32_bf16 v[88:91], v[28:31], v[210:213], v[88:91]
	v_mfma_f32_16x16x32_bf16 v[92:95], v[116:119], v[210:213], v[92:95]
	s_setprio 0
	s_setprio 1
	v_mfma_f32_16x16x32_bf16 v[96:99], v[120:123], v[182:185], v[96:99]
	v_mfma_f32_16x16x32_bf16 v[32:35], v[174:177], v[182:185], v[32:35]
	v_mfma_f32_16x16x32_bf16 v[36:39], v[120:123], v[190:193], v[36:39]
	v_mfma_f32_16x16x32_bf16 v[40:43], v[174:177], v[190:193], v[40:43]
	v_mfma_f32_16x16x32_bf16 v[44:47], v[120:123], v[198:201], v[44:47]
	v_mfma_f32_16x16x32_bf16 v[48:51], v[174:177], v[198:201], v[48:51]
	v_mfma_f32_16x16x32_bf16 v[52:55], v[120:123], v[206:209], v[52:55]
	v_mfma_f32_16x16x32_bf16 v[56:59], v[174:177], v[206:209], v[56:59]
	v_mfma_f32_16x16x32_bf16 v[96:99], v[124:127], v[186:189], v[96:99]
	v_mfma_f32_16x16x32_bf16 v[32:35], v[178:181], v[186:189], v[32:35]
	v_mfma_f32_16x16x32_bf16 v[36:39], v[124:127], v[194:197], v[36:39]
	v_mfma_f32_16x16x32_bf16 v[40:43], v[178:181], v[194:197], v[40:43]
	v_mfma_f32_16x16x32_bf16 v[44:47], v[124:127], v[202:205], v[44:47]
	v_mfma_f32_16x16x32_bf16 v[48:51], v[178:181], v[202:205], v[48:51]
	v_mfma_f32_16x16x32_bf16 v[52:55], v[124:127], v[210:213], v[52:55]
	v_mfma_f32_16x16x32_bf16 v[56:59], v[178:181], v[210:213], v[56:59]
	s_barrier
	s_setprio 0
	s_add_i32 s63, s62, s48
	s_add_i32 s23, s63, 0x2000
	v_lshl_add_u64 v[214:215], v[214:215], 0, s[20:21]
	s_mov_b32 m0, s63
	s_add_u32 s38, s38, 0x10180
	ds_read_b128 v[182:185], v147 offset:49152
	ds_read_b128 v[186:189], v147 offset:50176
	ds_read_b128 v[190:193], v147 offset:51200
	ds_read_b128 v[194:197], v147 offset:52224
	ds_read_b128 v[198:201], v147 offset:53248
	ds_read_b128 v[202:205], v147 offset:54272
	ds_read_b128 v[206:209], v147 offset:55296
	ds_read_b128 v[210:213], v147 offset:56320
	global_load_lds_dwordx4 v[214:215], off
	v_lshl_add_u64 v[214:215], v[216:217], 0, s[20:21]
	s_mov_b32 m0, s23
	s_addc_u32 s39, s39, 0
	s_add_i32 s25, s25, s48
	global_load_lds_dwordx4 v[214:215], off
	s_mov_b32 m0, s25
	s_nop 0
	global_load_lds_dwordx4 v130, s[38:39]
	v_lshl_add_u64 v[214:215], s[38:39], 0, v[134:135]
	s_add_i32 s38, s25, 0x2000
	s_mov_b32 m0, s38
	s_nop 0
	global_load_lds_dwordx4 v[214:215], off
	v_lshl_add_u64 v[214:215], v[218:219], 0, s[20:21]
	s_mov_b32 m0, s53
	s_nop 0
	global_load_lds_dwordx4 v[214:215], off
	v_lshl_add_u64 v[214:215], v[220:221], 0, s[20:21]
	s_mov_b32 m0, s54
	s_nop 0
	global_load_lds_dwordx4 v[214:215], off
	s_waitcnt vmcnt(8)
	s_waitcnt lgkmcnt(0)
	s_setprio 1
	s_barrier
	v_mfma_f32_16x16x32_bf16 v[0:3], v[24:27], v[206:209], v[0:3]
	v_mfma_f32_16x16x32_bf16 v[4:7], v[112:115], v[206:209], v[4:7]
	v_mfma_f32_16x16x32_bf16 v[150:153], v[24:27], v[182:185], v[150:153]
	v_mfma_f32_16x16x32_bf16 v[154:157], v[112:115], v[182:185], v[154:157]
	v_mfma_f32_16x16x32_bf16 v[158:161], v[24:27], v[190:193], v[158:161]
	v_mfma_f32_16x16x32_bf16 v[162:165], v[112:115], v[190:193], v[162:165]
	v_mfma_f32_16x16x32_bf16 v[166:169], v[24:27], v[198:201], v[166:169]
	v_mfma_f32_16x16x32_bf16 v[170:173], v[112:115], v[198:201], v[170:173]
	v_mfma_f32_16x16x32_bf16 v[0:3], v[28:31], v[210:213], v[0:3]
	v_mfma_f32_16x16x32_bf16 v[4:7], v[116:119], v[210:213], v[4:7]
	v_mfma_f32_16x16x32_bf16 v[150:153], v[28:31], v[186:189], v[150:153]
	v_mfma_f32_16x16x32_bf16 v[154:157], v[116:119], v[186:189], v[154:157]
	v_mfma_f32_16x16x32_bf16 v[158:161], v[28:31], v[194:197], v[158:161]
	v_mfma_f32_16x16x32_bf16 v[162:165], v[116:119], v[194:197], v[162:165]
	v_mfma_f32_16x16x32_bf16 v[166:169], v[28:31], v[202:205], v[166:169]
	v_mfma_f32_16x16x32_bf16 v[170:173], v[116:119], v[202:205], v[170:173]
	s_setprio 0
	s_setprio 1
	v_mfma_f32_16x16x32_bf16 v[8:11], v[120:123], v[182:185], v[8:11]
	v_mfma_f32_16x16x32_bf16 v[12:15], v[174:177], v[182:185], v[12:15]
	v_mfma_f32_16x16x32_bf16 v[24:27], v[120:123], v[190:193], v[60:63]
	v_mfma_f32_16x16x32_bf16 v[28:31], v[174:177], v[190:193], v[100:103]
	v_mfma_f32_16x16x32_bf16 v[60:63], v[120:123], v[198:201], v[104:107]
	v_mfma_f32_16x16x32_bf16 v[100:103], v[174:177], v[198:201], v[108:111]
	v_mfma_f32_16x16x32_bf16 v[16:19], v[120:123], v[206:209], v[16:19]
	v_mfma_f32_16x16x32_bf16 v[20:23], v[174:177], v[206:209], v[20:23]
	v_mfma_f32_16x16x32_bf16 v[8:11], v[124:127], v[186:189], v[8:11]
	v_mfma_f32_16x16x32_bf16 v[12:15], v[178:181], v[186:189], v[12:15]
	v_mfma_f32_16x16x32_bf16 v[24:27], v[124:127], v[194:197], v[24:27]
	v_mfma_f32_16x16x32_bf16 v[28:31], v[178:181], v[194:197], v[28:31]
	v_mfma_f32_16x16x32_bf16 v[60:63], v[124:127], v[202:205], v[60:63]
	v_mfma_f32_16x16x32_bf16 v[100:103], v[178:181], v[202:205], v[100:103]
	v_mfma_f32_16x16x32_bf16 v[16:19], v[124:127], v[210:213], v[16:19]
	v_mfma_f32_16x16x32_bf16 v[20:23], v[178:181], v[210:213], v[20:23]
	s_barrier
	s_setprio 0
	ds_read_b128 v[104:107], v145
	ds_read_b128 v[108:111], v145 offset:1024
	ds_read_b128 v[112:115], v145 offset:2048
	ds_read_b128 v[116:119], v145 offset:3072
	ds_read_b128 v[120:123], v146
	ds_read_b128 v[124:127], v146 offset:1024
	ds_read_b128 v[174:177], v146 offset:2048
	ds_read_b128 v[178:181], v146 offset:3072
	s_add_u32 s36, s36, 0x10180
	s_addc_u32 s37, s37, 0
	s_mov_b32 m0, s56
	ds_read_b128 v[182:185], v147
	ds_read_b128 v[186:189], v147 offset:1024
	ds_read_b128 v[190:193], v147 offset:2048
	ds_read_b128 v[194:197], v147 offset:3072
	ds_read_b128 v[198:201], v147 offset:4096
	ds_read_b128 v[202:205], v147 offset:5120
	ds_read_b128 v[206:209], v147 offset:6144
	ds_read_b128 v[210:213], v147 offset:7168
	global_load_lds_dwordx4 v128, s[36:37]
	s_mov_b32 m0, s57
	s_nop 0
	global_load_lds_dwordx4 v132, s[36:37]
	s_waitcnt vmcnt(8)
	s_waitcnt lgkmcnt(0)
	s_setprio 1
	s_barrier
	v_mfma_f32_16x16x32_bf16 v[64:67], v[104:107], v[182:185], v[64:67]
	v_mfma_f32_16x16x32_bf16 v[68:71], v[112:115], v[182:185], v[68:71]
	v_mfma_f32_16x16x32_bf16 v[72:75], v[104:107], v[190:193], v[72:75]
	v_mfma_f32_16x16x32_bf16 v[76:79], v[112:115], v[190:193], v[76:79]
	v_mfma_f32_16x16x32_bf16 v[80:83], v[104:107], v[198:201], v[80:83]
	v_mfma_f32_16x16x32_bf16 v[84:87], v[112:115], v[198:201], v[84:87]
	v_mfma_f32_16x16x32_bf16 v[88:91], v[104:107], v[206:209], v[88:91]
	v_mfma_f32_16x16x32_bf16 v[92:95], v[112:115], v[206:209], v[92:95]
	v_mfma_f32_16x16x32_bf16 v[64:67], v[108:111], v[186:189], v[64:67]
	v_mfma_f32_16x16x32_bf16 v[68:71], v[116:119], v[186:189], v[68:71]
	v_mfma_f32_16x16x32_bf16 v[72:75], v[108:111], v[194:197], v[72:75]
	v_mfma_f32_16x16x32_bf16 v[76:79], v[116:119], v[194:197], v[76:79]
	v_mfma_f32_16x16x32_bf16 v[80:83], v[108:111], v[202:205], v[80:83]
	v_mfma_f32_16x16x32_bf16 v[84:87], v[116:119], v[202:205], v[84:87]
	v_mfma_f32_16x16x32_bf16 v[88:91], v[108:111], v[210:213], v[88:91]
	v_mfma_f32_16x16x32_bf16 v[92:95], v[116:119], v[210:213], v[92:95]
	s_setprio 0
	s_setprio 1
	v_mfma_f32_16x16x32_bf16 v[32:35], v[174:177], v[182:185], v[32:35]
	v_mfma_f32_16x16x32_bf16 v[96:99], v[120:123], v[182:185], v[96:99]
	v_mfma_f32_16x16x32_bf16 v[182:185], v[178:181], v[186:189], v[32:35]
	v_mfma_f32_16x16x32_bf16 v[32:35], v[120:123], v[190:193], v[36:39]
	v_mfma_f32_16x16x32_bf16 v[214:217], v[124:127], v[186:189], v[96:99]
	v_mfma_f32_16x16x32_bf16 v[186:189], v[124:127], v[194:197], v[32:35]
	v_mfma_f32_16x16x32_bf16 v[32:35], v[174:177], v[190:193], v[40:43]
	v_mfma_f32_16x16x32_bf16 v[40:43], v[178:181], v[194:197], v[32:35]
	v_mfma_f32_16x16x32_bf16 v[32:35], v[120:123], v[198:201], v[44:47]
	v_mfma_f32_16x16x32_bf16 v[44:47], v[124:127], v[202:205], v[32:35]
	v_mfma_f32_16x16x32_bf16 v[32:35], v[174:177], v[198:201], v[48:51]
	v_mfma_f32_16x16x32_bf16 v[48:51], v[178:181], v[202:205], v[32:35]
	v_mfma_f32_16x16x32_bf16 v[32:35], v[120:123], v[206:209], v[52:55]
	v_mfma_f32_16x16x32_bf16 v[52:55], v[124:127], v[210:213], v[32:35]
	v_mfma_f32_16x16x32_bf16 v[32:35], v[174:177], v[206:209], v[56:59]
	v_mfma_f32_16x16x32_bf16 v[56:59], v[178:181], v[210:213], v[32:35]
	s_barrier
	s_setprio 0
	s_mov_b32 m0, s58
	v_lshl_add_u64 v[250:251], s[40:41], 0, v[130:131]
	s_add_u32 s36, s40, 0x10000
	s_nop 1
	ds_read_b128 v[32:35], v147 offset:16384
	ds_read_b128 v[36:39], v147 offset:17408
	ds_read_b128 v[96:99], v147 offset:18432
	ds_read_b128 v[190:193], v147 offset:19456
	ds_read_b128 v[194:197], v147 offset:20480
	ds_read_b128 v[198:201], v147 offset:21504
	ds_read_b128 v[202:205], v147 offset:22528
	ds_read_b128 v[206:209], v147 offset:23552
	global_load_lds_dwordx4 v[250:251], off
	v_lshl_add_u64 v[252:253], s[40:41], 0, v[134:135]
	s_mov_b32 m0, s59
	s_addc_u32 s37, s41, 0
	global_load_lds_dwordx4 v[252:253], off
	s_mov_b32 m0, s60
	v_lshl_add_u64 v[138:139], s[42:43], 0, v[128:129]
	global_load_lds_dwordx4 v130, s[36:37]
	s_mov_b32 m0, s61
	v_lshl_add_u64 v[140:141], s[42:43], 0, v[132:133]
	global_load_lds_dwordx4 v134, s[36:37]
	s_mov_b32 m0, s49
	s_nop 0
	global_load_lds_dwordx4 v[138:139], off
	s_mov_b32 m0, s50
	s_nop 0
	global_load_lds_dwordx4 v[140:141], off
	s_waitcnt vmcnt(8)
	s_waitcnt lgkmcnt(0)
	s_setprio 1
	s_barrier
	v_mfma_f32_16x16x32_bf16 v[0:3], v[104:107], v[202:205], v[0:3]
	v_mfma_f32_16x16x32_bf16 v[4:7], v[112:115], v[202:205], v[4:7]
	v_mfma_f32_16x16x32_bf16 v[150:153], v[104:107], v[32:35], v[150:153]
	v_mfma_f32_16x16x32_bf16 v[154:157], v[112:115], v[32:35], v[154:157]
	v_mfma_f32_16x16x32_bf16 v[158:161], v[104:107], v[96:99], v[158:161]
	v_mfma_f32_16x16x32_bf16 v[162:165], v[112:115], v[96:99], v[162:165]
	v_mfma_f32_16x16x32_bf16 v[166:169], v[104:107], v[194:197], v[166:169]
	v_mfma_f32_16x16x32_bf16 v[170:173], v[112:115], v[194:197], v[170:173]
	v_mfma_f32_16x16x32_bf16 v[0:3], v[108:111], v[206:209], v[0:3]
	v_mfma_f32_16x16x32_bf16 v[4:7], v[116:119], v[206:209], v[4:7]
	v_mfma_f32_16x16x32_bf16 v[150:153], v[108:111], v[36:39], v[150:153]
	v_mfma_f32_16x16x32_bf16 v[154:157], v[116:119], v[36:39], v[154:157]
	v_mfma_f32_16x16x32_bf16 v[158:161], v[108:111], v[190:193], v[158:161]
	v_mfma_f32_16x16x32_bf16 v[162:165], v[116:119], v[190:193], v[162:165]
	v_mfma_f32_16x16x32_bf16 v[166:169], v[108:111], v[198:201], v[166:169]
	v_mfma_f32_16x16x32_bf16 v[170:173], v[116:119], v[198:201], v[170:173]
	s_setprio 0
	s_setprio 1
	v_mfma_f32_16x16x32_bf16 v[8:11], v[120:123], v[32:35], v[8:11]
	v_mfma_f32_16x16x32_bf16 v[12:15], v[174:177], v[32:35], v[12:15]
	v_mfma_f32_16x16x32_bf16 v[24:27], v[120:123], v[96:99], v[24:27]
	v_mfma_f32_16x16x32_bf16 v[28:31], v[174:177], v[96:99], v[28:31]
	v_mfma_f32_16x16x32_bf16 v[32:35], v[120:123], v[194:197], v[60:63]
	v_mfma_f32_16x16x32_bf16 v[24:27], v[124:127], v[190:193], v[24:27]
	v_mfma_f32_16x16x32_bf16 v[28:31], v[178:181], v[190:193], v[28:31]
	v_mfma_f32_16x16x32_bf16 v[190:193], v[124:127], v[198:201], v[32:35]
	v_mfma_f32_16x16x32_bf16 v[32:35], v[174:177], v[194:197], v[100:103]
	v_mfma_f32_16x16x32_bf16 v[16:19], v[120:123], v[202:205], v[16:19]
	v_mfma_f32_16x16x32_bf16 v[8:11], v[124:127], v[36:39], v[8:11]
	v_mfma_f32_16x16x32_bf16 v[12:15], v[178:181], v[36:39], v[12:15]
	v_mfma_f32_16x16x32_bf16 v[194:197], v[178:181], v[198:201], v[32:35]
	v_mfma_f32_16x16x32_bf16 v[198:201], v[124:127], v[206:209], v[16:19]
	v_mfma_f32_16x16x32_bf16 v[16:19], v[174:177], v[202:205], v[20:23]
	v_mfma_f32_16x16x32_bf16 v[174:177], v[178:181], v[206:209], v[16:19]
	s_barrier
	s_setprio 0
	ds_read_b128 v[60:63], v148
	ds_read_b128 v[178:181], v148 offset:1024
	ds_read_b128 v[202:205], v148 offset:2048
	ds_read_b128 v[206:209], v148 offset:3072
	ds_read_b128 v[210:213], v149
	ds_read_b128 v[218:221], v149 offset:1024
	ds_read_b128 v[222:225], v149 offset:2048
	ds_read_b128 v[226:229], v149 offset:3072
	s_add_u32 s36, s42, 0x10000
	s_addc_u32 s37, s43, 0
	s_mov_b32 m0, s51
	ds_read_b128 v[16:19], v147 offset:32768
	ds_read_b128 v[20:23], v147 offset:33792
	ds_read_b128 v[108:111], v147 offset:34816
	ds_read_b128 v[230:233], v147 offset:35840
	ds_read_b128 v[234:237], v147 offset:36864
	ds_read_b128 v[238:241], v147 offset:37888
	ds_read_b128 v[242:245], v147 offset:38912
	ds_read_b128 v[246:249], v147 offset:39936
	global_load_lds_dwordx4 v128, s[36:37]
	s_mov_b32 m0, s52
	s_nop 0
	global_load_lds_dwordx4 v132, s[36:37]
	s_waitcnt vmcnt(8)
	s_waitcnt lgkmcnt(0)
	s_setprio 1
	s_barrier
	v_mfma_f32_16x16x32_bf16 v[32:35], v[60:63], v[16:19], v[64:67]
	v_mfma_f32_16x16x32_bf16 v[120:123], v[178:181], v[20:23], v[32:35]
	v_mfma_f32_16x16x32_bf16 v[32:35], v[202:205], v[16:19], v[68:71]
	v_mfma_f32_16x16x32_bf16 v[124:127], v[206:209], v[20:23], v[32:35]
	v_mfma_f32_16x16x32_bf16 v[32:35], v[60:63], v[108:111], v[72:75]
	v_mfma_f32_16x16x32_bf16 v[96:99], v[178:181], v[230:233], v[32:35]
	v_mfma_f32_16x16x32_bf16 v[32:35], v[202:205], v[108:111], v[76:79]
	v_mfma_f32_16x16x32_bf16 v[100:103], v[206:209], v[230:233], v[32:35]
	v_mfma_f32_16x16x32_bf16 v[32:35], v[60:63], v[234:237], v[80:83]
	v_mfma_f32_16x16x32_bf16 v[64:67], v[178:181], v[238:241], v[32:35]
	v_mfma_f32_16x16x32_bf16 v[32:35], v[202:205], v[234:237], v[84:87]
	v_mfma_f32_16x16x32_bf16 v[68:71], v[206:209], v[238:241], v[32:35]
	v_mfma_f32_16x16x32_bf16 v[32:35], v[60:63], v[242:245], v[88:91]
	v_mfma_f32_16x16x32_bf16 v[36:39], v[202:205], v[242:245], v[92:95]
	v_mfma_f32_16x16x32_bf16 v[32:35], v[178:181], v[246:249], v[32:35]
	v_mfma_f32_16x16x32_bf16 v[36:39], v[206:209], v[246:249], v[36:39]
	s_setprio 0
	s_setprio 1
	v_mfma_f32_16x16x32_bf16 v[72:75], v[210:213], v[16:19], v[214:217]
	v_mfma_f32_16x16x32_bf16 v[16:19], v[222:225], v[16:19], v[182:185]
	v_mfma_f32_16x16x32_bf16 v[116:119], v[226:229], v[20:23], v[16:19]
	v_mfma_f32_16x16x32_bf16 v[16:19], v[210:213], v[108:111], v[186:189]
	v_mfma_f32_16x16x32_bf16 v[104:107], v[218:221], v[230:233], v[16:19]
	v_mfma_f32_16x16x32_bf16 v[16:19], v[222:225], v[108:111], v[40:43]
	v_mfma_f32_16x16x32_bf16 v[108:111], v[226:229], v[230:233], v[16:19]
	v_mfma_f32_16x16x32_bf16 v[16:19], v[210:213], v[234:237], v[44:47]
	v_mfma_f32_16x16x32_bf16 v[112:115], v[218:221], v[20:23], v[72:75]
	v_mfma_f32_16x16x32_bf16 v[72:75], v[218:221], v[238:241], v[16:19]
	v_mfma_f32_16x16x32_bf16 v[16:19], v[222:225], v[234:237], v[48:51]
	v_mfma_f32_16x16x32_bf16 v[76:79], v[226:229], v[238:241], v[16:19]
	v_mfma_f32_16x16x32_bf16 v[16:19], v[210:213], v[242:245], v[52:55]
	v_mfma_f32_16x16x32_bf16 v[40:43], v[218:221], v[246:249], v[16:19]
	v_mfma_f32_16x16x32_bf16 v[16:19], v[222:225], v[242:245], v[56:59]
	v_mfma_f32_16x16x32_bf16 v[44:47], v[226:229], v[246:249], v[16:19]
	s_barrier
	s_setprio 0
	s_mov_b32 m0, s63
	s_nop 3
	v_lshl_add_u64 v[16:17], v[250:251], 0, s[12:13]
	s_add_u32 s36, s40, 0x10080
	ds_read_b128 v[56:59], v147 offset:49152
	ds_read_b128 v[92:95], v147 offset:50176
	ds_read_b128 v[182:185], v147 offset:51200
	ds_read_b128 v[186:189], v147 offset:52224
	ds_read_b128 v[214:217], v147 offset:53248
	ds_read_b128 v[230:233], v147 offset:54272
	ds_read_b128 v[234:237], v147 offset:55296
	ds_read_b128 v[238:241], v147 offset:56320
	global_load_lds_dwordx4 v[16:17], off
	v_lshl_add_u64 v[16:17], v[252:253], 0, s[12:13]
	s_mov_b32 m0, s23
	s_addc_u32 s37, s41, 0
	global_load_lds_dwordx4 v[16:17], off
	s_mov_b32 m0, s25
	s_nop 0
	global_load_lds_dwordx4 v130, s[36:37]
	s_mov_b32 m0, s38
	s_nop 0
	global_load_lds_dwordx4 v134, s[36:37]
	v_lshl_add_u64 v[16:17], v[138:139], 0, s[12:13]
	s_mov_b32 m0, s53
	s_nop 0
	global_load_lds_dwordx4 v[16:17], off
	v_lshl_add_u64 v[16:17], v[140:141], 0, s[12:13]
	s_mov_b32 m0, s54
	s_nop 0
	global_load_lds_dwordx4 v[16:17], off
	s_waitcnt vmcnt(8)
	s_waitcnt lgkmcnt(0)
	s_setprio 1
	s_barrier
	v_mfma_f32_16x16x32_bf16 v[16:19], v[60:63], v[56:59], v[150:153]
	v_mfma_f32_16x16x32_bf16 v[80:83], v[178:181], v[92:95], v[16:19]
	v_mfma_f32_16x16x32_bf16 v[16:19], v[202:205], v[56:59], v[154:157]
	v_mfma_f32_16x16x32_bf16 v[84:87], v[206:209], v[92:95], v[16:19]
	v_mfma_f32_16x16x32_bf16 v[16:19], v[60:63], v[182:185], v[158:161]
	v_mfma_f32_16x16x32_bf16 v[48:51], v[178:181], v[186:189], v[16:19]
	v_mfma_f32_16x16x32_bf16 v[16:19], v[202:205], v[182:185], v[162:165]
	v_mfma_f32_16x16x32_bf16 v[52:55], v[206:209], v[186:189], v[16:19]
	v_mfma_f32_16x16x32_bf16 v[16:19], v[60:63], v[214:217], v[166:169]
	v_mfma_f32_16x16x32_bf16 v[20:23], v[202:205], v[214:217], v[170:173]
	v_mfma_f32_16x16x32_bf16 v[0:3], v[60:63], v[234:237], v[0:3]
	v_mfma_f32_16x16x32_bf16 v[4:7], v[202:205], v[234:237], v[4:7]
	v_mfma_f32_16x16x32_bf16 v[16:19], v[178:181], v[230:233], v[16:19]
	v_mfma_f32_16x16x32_bf16 v[20:23], v[206:209], v[230:233], v[20:23]
	v_mfma_f32_16x16x32_bf16 v[0:3], v[178:181], v[238:241], v[0:3]
	v_mfma_f32_16x16x32_bf16 v[4:7], v[206:209], v[238:241], v[4:7]
	s_setprio 0
	s_setprio 1
	v_mfma_f32_16x16x32_bf16 v[8:11], v[210:213], v[56:59], v[8:11]
	v_mfma_f32_16x16x32_bf16 v[88:91], v[218:221], v[92:95], v[8:11]
	v_mfma_f32_16x16x32_bf16 v[8:11], v[222:225], v[56:59], v[12:15]
	v_mfma_f32_16x16x32_bf16 v[92:95], v[226:229], v[92:95], v[8:11]
	v_mfma_f32_16x16x32_bf16 v[8:11], v[210:213], v[182:185], v[24:27]
	v_mfma_f32_16x16x32_bf16 v[56:59], v[218:221], v[186:189], v[8:11]
	v_mfma_f32_16x16x32_bf16 v[8:11], v[222:225], v[182:185], v[28:31]
	v_mfma_f32_16x16x32_bf16 v[60:63], v[226:229], v[186:189], v[8:11]
	v_mfma_f32_16x16x32_bf16 v[8:11], v[210:213], v[214:217], v[190:193]
	v_mfma_f32_16x16x32_bf16 v[24:27], v[218:221], v[230:233], v[8:11]
	v_mfma_f32_16x16x32_bf16 v[8:11], v[222:225], v[214:217], v[194:197]
	v_mfma_f32_16x16x32_bf16 v[28:31], v[226:229], v[230:233], v[8:11]
	v_mfma_f32_16x16x32_bf16 v[8:11], v[210:213], v[234:237], v[198:201]
	v_mfma_f32_16x16x32_bf16 v[12:15], v[222:225], v[234:237], v[174:177]
	v_mfma_f32_16x16x32_bf16 v[8:11], v[218:221], v[238:241], v[8:11]
	v_mfma_f32_16x16x32_bf16 v[12:15], v[226:229], v[238:241], v[12:15]
	s_barrier
	s_setprio 0
	s_andn2_b64 vcc, exec, s[14:15]
	s_cbranch_vccnz .LBB0_997
	s_barrier

.LBB0_1017:
	s_add_u32 s65, s54, s6
	s_addc_u32 s66, s55, s7
	s_add_u32 s67, s56, s8
	s_addc_u32 s68, s57, s9
	s_ashr_i32 s19, s18, 31
	s_lshl_b64 s[6:7], s[18:19], 19
	s_add_u32 s20, s34, s6
	s_addc_u32 s21, s35, s7
	s_and_b64 s[8:9], s[0:1], exec
	s_cselect_b32 s19, s21, s29
	s_cselect_b32 s69, s20, s28
	s_ashr_i32 s17, s16, 31
	s_lshl_b64 s[8:9], s[16:17], 19
	s_add_u32 s22, s48, s8
	s_addc_u32 s23, s49, s9
	s_and_b64 s[30:31], s[0:1], exec
	s_cselect_b32 s17, s23, s27
	s_cselect_b32 s70, s22, s26
	s_add_u32 s30, s69, 0x80
	s_addc_u32 s31, s19, 0
	s_add_u32 s36, s70, 0x80
	s_addc_u32 s37, s17, 0
	v_lshl_add_u64 v[128:129], s[28:29], 0, v[196:197]
	v_lshl_add_u64 v[130:131], s[28:29], 0, v[198:199]
	s_mov_b32 s71, 0
	s_mov_b64 s[38:39], 0
	s_cmpk_eq_i32 s38, 0x700
	s_cselect_b64 s[44:45], -1, 0
	s_add_u32 s46, s28, s38
	s_addc_u32 s47, s29, s39
	s_add_u32 s73, s26, s38
	s_addc_u32 s72, s27, s39
	s_add_u32 s40, s46, 0x180
	s_addc_u32 s41, s47, 0
	s_add_u32 s42, s73, 0x180
	s_addc_u32 s43, s72, 0
	s_cmpk_eq_i32 s38, 0x700
	s_cselect_b32 s40, s30, s40
	s_cselect_b32 s41, s31, s41
	s_cselect_b32 s42, s36, s42
	s_cselect_b32 s43, s37, s43
	v_add_u32_e32 v144, s61, v220
	v_add_u32_e32 v160, s62, v220
	ds_read_b128 v[132:135], v144
	ds_read_b128 v[136:139], v144 offset:1024
	ds_read_b128 v[140:143], v144 offset:2048
	ds_read_b128 v[144:147], v144 offset:3072
	ds_read_b128 v[148:151], v160
	ds_read_b128 v[152:155], v160 offset:1024
	ds_read_b128 v[156:159], v160 offset:2048
	ds_read_b128 v[160:163], v160 offset:3072
	s_add_u32 s10, s46, 0x100
	s_addc_u32 s76, s47, 0
	s_and_b64 s[46:47], exec, s[44:45]
	s_cselect_b32 s47, s19, s76
	s_cselect_b32 s46, s69, s10
	s_add_u32 s10, s73, 0x100
	s_addc_u32 s72, s72, 0
	s_and_b64 s[44:45], exec, s[44:45]
	s_cselect_b32 s45, s17, s72
	s_cselect_b32 s44, s70, s10
	v_lshl_add_u64 v[216:217], v[128:129], 0, s[38:39]
	s_add_i32 m0, s25, 0xc000
	ds_read_b128 v[164:167], v221
	ds_read_b128 v[168:171], v221 offset:1024
	ds_read_b128 v[172:175], v221 offset:2048
	ds_read_b128 v[176:179], v221 offset:3072
	ds_read_b128 v[180:183], v221 offset:4096
	ds_read_b128 v[204:207], v221 offset:5120
	ds_read_b128 v[208:211], v221 offset:6144
	global_load_lds_dwordx4 v[216:217], off
	v_lshl_add_u64 v[216:217], v[130:131], 0, s[38:39]
	s_add_i32 m0, s25, 0xe000
	ds_read_b128 v[212:215], v221 offset:7168
	global_load_lds_dwordx4 v[216:217], off
	s_waitcnt vmcnt(8)
	s_waitcnt lgkmcnt(0)
	s_setprio 1
	s_barrier
	v_mfma_f32_16x16x32_bf16 v[124:127], v[132:135], v[164:167], 0
	v_mfma_f32_16x16x32_bf16 v[120:123], v[140:143], v[164:167], 0
	v_mfma_f32_16x16x32_bf16 v[108:111], v[132:135], v[172:175], 0
	v_mfma_f32_16x16x32_bf16 v[104:107], v[140:143], v[172:175], 0
	v_mfma_f32_16x16x32_bf16 v[92:95], v[132:135], v[180:183], 0
	v_mfma_f32_16x16x32_bf16 v[88:91], v[140:143], v[180:183], 0
	v_mfma_f32_16x16x32_bf16 v[76:79], v[132:135], v[208:211], 0
	v_mfma_f32_16x16x32_bf16 v[72:75], v[140:143], v[208:211], 0
	v_mfma_f32_16x16x32_bf16 v[124:127], v[136:139], v[168:171], v[124:127]
	v_mfma_f32_16x16x32_bf16 v[120:123], v[144:147], v[168:171], v[120:123]
	v_mfma_f32_16x16x32_bf16 v[108:111], v[136:139], v[176:179], v[108:111]
	v_mfma_f32_16x16x32_bf16 v[104:107], v[144:147], v[176:179], v[104:107]
	v_mfma_f32_16x16x32_bf16 v[92:95], v[136:139], v[204:207], v[92:95]
	v_mfma_f32_16x16x32_bf16 v[88:91], v[144:147], v[204:207], v[88:91]
	v_mfma_f32_16x16x32_bf16 v[76:79], v[136:139], v[212:215], v[76:79]
	v_mfma_f32_16x16x32_bf16 v[72:75], v[144:147], v[212:215], v[72:75]
	s_setprio 0
	s_setprio 1
	v_mfma_f32_16x16x32_bf16 v[116:119], v[148:151], v[164:167], 0
	v_mfma_f32_16x16x32_bf16 v[112:115], v[156:159], v[164:167], 0
	v_mfma_f32_16x16x32_bf16 v[100:103], v[148:151], v[172:175], 0
	v_mfma_f32_16x16x32_bf16 v[96:99], v[156:159], v[172:175], 0
	v_mfma_f32_16x16x32_bf16 v[84:87], v[148:151], v[180:183], 0
	v_mfma_f32_16x16x32_bf16 v[80:83], v[156:159], v[180:183], 0
	v_mfma_f32_16x16x32_bf16 v[68:71], v[148:151], v[208:211], 0
	v_mfma_f32_16x16x32_bf16 v[64:67], v[156:159], v[208:211], 0
	v_mfma_f32_16x16x32_bf16 v[116:119], v[152:155], v[168:171], v[116:119]
	v_mfma_f32_16x16x32_bf16 v[112:115], v[160:163], v[168:171], v[112:115]
	v_mfma_f32_16x16x32_bf16 v[100:103], v[152:155], v[176:179], v[100:103]
	v_mfma_f32_16x16x32_bf16 v[96:99], v[160:163], v[176:179], v[96:99]
	v_mfma_f32_16x16x32_bf16 v[84:87], v[152:155], v[204:207], v[84:87]
	v_mfma_f32_16x16x32_bf16 v[80:83], v[160:163], v[204:207], v[80:83]
	v_mfma_f32_16x16x32_bf16 v[68:71], v[152:155], v[212:215], v[68:71]
	v_mfma_f32_16x16x32_bf16 v[64:67], v[160:163], v[212:215], v[64:67]
	s_barrier
	s_setprio 0
	s_add_i32 s10, s61, s50
	s_mov_b32 m0, s10
	ds_read_b128 v[164:167], v221 offset:16384
	ds_read_b128 v[168:171], v221 offset:17408
	ds_read_b128 v[172:175], v221 offset:18432
	global_load_lds_dwordx4 v186, s[44:45]
	s_add_i32 m0, s10, 0x2000
	ds_read_b128 v[176:179], v221 offset:19456
	global_load_lds_dwordx4 v190, s[44:45]
	s_add_u32 s44, s44, 0x40000
	s_addc_u32 s45, s45, 0
	s_add_i32 s10, s62, s50
	s_mov_b32 m0, s10
	ds_read_b128 v[180:183], v221 offset:20480
	global_load_lds_dwordx4 v186, s[44:45]
	s_add_i32 m0, s10, 0x2000
	ds_read_b128 v[204:207], v221 offset:21504
	global_load_lds_dwordx4 v190, s[44:45]
	s_mov_b32 m0, s25
	ds_read_b128 v[208:211], v221 offset:22528
	global_load_lds_dwordx4 v184, s[46:47]
	s_mov_b32 m0, s51
	ds_read_b128 v[212:215], v221 offset:23552
	global_load_lds_dwordx4 v188, s[46:47]
	s_waitcnt vmcnt(8)
	s_waitcnt lgkmcnt(0)
	s_setprio 1
	s_barrier
	v_mfma_f32_16x16x32_bf16 v[60:63], v[132:135], v[164:167], 0
	v_mfma_f32_16x16x32_bf16 v[56:59], v[140:143], v[164:167], 0
	v_mfma_f32_16x16x32_bf16 v[44:47], v[132:135], v[172:175], 0
	v_mfma_f32_16x16x32_bf16 v[40:43], v[140:143], v[172:175], 0
	v_mfma_f32_16x16x32_bf16 v[28:31], v[132:135], v[180:183], 0
	v_mfma_f32_16x16x32_bf16 v[24:27], v[140:143], v[180:183], 0
	v_mfma_f32_16x16x32_bf16 v[12:15], v[132:135], v[208:211], 0
	v_mfma_f32_16x16x32_bf16 v[8:11], v[140:143], v[208:211], 0
	v_mfma_f32_16x16x32_bf16 v[60:63], v[136:139], v[168:171], v[60:63]
	v_mfma_f32_16x16x32_bf16 v[56:59], v[144:147], v[168:171], v[56:59]
	v_mfma_f32_16x16x32_bf16 v[44:47], v[136:139], v[176:179], v[44:47]
	v_mfma_f32_16x16x32_bf16 v[40:43], v[144:147], v[176:179], v[40:43]
	v_mfma_f32_16x16x32_bf16 v[28:31], v[136:139], v[204:207], v[28:31]
	v_mfma_f32_16x16x32_bf16 v[24:27], v[144:147], v[204:207], v[24:27]
	v_mfma_f32_16x16x32_bf16 v[12:15], v[136:139], v[212:215], v[12:15]
	v_mfma_f32_16x16x32_bf16 v[8:11], v[144:147], v[212:215], v[8:11]
	s_setprio 0
	s_setprio 1
	v_mfma_f32_16x16x32_bf16 v[52:55], v[148:151], v[164:167], 0
	v_mfma_f32_16x16x32_bf16 v[48:51], v[156:159], v[164:167], 0
	v_mfma_f32_16x16x32_bf16 v[36:39], v[148:151], v[172:175], 0
	v_mfma_f32_16x16x32_bf16 v[32:35], v[156:159], v[172:175], 0
	v_mfma_f32_16x16x32_bf16 v[20:23], v[148:151], v[180:183], 0
	v_mfma_f32_16x16x32_bf16 v[16:19], v[156:159], v[180:183], 0
	v_mfma_f32_16x16x32_bf16 v[4:7], v[148:151], v[208:211], 0
	v_mfma_f32_16x16x32_bf16 v[0:3], v[156:159], v[208:211], 0
	v_mfma_f32_16x16x32_bf16 v[52:55], v[152:155], v[168:171], v[52:55]
	v_mfma_f32_16x16x32_bf16 v[48:51], v[160:163], v[168:171], v[48:51]
	v_mfma_f32_16x16x32_bf16 v[36:39], v[152:155], v[176:179], v[36:39]
	v_mfma_f32_16x16x32_bf16 v[32:35], v[160:163], v[176:179], v[32:35]
	v_mfma_f32_16x16x32_bf16 v[20:23], v[152:155], v[204:207], v[20:23]
	v_mfma_f32_16x16x32_bf16 v[16:19], v[160:163], v[204:207], v[16:19]
	v_mfma_f32_16x16x32_bf16 v[4:7], v[152:155], v[212:215], v[4:7]
	v_mfma_f32_16x16x32_bf16 v[0:3], v[160:163], v[212:215], v[0:3]
	s_barrier
	s_setprio 0
	s_add_i32 s10, 0, 0x18000
	s_add_i32 s72, 0, 0x1c000
	v_add_u32_e32 v144, s10, v220
	v_add_u32_e32 v160, s72, v220
	ds_read_b128 v[132:135], v144
	ds_read_b128 v[136:139], v144 offset:1024
	ds_read_b128 v[140:143], v144 offset:2048
	ds_read_b128 v[144:147], v144 offset:3072
	ds_read_b128 v[148:151], v160
	ds_read_b128 v[152:155], v160 offset:1024
	ds_read_b128 v[156:159], v160 offset:2048
	ds_read_b128 v[160:163], v160 offset:3072
	s_add_u32 s44, s46, 0x40000
	s_addc_u32 s45, s47, 0
	s_mov_b32 m0, s52
	ds_read_b128 v[164:167], v221 offset:32768
	ds_read_b128 v[168:171], v221 offset:33792
	ds_read_b128 v[172:175], v221 offset:34816
	ds_read_b128 v[176:179], v221 offset:35840
	ds_read_b128 v[180:183], v221 offset:36864
	ds_read_b128 v[204:207], v221 offset:37888
	ds_read_b128 v[208:211], v221 offset:38912
	global_load_lds_dwordx4 v184, s[44:45]
	s_mov_b32 m0, s53
	ds_read_b128 v[212:215], v221 offset:39936
	global_load_lds_dwordx4 v188, s[44:45]
	s_waitcnt vmcnt(8)
	s_waitcnt lgkmcnt(0)
	s_setprio 1
	s_barrier
	v_mfma_f32_16x16x32_bf16 v[124:127], v[132:135], v[164:167], v[124:127]
	v_mfma_f32_16x16x32_bf16 v[120:123], v[140:143], v[164:167], v[120:123]
	v_mfma_f32_16x16x32_bf16 v[108:111], v[132:135], v[172:175], v[108:111]
	v_mfma_f32_16x16x32_bf16 v[104:107], v[140:143], v[172:175], v[104:107]
	v_mfma_f32_16x16x32_bf16 v[92:95], v[132:135], v[180:183], v[92:95]
	v_mfma_f32_16x16x32_bf16 v[88:91], v[140:143], v[180:183], v[88:91]
	v_mfma_f32_16x16x32_bf16 v[76:79], v[132:135], v[208:211], v[76:79]
	v_mfma_f32_16x16x32_bf16 v[72:75], v[140:143], v[208:211], v[72:75]
	v_mfma_f32_16x16x32_bf16 v[124:127], v[136:139], v[168:171], v[124:127]
	v_mfma_f32_16x16x32_bf16 v[120:123], v[144:147], v[168:171], v[120:123]
	v_mfma_f32_16x16x32_bf16 v[108:111], v[136:139], v[176:179], v[108:111]
	v_mfma_f32_16x16x32_bf16 v[104:107], v[144:147], v[176:179], v[104:107]
	v_mfma_f32_16x16x32_bf16 v[92:95], v[136:139], v[204:207], v[92:95]
	v_mfma_f32_16x16x32_bf16 v[88:91], v[144:147], v[204:207], v[88:91]
	v_mfma_f32_16x16x32_bf16 v[76:79], v[136:139], v[212:215], v[76:79]
	v_mfma_f32_16x16x32_bf16 v[72:75], v[144:147], v[212:215], v[72:75]
	s_setprio 0
	s_setprio 1
	v_mfma_f32_16x16x32_bf16 v[116:119], v[148:151], v[164:167], v[116:119]
	v_mfma_f32_16x16x32_bf16 v[112:115], v[156:159], v[164:167], v[112:115]
	v_mfma_f32_16x16x32_bf16 v[100:103], v[148:151], v[172:175], v[100:103]
	v_mfma_f32_16x16x32_bf16 v[96:99], v[156:159], v[172:175], v[96:99]
	v_mfma_f32_16x16x32_bf16 v[84:87], v[148:151], v[180:183], v[84:87]
	v_mfma_f32_16x16x32_bf16 v[80:83], v[156:159], v[180:183], v[80:83]
	v_mfma_f32_16x16x32_bf16 v[68:71], v[148:151], v[208:211], v[68:71]
	v_mfma_f32_16x16x32_bf16 v[64:67], v[156:159], v[208:211], v[64:67]
	v_mfma_f32_16x16x32_bf16 v[116:119], v[152:155], v[168:171], v[116:119]
	v_mfma_f32_16x16x32_bf16 v[112:115], v[160:163], v[168:171], v[112:115]
	v_mfma_f32_16x16x32_bf16 v[100:103], v[152:155], v[176:179], v[100:103]
	v_mfma_f32_16x16x32_bf16 v[96:99], v[160:163], v[176:179], v[96:99]
	v_mfma_f32_16x16x32_bf16 v[84:87], v[152:155], v[204:207], v[84:87]
	v_mfma_f32_16x16x32_bf16 v[80:83], v[160:163], v[204:207], v[80:83]
	v_mfma_f32_16x16x32_bf16 v[68:71], v[152:155], v[212:215], v[68:71]
	v_mfma_f32_16x16x32_bf16 v[64:67], v[160:163], v[212:215], v[64:67]
	s_barrier
	s_setprio 0
	s_add_i32 s10, s10, s50
	s_mov_b32 m0, s10
	ds_read_b128 v[164:167], v221 offset:49152
	ds_read_b128 v[168:171], v221 offset:50176
	ds_read_b128 v[172:175], v221 offset:51200
	global_load_lds_dwordx4 v186, s[42:43]
	s_add_i32 m0, s10, 0x2000
	ds_read_b128 v[176:179], v221 offset:52224
	global_load_lds_dwordx4 v190, s[42:43]
	s_add_u32 s42, s42, 0x40000
	s_addc_u32 s43, s43, 0
	s_add_i32 s10, s72, s50
	s_mov_b32 m0, s10
	ds_read_b128 v[180:183], v221 offset:53248
	global_load_lds_dwordx4 v186, s[42:43]
	s_add_i32 m0, s10, 0x2000
	ds_read_b128 v[204:207], v221 offset:54272
	global_load_lds_dwordx4 v190, s[42:43]
	s_mov_b32 m0, s58
	ds_read_b128 v[208:211], v221 offset:55296
	global_load_lds_dwordx4 v184, s[40:41]
	s_mov_b32 m0, s59
	ds_read_b128 v[212:215], v221 offset:56320
	global_load_lds_dwordx4 v188, s[40:41]
	s_waitcnt vmcnt(8)
	s_waitcnt lgkmcnt(0)
	s_setprio 1
	s_barrier
	v_mfma_f32_16x16x32_bf16 v[60:63], v[132:135], v[164:167], v[60:63]
	v_mfma_f32_16x16x32_bf16 v[56:59], v[140:143], v[164:167], v[56:59]
	v_mfma_f32_16x16x32_bf16 v[44:47], v[132:135], v[172:175], v[44:47]
	v_mfma_f32_16x16x32_bf16 v[40:43], v[140:143], v[172:175], v[40:43]
	v_mfma_f32_16x16x32_bf16 v[28:31], v[132:135], v[180:183], v[28:31]
	v_mfma_f32_16x16x32_bf16 v[24:27], v[140:143], v[180:183], v[24:27]
	v_mfma_f32_16x16x32_bf16 v[12:15], v[132:135], v[208:211], v[12:15]
	v_mfma_f32_16x16x32_bf16 v[8:11], v[140:143], v[208:211], v[8:11]
	v_mfma_f32_16x16x32_bf16 v[60:63], v[136:139], v[168:171], v[60:63]
	v_mfma_f32_16x16x32_bf16 v[56:59], v[144:147], v[168:171], v[56:59]
	v_mfma_f32_16x16x32_bf16 v[44:47], v[136:139], v[176:179], v[44:47]
	v_mfma_f32_16x16x32_bf16 v[40:43], v[144:147], v[176:179], v[40:43]
	v_mfma_f32_16x16x32_bf16 v[28:31], v[136:139], v[204:207], v[28:31]
	v_mfma_f32_16x16x32_bf16 v[24:27], v[144:147], v[204:207], v[24:27]
	v_mfma_f32_16x16x32_bf16 v[12:15], v[136:139], v[212:215], v[12:15]
	v_mfma_f32_16x16x32_bf16 v[8:11], v[144:147], v[212:215], v[8:11]
	s_setprio 0
	s_setprio 1
	v_mfma_f32_16x16x32_bf16 v[52:55], v[148:151], v[164:167], v[52:55]
	v_mfma_f32_16x16x32_bf16 v[48:51], v[156:159], v[164:167], v[48:51]
	v_mfma_f32_16x16x32_bf16 v[36:39], v[148:151], v[172:175], v[36:39]
	v_mfma_f32_16x16x32_bf16 v[32:35], v[156:159], v[172:175], v[32:35]
	v_mfma_f32_16x16x32_bf16 v[20:23], v[148:151], v[180:183], v[20:23]
	v_mfma_f32_16x16x32_bf16 v[16:19], v[156:159], v[180:183], v[16:19]
	v_mfma_f32_16x16x32_bf16 v[4:7], v[148:151], v[208:211], v[4:7]
	v_mfma_f32_16x16x32_bf16 v[0:3], v[156:159], v[208:211], v[0:3]
	v_mfma_f32_16x16x32_bf16 v[52:55], v[152:155], v[168:171], v[52:55]
	v_mfma_f32_16x16x32_bf16 v[48:51], v[160:163], v[168:171], v[48:51]
	v_mfma_f32_16x16x32_bf16 v[36:39], v[152:155], v[176:179], v[36:39]
	v_mfma_f32_16x16x32_bf16 v[32:35], v[160:163], v[176:179], v[32:35]
	v_mfma_f32_16x16x32_bf16 v[20:23], v[152:155], v[204:207], v[20:23]
	v_mfma_f32_16x16x32_bf16 v[16:19], v[160:163], v[204:207], v[16:19]
	v_mfma_f32_16x16x32_bf16 v[4:7], v[152:155], v[212:215], v[4:7]
	v_mfma_f32_16x16x32_bf16 v[0:3], v[160:163], v[212:215], v[0:3]
	s_barrier
	s_setprio 0
	s_add_i32 s10, s71, 2
	s_add_u32 s38, s38, 0x100
	s_addc_u32 s39, s39, 0
	s_cmp_gt_u32 s71, 13
	s_mov_b32 s71, s10
	s_cbranch_scc1 .LBB0_1025
	s_branch .LBB0_1019
.LBB0_1018:
	v_add_u32_e32 v144, s61, v220
	v_add_u32_e32 v160, s62, v220
	ds_read_b128 v[132:135], v144
	ds_read_b128 v[136:139], v144 offset:1024
	ds_read_b128 v[140:143], v144 offset:2048
	ds_read_b128 v[144:147], v144 offset:3072
	ds_read_b128 v[148:151], v160
	ds_read_b128 v[152:155], v160 offset:1024
	ds_read_b128 v[156:159], v160 offset:2048
	ds_read_b128 v[160:163], v160 offset:3072
	s_add_u32 s10, s46, 0x100
	s_addc_u32 s76, s47, 0
	s_and_b64 s[46:47], exec, s[44:45]
	s_cselect_b32 s47, s19, s76
	s_cselect_b32 s46, s69, s10
	s_add_u32 s10, s73, 0x100
	s_addc_u32 s72, s72, 0
	s_and_b64 s[44:45], exec, s[44:45]
	s_cselect_b32 s45, s17, s72
	s_cselect_b32 s44, s70, s10
	v_lshl_add_u64 v[216:217], v[128:129], 0, s[38:39]
	s_add_i32 m0, s25, 0xc000
	ds_read_b128 v[164:167], v221
	ds_read_b128 v[168:171], v221 offset:1024
	ds_read_b128 v[172:175], v221 offset:2048
	ds_read_b128 v[176:179], v221 offset:3072
	ds_read_b128 v[180:183], v221 offset:4096
	ds_read_b128 v[204:207], v221 offset:5120
	ds_read_b128 v[208:211], v221 offset:6144
	global_load_lds_dwordx4 v[216:217], off
	v_lshl_add_u64 v[216:217], v[130:131], 0, s[38:39]
	s_add_i32 m0, s25, 0xe000
	ds_read_b128 v[212:215], v221 offset:7168
	global_load_lds_dwordx4 v[216:217], off
	s_waitcnt vmcnt(8)
	s_waitcnt lgkmcnt(0)
	s_setprio 1
	s_barrier
	v_mfma_f32_16x16x32_bf16 v[124:127], v[132:135], v[164:167], v[124:127]
	v_mfma_f32_16x16x32_bf16 v[120:123], v[140:143], v[164:167], v[120:123]
	v_mfma_f32_16x16x32_bf16 v[108:111], v[132:135], v[172:175], v[108:111]
	v_mfma_f32_16x16x32_bf16 v[104:107], v[140:143], v[172:175], v[104:107]
	v_mfma_f32_16x16x32_bf16 v[92:95], v[132:135], v[180:183], v[92:95]
	v_mfma_f32_16x16x32_bf16 v[88:91], v[140:143], v[180:183], v[88:91]
	v_mfma_f32_16x16x32_bf16 v[76:79], v[132:135], v[208:211], v[76:79]
	v_mfma_f32_16x16x32_bf16 v[72:75], v[140:143], v[208:211], v[72:75]
	v_mfma_f32_16x16x32_bf16 v[124:127], v[136:139], v[168:171], v[124:127]
	v_mfma_f32_16x16x32_bf16 v[120:123], v[144:147], v[168:171], v[120:123]
	v_mfma_f32_16x16x32_bf16 v[108:111], v[136:139], v[176:179], v[108:111]
	v_mfma_f32_16x16x32_bf16 v[104:107], v[144:147], v[176:179], v[104:107]
	v_mfma_f32_16x16x32_bf16 v[92:95], v[136:139], v[204:207], v[92:95]
	v_mfma_f32_16x16x32_bf16 v[88:91], v[144:147], v[204:207], v[88:91]
	v_mfma_f32_16x16x32_bf16 v[76:79], v[136:139], v[212:215], v[76:79]
	v_mfma_f32_16x16x32_bf16 v[72:75], v[144:147], v[212:215], v[72:75]
	s_setprio 0
	s_setprio 1
	v_mfma_f32_16x16x32_bf16 v[116:119], v[148:151], v[164:167], v[116:119]
	v_mfma_f32_16x16x32_bf16 v[112:115], v[156:159], v[164:167], v[112:115]
	v_mfma_f32_16x16x32_bf16 v[100:103], v[148:151], v[172:175], v[100:103]
	v_mfma_f32_16x16x32_bf16 v[96:99], v[156:159], v[172:175], v[96:99]
	v_mfma_f32_16x16x32_bf16 v[84:87], v[148:151], v[180:183], v[84:87]
	v_mfma_f32_16x16x32_bf16 v[80:83], v[156:159], v[180:183], v[80:83]
	v_mfma_f32_16x16x32_bf16 v[68:71], v[148:151], v[208:211], v[68:71]
	v_mfma_f32_16x16x32_bf16 v[64:67], v[156:159], v[208:211], v[64:67]
	v_mfma_f32_16x16x32_bf16 v[116:119], v[152:155], v[168:171], v[116:119]
	v_mfma_f32_16x16x32_bf16 v[112:115], v[160:163], v[168:171], v[112:115]
	v_mfma_f32_16x16x32_bf16 v[100:103], v[152:155], v[176:179], v[100:103]
	v_mfma_f32_16x16x32_bf16 v[96:99], v[160:163], v[176:179], v[96:99]
	v_mfma_f32_16x16x32_bf16 v[84:87], v[152:155], v[204:207], v[84:87]
	v_mfma_f32_16x16x32_bf16 v[80:83], v[160:163], v[204:207], v[80:83]
	v_mfma_f32_16x16x32_bf16 v[68:71], v[152:155], v[212:215], v[68:71]
	v_mfma_f32_16x16x32_bf16 v[64:67], v[160:163], v[212:215], v[64:67]
	s_barrier
	s_setprio 0
	s_add_i32 s10, s61, s50
	s_mov_b32 m0, s10
	ds_read_b128 v[164:167], v221 offset:16384
	ds_read_b128 v[168:171], v221 offset:17408
	ds_read_b128 v[172:175], v221 offset:18432
	global_load_lds_dwordx4 v186, s[44:45]
	s_add_i32 m0, s10, 0x2000
	ds_read_b128 v[176:179], v221 offset:19456
	global_load_lds_dwordx4 v190, s[44:45]
	s_add_u32 s44, s44, 0x40000
	s_addc_u32 s45, s45, 0
	s_add_i32 s10, s62, s50
	s_mov_b32 m0, s10
	ds_read_b128 v[180:183], v221 offset:20480
	global_load_lds_dwordx4 v186, s[44:45]
	s_add_i32 m0, s10, 0x2000
	ds_read_b128 v[204:207], v221 offset:21504
	global_load_lds_dwordx4 v190, s[44:45]
	s_mov_b32 m0, s25
	ds_read_b128 v[208:211], v221 offset:22528
	global_load_lds_dwordx4 v184, s[46:47]
	s_mov_b32 m0, s51
	ds_read_b128 v[212:215], v221 offset:23552
	global_load_lds_dwordx4 v188, s[46:47]
	s_waitcnt vmcnt(8)
	s_waitcnt lgkmcnt(0)
	s_setprio 1
	s_barrier
	v_mfma_f32_16x16x32_bf16 v[60:63], v[132:135], v[164:167], v[60:63]
	v_mfma_f32_16x16x32_bf16 v[56:59], v[140:143], v[164:167], v[56:59]
	v_mfma_f32_16x16x32_bf16 v[44:47], v[132:135], v[172:175], v[44:47]
	v_mfma_f32_16x16x32_bf16 v[40:43], v[140:143], v[172:175], v[40:43]
	v_mfma_f32_16x16x32_bf16 v[28:31], v[132:135], v[180:183], v[28:31]
	v_mfma_f32_16x16x32_bf16 v[24:27], v[140:143], v[180:183], v[24:27]
	v_mfma_f32_16x16x32_bf16 v[12:15], v[132:135], v[208:211], v[12:15]
	v_mfma_f32_16x16x32_bf16 v[8:11], v[140:143], v[208:211], v[8:11]
	v_mfma_f32_16x16x32_bf16 v[60:63], v[136:139], v[168:171], v[60:63]
	v_mfma_f32_16x16x32_bf16 v[56:59], v[144:147], v[168:171], v[56:59]
	v_mfma_f32_16x16x32_bf16 v[44:47], v[136:139], v[176:179], v[44:47]
	v_mfma_f32_16x16x32_bf16 v[40:43], v[144:147], v[176:179], v[40:43]
	v_mfma_f32_16x16x32_bf16 v[28:31], v[136:139], v[204:207], v[28:31]
	v_mfma_f32_16x16x32_bf16 v[24:27], v[144:147], v[204:207], v[24:27]
	v_mfma_f32_16x16x32_bf16 v[12:15], v[136:139], v[212:215], v[12:15]
	v_mfma_f32_16x16x32_bf16 v[8:11], v[144:147], v[212:215], v[8:11]
	s_setprio 0
	s_setprio 1
	v_mfma_f32_16x16x32_bf16 v[52:55], v[148:151], v[164:167], v[52:55]
	v_mfma_f32_16x16x32_bf16 v[48:51], v[156:159], v[164:167], v[48:51]
	v_mfma_f32_16x16x32_bf16 v[36:39], v[148:151], v[172:175], v[36:39]
	v_mfma_f32_16x16x32_bf16 v[32:35], v[156:159], v[172:175], v[32:35]
	v_mfma_f32_16x16x32_bf16 v[20:23], v[148:151], v[180:183], v[20:23]
	v_mfma_f32_16x16x32_bf16 v[16:19], v[156:159], v[180:183], v[16:19]
	v_mfma_f32_16x16x32_bf16 v[4:7], v[148:151], v[208:211], v[4:7]
	v_mfma_f32_16x16x32_bf16 v[0:3], v[156:159], v[208:211], v[0:3]
	v_mfma_f32_16x16x32_bf16 v[52:55], v[152:155], v[168:171], v[52:55]
	v_mfma_f32_16x16x32_bf16 v[48:51], v[160:163], v[168:171], v[48:51]
	v_mfma_f32_16x16x32_bf16 v[36:39], v[152:155], v[176:179], v[36:39]
	v_mfma_f32_16x16x32_bf16 v[32:35], v[160:163], v[176:179], v[32:35]
	v_mfma_f32_16x16x32_bf16 v[20:23], v[152:155], v[204:207], v[20:23]
	v_mfma_f32_16x16x32_bf16 v[16:19], v[160:163], v[204:207], v[16:19]
	v_mfma_f32_16x16x32_bf16 v[4:7], v[152:155], v[212:215], v[4:7]
	v_mfma_f32_16x16x32_bf16 v[0:3], v[160:163], v[212:215], v[0:3]
	s_barrier
	s_setprio 0
	s_add_i32 s10, 0, 0x18000
	s_add_i32 s72, 0, 0x1c000
	v_add_u32_e32 v144, s10, v220
	v_add_u32_e32 v160, s72, v220
	ds_read_b128 v[132:135], v144
	ds_read_b128 v[136:139], v144 offset:1024
	ds_read_b128 v[140:143], v144 offset:2048
	ds_read_b128 v[144:147], v144 offset:3072
	ds_read_b128 v[148:151], v160
	ds_read_b128 v[152:155], v160 offset:1024
	ds_read_b128 v[156:159], v160 offset:2048
	ds_read_b128 v[160:163], v160 offset:3072
	s_add_u32 s44, s46, 0x40000
	s_addc_u32 s45, s47, 0
	s_mov_b32 m0, s52
	ds_read_b128 v[164:167], v221 offset:32768
	ds_read_b128 v[168:171], v221 offset:33792
	ds_read_b128 v[172:175], v221 offset:34816
	ds_read_b128 v[176:179], v221 offset:35840
	ds_read_b128 v[180:183], v221 offset:36864
	ds_read_b128 v[204:207], v221 offset:37888
	ds_read_b128 v[208:211], v221 offset:38912
	global_load_lds_dwordx4 v184, s[44:45]
	s_mov_b32 m0, s53
	ds_read_b128 v[212:215], v221 offset:39936
	global_load_lds_dwordx4 v188, s[44:45]
	s_waitcnt vmcnt(8)
	s_waitcnt lgkmcnt(0)
	s_setprio 1
	s_barrier
	v_mfma_f32_16x16x32_bf16 v[124:127], v[132:135], v[164:167], v[124:127]
	v_mfma_f32_16x16x32_bf16 v[120:123], v[140:143], v[164:167], v[120:123]
	v_mfma_f32_16x16x32_bf16 v[108:111], v[132:135], v[172:175], v[108:111]
	v_mfma_f32_16x16x32_bf16 v[104:107], v[140:143], v[172:175], v[104:107]
	v_mfma_f32_16x16x32_bf16 v[92:95], v[132:135], v[180:183], v[92:95]
	v_mfma_f32_16x16x32_bf16 v[88:91], v[140:143], v[180:183], v[88:91]
	v_mfma_f32_16x16x32_bf16 v[76:79], v[132:135], v[208:211], v[76:79]
	v_mfma_f32_16x16x32_bf16 v[72:75], v[140:143], v[208:211], v[72:75]
	v_mfma_f32_16x16x32_bf16 v[124:127], v[136:139], v[168:171], v[124:127]
	v_mfma_f32_16x16x32_bf16 v[120:123], v[144:147], v[168:171], v[120:123]
	v_mfma_f32_16x16x32_bf16 v[108:111], v[136:139], v[176:179], v[108:111]
	v_mfma_f32_16x16x32_bf16 v[104:107], v[144:147], v[176:179], v[104:107]
	v_mfma_f32_16x16x32_bf16 v[92:95], v[136:139], v[204:207], v[92:95]
	v_mfma_f32_16x16x32_bf16 v[88:91], v[144:147], v[204:207], v[88:91]
	v_mfma_f32_16x16x32_bf16 v[76:79], v[136:139], v[212:215], v[76:79]
	v_mfma_f32_16x16x32_bf16 v[72:75], v[144:147], v[212:215], v[72:75]
	s_setprio 0
	s_setprio 1
	v_mfma_f32_16x16x32_bf16 v[116:119], v[148:151], v[164:167], v[116:119]
	v_mfma_f32_16x16x32_bf16 v[112:115], v[156:159], v[164:167], v[112:115]
	v_mfma_f32_16x16x32_bf16 v[100:103], v[148:151], v[172:175], v[100:103]
	v_mfma_f32_16x16x32_bf16 v[96:99], v[156:159], v[172:175], v[96:99]
	v_mfma_f32_16x16x32_bf16 v[84:87], v[148:151], v[180:183], v[84:87]
	v_mfma_f32_16x16x32_bf16 v[80:83], v[156:159], v[180:183], v[80:83]
	v_mfma_f32_16x16x32_bf16 v[68:71], v[148:151], v[208:211], v[68:71]
	v_mfma_f32_16x16x32_bf16 v[64:67], v[156:159], v[208:211], v[64:67]
	v_mfma_f32_16x16x32_bf16 v[116:119], v[152:155], v[168:171], v[116:119]
	v_mfma_f32_16x16x32_bf16 v[112:115], v[160:163], v[168:171], v[112:115]
	v_mfma_f32_16x16x32_bf16 v[100:103], v[152:155], v[176:179], v[100:103]
	v_mfma_f32_16x16x32_bf16 v[96:99], v[160:163], v[176:179], v[96:99]
	v_mfma_f32_16x16x32_bf16 v[84:87], v[152:155], v[204:207], v[84:87]
	v_mfma_f32_16x16x32_bf16 v[80:83], v[160:163], v[204:207], v[80:83]
	v_mfma_f32_16x16x32_bf16 v[68:71], v[152:155], v[212:215], v[68:71]
	v_mfma_f32_16x16x32_bf16 v[64:67], v[160:163], v[212:215], v[64:67]
	s_barrier
	s_setprio 0
	s_add_i32 s10, s10, s50
	s_mov_b32 m0, s10
	ds_read_b128 v[164:167], v221 offset:49152
	ds_read_b128 v[168:171], v221 offset:50176
	ds_read_b128 v[172:175], v221 offset:51200
	global_load_lds_dwordx4 v186, s[42:43]
	s_add_i32 m0, s10, 0x2000
	ds_read_b128 v[176:179], v221 offset:52224
	global_load_lds_dwordx4 v190, s[42:43]
	s_add_u32 s42, s42, 0x40000
	s_addc_u32 s43, s43, 0
	s_add_i32 s10, s72, s50
	s_mov_b32 m0, s10
	ds_read_b128 v[180:183], v221 offset:53248
	global_load_lds_dwordx4 v186, s[42:43]
	s_add_i32 m0, s10, 0x2000
	ds_read_b128 v[204:207], v221 offset:54272
	global_load_lds_dwordx4 v190, s[42:43]
	s_mov_b32 m0, s58
	ds_read_b128 v[208:211], v221 offset:55296
	global_load_lds_dwordx4 v184, s[40:41]
	s_mov_b32 m0, s59
	ds_read_b128 v[212:215], v221 offset:56320
	global_load_lds_dwordx4 v188, s[40:41]
	s_waitcnt vmcnt(8)
	s_waitcnt lgkmcnt(0)
	s_setprio 1
	s_barrier
	v_mfma_f32_16x16x32_bf16 v[60:63], v[132:135], v[164:167], v[60:63]
	v_mfma_f32_16x16x32_bf16 v[56:59], v[140:143], v[164:167], v[56:59]
	v_mfma_f32_16x16x32_bf16 v[44:47], v[132:135], v[172:175], v[44:47]
	v_mfma_f32_16x16x32_bf16 v[40:43], v[140:143], v[172:175], v[40:43]
	v_mfma_f32_16x16x32_bf16 v[28:31], v[132:135], v[180:183], v[28:31]
	v_mfma_f32_16x16x32_bf16 v[24:27], v[140:143], v[180:183], v[24:27]
	v_mfma_f32_16x16x32_bf16 v[12:15], v[132:135], v[208:211], v[12:15]
	v_mfma_f32_16x16x32_bf16 v[8:11], v[140:143], v[208:211], v[8:11]
	v_mfma_f32_16x16x32_bf16 v[60:63], v[136:139], v[168:171], v[60:63]
	v_mfma_f32_16x16x32_bf16 v[56:59], v[144:147], v[168:171], v[56:59]
	v_mfma_f32_16x16x32_bf16 v[44:47], v[136:139], v[176:179], v[44:47]
	v_mfma_f32_16x16x32_bf16 v[40:43], v[144:147], v[176:179], v[40:43]
	v_mfma_f32_16x16x32_bf16 v[28:31], v[136:139], v[204:207], v[28:31]
	v_mfma_f32_16x16x32_bf16 v[24:27], v[144:147], v[204:207], v[24:27]
	v_mfma_f32_16x16x32_bf16 v[12:15], v[136:139], v[212:215], v[12:15]
	v_mfma_f32_16x16x32_bf16 v[8:11], v[144:147], v[212:215], v[8:11]
	s_setprio 0
	s_setprio 1
	v_mfma_f32_16x16x32_bf16 v[52:55], v[148:151], v[164:167], v[52:55]
	v_mfma_f32_16x16x32_bf16 v[48:51], v[156:159], v[164:167], v[48:51]
	v_mfma_f32_16x16x32_bf16 v[36:39], v[148:151], v[172:175], v[36:39]
	v_mfma_f32_16x16x32_bf16 v[32:35], v[156:159], v[172:175], v[32:35]
	v_mfma_f32_16x16x32_bf16 v[20:23], v[148:151], v[180:183], v[20:23]
	v_mfma_f32_16x16x32_bf16 v[16:19], v[156:159], v[180:183], v[16:19]
	v_mfma_f32_16x16x32_bf16 v[4:7], v[148:151], v[208:211], v[4:7]
	v_mfma_f32_16x16x32_bf16 v[0:3], v[156:159], v[208:211], v[0:3]
	v_mfma_f32_16x16x32_bf16 v[52:55], v[152:155], v[168:171], v[52:55]
	v_mfma_f32_16x16x32_bf16 v[48:51], v[160:163], v[168:171], v[48:51]
	v_mfma_f32_16x16x32_bf16 v[36:39], v[152:155], v[176:179], v[36:39]
	v_mfma_f32_16x16x32_bf16 v[32:35], v[160:163], v[176:179], v[32:35]
	v_mfma_f32_16x16x32_bf16 v[20:23], v[152:155], v[204:207], v[20:23]
	v_mfma_f32_16x16x32_bf16 v[16:19], v[160:163], v[204:207], v[16:19]
	v_mfma_f32_16x16x32_bf16 v[4:7], v[152:155], v[212:215], v[4:7]
	v_mfma_f32_16x16x32_bf16 v[0:3], v[160:163], v[212:215], v[0:3]
	s_barrier
	s_setprio 0
	s_add_i32 s10, s71, 2
	s_add_u32 s38, s38, 0x100
	s_addc_u32 s39, s39, 0
	s_cmp_gt_u32 s71, 13
	s_mov_b32 s71, s10
	s_cbranch_scc1 .LBB0_1025
